# GEMM K loops: per-cluster s_setprio flips replaced by one static priority raise for waves 4-7 during the loop
# speedup vs baseline: 1.0055x; 1.0055x over previous
; #define PG8_STAGE(bufoff, gbase) do { _Pragma("unroll") for (int _i = 0; _i < 2; ++_i) \
;         __builtin_amdgcn_global_load_lds((const unsigned*)((const char*)(gbase) + voffA[_i]), (LAS unsigned*)(lds + (bufoff) + ldsw + _i * 8192), 16, 0, 0); } while (0)
; #define PG8_LDA(dst, b, h) do { _Pragma("unroll") for (int m = 0; m < 4; ++m) _Pragma("unroll") for (int k = 0; k < 2; ++k) dst[m][k] = *(const LAS bf16x8*)(lds + PG8_SA(b, h) + aoff + m * 2048 + k * 1024); } while (0)
; #define PG8_LDB(dst, b, h) do { _Pragma("unroll") for (int n = 0; n < 2; ++n) _Pragma("unroll") for (int k = 0; k < 2; ++k) dst[n][k] = *(const LAS bf16x8*)(lds + PG8_SB(b, h) + boff + n * 2048 + k * 1024); } while (0)
; #define PG8_MMA(ai, bj, At, Bt) do { __builtin_amdgcn_s_setprio(1); _Pragma("unroll") for (int m = 0; m < 4; ++m) _Pragma("unroll") for (int n = 0; n < 2; ++n) _Pragma("unroll") for (int k = 0; k < 2; ++k) \
;         acc[ai][bj][m][n] = __builtin_amdgcn_mfma_f32_16x16x32_bf16(Bt[n][k], At[m][k], acc[ai][bj][m][n], 0, 0, 0); __builtin_amdgcn_s_setprio(0); } while (0)
; #define PG8_WAIT_V(n) asm volatile("s_waitcnt vmcnt(" #n ")" ::: "memory")
; template <class Epi, class Sched>
; __device__ __forceinline__ void gemm_phase(LAS unsigned char* lds, const Gemm g, const Sched& S, const Epi& E, int wid) {
;     ...
; #pragma unroll
;     for (int a = 0; a < 2; ++a)
; #pragma unroll
;         for (int b = 0; b < 2; ++b)
; #pragma unroll
;             for (int m = 0; m < 4; ++m)
; #pragma unroll
;                 for (int n = 0; n < 2; ++n) acc[a][b][m][n] = (f32x4){0.f, 0.f, 0.f, 0.f};
;     ...
;         const bool has_next = S.next(ui + 1, nxt);
;         const char* nA = has_next ? (const char*)g.A + (size_t)nxt.pm * tstep : cA; const char* nB = has_next ? (const char*)g.Bt + (size_t)nxt.pn * tstep : cB;
;         for (int t = 0; t < nt; t += 2) {
;             const bool last = (t == nt - 2);
;             const char* a1 = cA + (size_t)(t + 1) * kstep;
;             const char* a2 = last ? nA : cA + (size_t)(t + 2) * kstep; const char* b2 = last ? nB : cB + (size_t)(t + 2) * kstep;
;             const char* a3 = a2 + kstep; const char* b3 = b2 + kstep;
;             PG8_LDB(B0, 0, 0); PG8_LDB(B1, 0, 1); PG8_SCHED; PG8_LDA(At, 0, 0); PG8_STAGE(PG8_SA(1, 1), a1 + hstep);
;             PG8_WAIT_V(8); PG8_WAIT_L(0); PG8_BAR; PG8_MMA(0, 0, At, B0); PG8_MMA(0, 1, At, B1); PG8_BAR; PG8_SCHED;
.LBB0_215:
	s_ashr_i32 s77, s76, 31
	s_lshl_b64 s[0:1], s[76:77], 19
	v_readlane_b32 s6, v250, 28
	v_readlane_b32 s7, v250, 29
	s_add_u32 s78, s6, s0
	s_addc_u32 s79, s7, s1
	s_and_b64 s[0:1], s[44:45], exec
	s_cselect_b32 s0, s79, s47
	s_cselect_b32 s1, s78, s46
	s_ashr_i32 s71, s70, 31
	s_lshl_b64 s[6:7], s[70:71], 19
	v_readlane_b32 s10, v250, 42
	s_add_u32 s36, s10, s6
	v_readlane_b32 s6, v250, 43
	s_addc_u32 s37, s6, s7
	s_and_b64 s[6:7], s[44:45], exec
	s_cselect_b32 s6, s37, s49
	s_cselect_b32 s7, s36, s48
	s_add_u32 s46, s46, 0x40080
	s_addc_u32 s47, s47, 0
	s_add_u32 s10, s48, 0x100
	v_mov_b32_e32 v4, 0
	s_addc_u32 s11, s49, 0
	s_mov_b32 s29, -2
	v_mov_b32_e32 v5, v4
	s_waitcnt lgkmcnt(0)
	v_mov_b32_e32 v6, v4
	v_mov_b32_e32 v7, v4
	v_mov_b32_e32 v36, v4
	v_mov_b32_e32 v37, v4
	v_mov_b32_e32 v38, v4
	v_mov_b32_e32 v39, v4
	v_mov_b32_e32 v8, v4
	v_mov_b32_e32 v9, v4
	v_mov_b32_e32 v10, v4
	v_mov_b32_e32 v11, v4
	v_mov_b32_e32 v40, v4
	v_mov_b32_e32 v41, v4
	v_mov_b32_e32 v42, v4
	v_mov_b32_e32 v43, v4
	v_mov_b32_e32 v12, v4
	v_mov_b32_e32 v13, v4
	v_mov_b32_e32 v14, v4
	v_mov_b32_e32 v15, v4
	v_mov_b32_e32 v44, v4
	v_mov_b32_e32 v45, v4
	v_mov_b32_e32 v46, v4
	v_mov_b32_e32 v47, v4
	v_mov_b32_e32 v16, v4
	v_mov_b32_e32 v17, v4
	v_mov_b32_e32 v18, v4
	v_mov_b32_e32 v19, v4
	v_mov_b32_e32 v48, v4
	v_mov_b32_e32 v49, v4
	v_mov_b32_e32 v50, v4
	v_mov_b32_e32 v51, v4
	v_mov_b32_e32 v68, v4
	v_mov_b32_e32 v69, v4
	v_mov_b32_e32 v70, v4
	v_mov_b32_e32 v71, v4
	v_mov_b32_e32 v100, v4
	v_mov_b32_e32 v101, v4
	v_mov_b32_e32 v102, v4
	v_mov_b32_e32 v103, v4
	v_mov_b32_e32 v72, v4
	v_mov_b32_e32 v73, v4
	v_mov_b32_e32 v74, v4
	v_mov_b32_e32 v75, v4
	v_mov_b32_e32 v104, v4
	v_mov_b32_e32 v105, v4
	v_mov_b32_e32 v106, v4
	v_mov_b32_e32 v107, v4
	v_mov_b32_e32 v76, v4
	v_mov_b32_e32 v77, v4
	v_mov_b32_e32 v78, v4
	v_mov_b32_e32 v79, v4
	v_mov_b32_e32 v108, v4
	v_mov_b32_e32 v109, v4
	v_mov_b32_e32 v110, v4
	v_mov_b32_e32 v111, v4
	v_mov_b32_e32 v80, v4
	v_mov_b32_e32 v81, v4
	v_mov_b32_e32 v82, v4
	v_mov_b32_e32 v83, v4
	v_mov_b32_e32 v112, v4
	v_mov_b32_e32 v113, v4
	v_mov_b32_e32 v114, v4
	v_mov_b32_e32 v115, v4
	v_mov_b32_e32 v20, v4
	v_mov_b32_e32 v21, v4
	v_mov_b32_e32 v22, v4
	v_mov_b32_e32 v23, v4
	v_mov_b32_e32 v52, v4
	v_mov_b32_e32 v53, v4
	v_mov_b32_e32 v54, v4
	v_mov_b32_e32 v55, v4
	v_mov_b32_e32 v24, v4
	v_mov_b32_e32 v25, v4
	v_mov_b32_e32 v26, v4
	v_mov_b32_e32 v27, v4
	v_mov_b32_e32 v56, v4
	v_mov_b32_e32 v57, v4
	v_mov_b32_e32 v58, v4
	v_mov_b32_e32 v59, v4
	v_mov_b32_e32 v28, v4
	v_mov_b32_e32 v29, v4
	v_mov_b32_e32 v30, v4
	v_mov_b32_e32 v31, v4
	v_mov_b32_e32 v60, v4
	v_mov_b32_e32 v61, v4
	v_mov_b32_e32 v62, v4
	v_mov_b32_e32 v63, v4
	v_mov_b32_e32 v32, v4
	v_mov_b32_e32 v33, v4
	v_mov_b32_e32 v34, v4
	v_mov_b32_e32 v35, v4
	v_mov_b32_e32 v64, v4
	v_mov_b32_e32 v65, v4
	v_mov_b32_e32 v66, v4
	v_mov_b32_e32 v67, v4
	v_mov_b32_e32 v84, v4
	v_mov_b32_e32 v85, v4
	v_mov_b32_e32 v86, v4
	v_mov_b32_e32 v87, v4
	v_mov_b32_e32 v124, v4
	v_mov_b32_e32 v125, v4
	v_mov_b32_e32 v126, v4
	v_mov_b32_e32 v127, v4
	v_mov_b32_e32 v88, v4
	v_mov_b32_e32 v89, v4
	v_mov_b32_e32 v90, v4
	v_mov_b32_e32 v91, v4
	v_mov_b32_e32 v128, v4
	v_mov_b32_e32 v129, v4
	v_mov_b32_e32 v130, v4
	v_mov_b32_e32 v131, v4
	v_mov_b32_e32 v92, v4
	v_mov_b32_e32 v93, v4
	v_mov_b32_e32 v94, v4
	v_mov_b32_e32 v95, v4
	v_mov_b32_e32 v132, v4
	v_mov_b32_e32 v133, v4
	v_mov_b32_e32 v134, v4
	v_mov_b32_e32 v135, v4
	v_mov_b32_e32 v96, v4
	v_mov_b32_e32 v97, v4
	v_mov_b32_e32 v98, v4
	v_mov_b32_e32 v99, v4
	v_mov_b32_e32 v136, v4
	v_mov_b32_e32 v137, v4
	v_mov_b32_e32 v138, v4
	v_mov_b32_e32 v139, v4
	v_readlane_b32 s100, v251, 60
	s_cmp_lt_u32 s100, 4
	s_cbranch_scc1 .Lmy_prio_0
	s_setprio 1
.Lmy_prio_0:
.LBB0_216:
	s_add_u32 s30, s46, 0xfffc0080
	s_addc_u32 s48, s47, -1
	s_add_i32 s52, 0, 0x10000
	s_cmp_eq_u32 s29, 12
	s_cselect_b32 s51, s0, s48
	s_cselect_b32 s50, s1, s30
	v_add_u32_e32 v3, s52, v145
	s_cselect_b32 s49, s6, s11
	s_cselect_b32 s48, s7, s10
	s_add_i32 s30, 0, 0x14000
	ds_read_b128 v[116:119], v3
	ds_read_b128 v[120:123], v3 offset:1024
	ds_read_b128 v[154:157], v3 offset:2048
	ds_read_b128 v[158:161], v3 offset:3072
	v_add_u32_e32 v3, s30, v145
	ds_read_b128 v[162:165], v3
	ds_read_b128 v[180:183], v3 offset:1024
	ds_read_b128 v[184:187], v3 offset:2048
	ds_read_b128 v[188:191], v3 offset:3072
	v_lshl_add_u64 v[166:167], s[46:47], 0, v[150:151]
	s_add_i32 m0, s85, 0xc000
	ds_read_b128 v[192:195], v236
	ds_read_b128 v[196:199], v236 offset:1024
	ds_read_b128 v[200:203], v236 offset:2048
	ds_read_b128 v[204:207], v236 offset:3072
	ds_read_b128 v[208:211], v236 offset:4096
	ds_read_b128 v[212:215], v236 offset:5120
	ds_read_b128 v[238:241], v236 offset:6144
	ds_read_b128 v[242:245], v236 offset:7168
	global_load_lds_dwordx4 v[166:167], off
	v_lshl_add_u64 v[166:167], s[46:47], 0, v[152:153]
	s_add_i32 m0, s85, 0xe000
	s_nop 0
	global_load_lds_dwordx4 v[166:167], off
	s_waitcnt vmcnt(8)
	s_waitcnt lgkmcnt(0)
	s_barrier
; #define PG8_STAGE(bufoff, gbase) do { _Pragma("unroll") for (int _i = 0; _i < 2; ++_i) \
;         __builtin_amdgcn_global_load_lds((const unsigned*)((const char*)(gbase) + voffA[_i]), (LAS unsigned*)(lds + (bufoff) + ldsw + _i * 8192), 16, 0, 0); } while (0)
; #define PG8_LDA(dst, b, h) do { _Pragma("unroll") for (int m = 0; m < 4; ++m) _Pragma("unroll") for (int k = 0; k < 2; ++k) dst[m][k] = *(const LAS bf16x8*)(lds + PG8_SA(b, h) + aoff + m * 2048 + k * 1024); } while (0)
; #define PG8_MMA(ai, bj, At, Bt) do { __builtin_amdgcn_s_setprio(1); _Pragma("unroll") for (int m = 0; m < 4; ++m) _Pragma("unroll") for (int n = 0; n < 2; ++n) _Pragma("unroll") for (int k = 0; k < 2; ++k) \
;         acc[ai][bj][m][n] = __builtin_amdgcn_mfma_f32_16x16x32_bf16(Bt[n][k], At[m][k], acc[ai][bj][m][n], 0, 0, 0); __builtin_amdgcn_s_setprio(0); } while (0)
; #define PG8_WAIT_V(n) asm volatile("s_waitcnt vmcnt(" #n ")" ::: "memory")
; #define PG8_WAIT_L(n) asm volatile("s_waitcnt lgkmcnt(" #n ")" ::: "memory")
; #define PG8_BAR __builtin_amdgcn_s_barrier()
; #define PG8_SCHED __builtin_amdgcn_sched_barrier(0)
; template <class Epi, class Sched>
; __device__ __forceinline__ void gemm_phase(LAS unsigned char* lds, const Gemm g, const Sched& S, const Epi& E, int wid) {
;     ...
;             PG8_WAIT_V(8); PG8_WAIT_L(0); PG8_BAR; PG8_MMA(0, 0, At, B0); PG8_MMA(0, 1, At, B1); PG8_BAR; PG8_SCHED;
;             PG8_LDA(At, 0, 1); PG8_STAGE(PG8_SB(0, 0), b2); PG8_STAGE(PG8_SB(0, 1), b2 + hstep); PG8_STAGE(PG8_SA(0, 0), a2);
;             PG8_WAIT_V(8); PG8_WAIT_L(0); PG8_BAR; PG8_MMA(1, 0, At, B0); PG8_MMA(1, 1, At, B1); PG8_BAR; PG8_SCHED;
	s_waitcnt lgkmcnt(0)
	v_mfma_f32_16x16x32_bf16 v[136:139], v[116:119], v[192:195], v[136:139]
	v_mfma_f32_16x16x32_bf16 v[96:99], v[154:157], v[192:195], v[96:99]
	v_mfma_f32_16x16x32_bf16 v[132:135], v[116:119], v[200:203], v[132:135]
	v_mfma_f32_16x16x32_bf16 v[92:95], v[154:157], v[200:203], v[92:95]
	v_mfma_f32_16x16x32_bf16 v[128:131], v[116:119], v[208:211], v[128:131]
	v_mfma_f32_16x16x32_bf16 v[88:91], v[154:157], v[208:211], v[88:91]
	v_mfma_f32_16x16x32_bf16 v[124:127], v[116:119], v[238:241], v[124:127]
	v_mfma_f32_16x16x32_bf16 v[84:87], v[154:157], v[238:241], v[84:87]
	v_mfma_f32_16x16x32_bf16 v[136:139], v[120:123], v[196:199], v[136:139]
	v_mfma_f32_16x16x32_bf16 v[96:99], v[158:161], v[196:199], v[96:99]
	v_mfma_f32_16x16x32_bf16 v[132:135], v[120:123], v[204:207], v[132:135]
	v_mfma_f32_16x16x32_bf16 v[92:95], v[158:161], v[204:207], v[92:95]
	v_mfma_f32_16x16x32_bf16 v[128:131], v[120:123], v[212:215], v[128:131]
	v_mfma_f32_16x16x32_bf16 v[88:91], v[158:161], v[212:215], v[88:91]
	v_mfma_f32_16x16x32_bf16 v[124:127], v[120:123], v[242:245], v[124:127]
	v_mfma_f32_16x16x32_bf16 v[84:87], v[158:161], v[242:245], v[84:87]
	v_mfma_f32_16x16x32_bf16 v[64:67], v[162:165], v[192:195], v[64:67]
	v_mfma_f32_16x16x32_bf16 v[32:35], v[184:187], v[192:195], v[32:35]
	v_mfma_f32_16x16x32_bf16 v[60:63], v[162:165], v[200:203], v[60:63]
	v_mfma_f32_16x16x32_bf16 v[28:31], v[184:187], v[200:203], v[28:31]
	v_mfma_f32_16x16x32_bf16 v[56:59], v[162:165], v[208:211], v[56:59]
	v_mfma_f32_16x16x32_bf16 v[24:27], v[184:187], v[208:211], v[24:27]
	v_mfma_f32_16x16x32_bf16 v[52:55], v[162:165], v[238:241], v[52:55]
	v_mfma_f32_16x16x32_bf16 v[20:23], v[184:187], v[238:241], v[20:23]
	v_mfma_f32_16x16x32_bf16 v[64:67], v[180:183], v[196:199], v[64:67]
	v_mfma_f32_16x16x32_bf16 v[32:35], v[188:191], v[196:199], v[32:35]
	v_mfma_f32_16x16x32_bf16 v[60:63], v[180:183], v[204:207], v[60:63]
	v_mfma_f32_16x16x32_bf16 v[28:31], v[188:191], v[204:207], v[28:31]
	v_mfma_f32_16x16x32_bf16 v[56:59], v[180:183], v[212:215], v[56:59]
	v_mfma_f32_16x16x32_bf16 v[24:27], v[188:191], v[212:215], v[24:27]
	v_mfma_f32_16x16x32_bf16 v[52:55], v[180:183], v[242:245], v[52:55]
	v_mfma_f32_16x16x32_bf16 v[20:23], v[188:191], v[242:245], v[20:23]
	s_barrier
	s_add_i32 s52, s52, s87
	v_lshl_add_u64 v[166:167], s[48:49], 0, v[140:141]
	s_mov_b32 m0, s52
	ds_read_b128 v[192:195], v236 offset:16384
	ds_read_b128 v[196:199], v236 offset:17408
	ds_read_b128 v[200:203], v236 offset:18432
	ds_read_b128 v[204:207], v236 offset:19456
	ds_read_b128 v[208:211], v236 offset:20480
	ds_read_b128 v[212:215], v236 offset:21504
	ds_read_b128 v[238:241], v236 offset:22528
	ds_read_b128 v[242:245], v236 offset:23552
	global_load_lds_dwordx4 v[166:167], off
	s_add_i32 m0, s52, 0x2000
	s_add_u32 s52, s48, 0x40000
	v_lshl_add_u64 v[216:217], s[48:49], 0, v[0:1]
	s_addc_u32 s53, s49, 0
	s_add_i32 s30, s30, s87
	global_load_lds_dwordx4 v[216:217], off
	v_lshl_add_u64 v[246:247], s[52:53], 0, v[140:141]
	s_mov_b32 m0, s30
	v_lshl_add_u64 v[248:249], s[50:51], 0, v[0:1]
	global_load_lds_dwordx4 v[246:247], off
	v_lshl_add_u64 v[246:247], s[52:53], 0, v[0:1]
	s_add_i32 m0, s30, 0x2000
	s_nop 0
	global_load_lds_dwordx4 v[246:247], off
	v_lshl_add_u64 v[246:247], s[50:51], 0, v[140:141]
	s_mov_b32 m0, s85
	s_nop 0
	global_load_lds_dwordx4 v[246:247], off
	s_mov_b32 m0, s95
	s_nop 0
	global_load_lds_dwordx4 v[248:249], off
	s_waitcnt vmcnt(8)
	s_waitcnt lgkmcnt(0)
	s_barrier
	s_waitcnt lgkmcnt(0)
	v_mfma_f32_16x16x32_bf16 v[112:115], v[116:119], v[192:195], v[112:115]
	v_mfma_f32_16x16x32_bf16 v[80:83], v[154:157], v[192:195], v[80:83]
	v_mfma_f32_16x16x32_bf16 v[108:111], v[116:119], v[200:203], v[108:111]
	v_mfma_f32_16x16x32_bf16 v[76:79], v[154:157], v[200:203], v[76:79]
	v_mfma_f32_16x16x32_bf16 v[104:107], v[116:119], v[208:211], v[104:107]
	v_mfma_f32_16x16x32_bf16 v[72:75], v[154:157], v[208:211], v[72:75]
	v_mfma_f32_16x16x32_bf16 v[100:103], v[116:119], v[238:241], v[100:103]
	v_mfma_f32_16x16x32_bf16 v[68:71], v[154:157], v[238:241], v[68:71]
	v_mfma_f32_16x16x32_bf16 v[112:115], v[120:123], v[196:199], v[112:115]
	v_mfma_f32_16x16x32_bf16 v[80:83], v[158:161], v[196:199], v[80:83]
	v_mfma_f32_16x16x32_bf16 v[108:111], v[120:123], v[204:207], v[108:111]
	v_mfma_f32_16x16x32_bf16 v[76:79], v[158:161], v[204:207], v[76:79]
	v_mfma_f32_16x16x32_bf16 v[104:107], v[120:123], v[212:215], v[104:107]
	v_mfma_f32_16x16x32_bf16 v[72:75], v[158:161], v[212:215], v[72:75]
	v_mfma_f32_16x16x32_bf16 v[100:103], v[120:123], v[242:245], v[100:103]
	v_mfma_f32_16x16x32_bf16 v[68:71], v[158:161], v[242:245], v[68:71]
	v_mfma_f32_16x16x32_bf16 v[48:51], v[162:165], v[192:195], v[48:51]
	v_mfma_f32_16x16x32_bf16 v[16:19], v[184:187], v[192:195], v[16:19]
	v_mfma_f32_16x16x32_bf16 v[44:47], v[162:165], v[200:203], v[44:47]
	v_mfma_f32_16x16x32_bf16 v[12:15], v[184:187], v[200:203], v[12:15]
	v_mfma_f32_16x16x32_bf16 v[40:43], v[162:165], v[208:211], v[40:43]
	v_mfma_f32_16x16x32_bf16 v[8:11], v[184:187], v[208:211], v[8:11]
	v_mfma_f32_16x16x32_bf16 v[36:39], v[162:165], v[238:241], v[36:39]
	v_mfma_f32_16x16x32_bf16 v[4:7], v[184:187], v[238:241], v[4:7]
	v_mfma_f32_16x16x32_bf16 v[48:51], v[180:183], v[196:199], v[48:51]
	v_mfma_f32_16x16x32_bf16 v[16:19], v[188:191], v[196:199], v[16:19]
	v_mfma_f32_16x16x32_bf16 v[44:47], v[180:183], v[204:207], v[44:47]
	v_mfma_f32_16x16x32_bf16 v[12:15], v[188:191], v[204:207], v[12:15]
	v_mfma_f32_16x16x32_bf16 v[40:43], v[180:183], v[212:215], v[40:43]
	v_mfma_f32_16x16x32_bf16 v[8:11], v[188:191], v[212:215], v[8:11]
	v_mfma_f32_16x16x32_bf16 v[36:39], v[180:183], v[242:245], v[36:39]
	v_mfma_f32_16x16x32_bf16 v[4:7], v[188:191], v[242:245], v[4:7]
	s_barrier
; #define PG8_STAGE(bufoff, gbase) do { _Pragma("unroll") for (int _i = 0; _i < 2; ++_i) \
;         __builtin_amdgcn_global_load_lds((const unsigned*)((const char*)(gbase) + voffA[_i]), (LAS unsigned*)(lds + (bufoff) + ldsw + _i * 8192), 16, 0, 0); } while (0)
; #define PG8_LDA(dst, b, h) do { _Pragma("unroll") for (int m = 0; m < 4; ++m) _Pragma("unroll") for (int k = 0; k < 2; ++k) dst[m][k] = *(const LAS bf16x8*)(lds + PG8_SA(b, h) + aoff + m * 2048 + k * 1024); } while (0)
; #define PG8_LDB(dst, b, h) do { _Pragma("unroll") for (int n = 0; n < 2; ++n) _Pragma("unroll") for (int k = 0; k < 2; ++k) dst[n][k] = *(const LAS bf16x8*)(lds + PG8_SB(b, h) + boff + n * 2048 + k * 1024); } while (0)
; #define PG8_MMA(ai, bj, At, Bt) do { __builtin_amdgcn_s_setprio(1); _Pragma("unroll") for (int m = 0; m < 4; ++m) _Pragma("unroll") for (int n = 0; n < 2; ++n) _Pragma("unroll") for (int k = 0; k < 2; ++k) \
;         acc[ai][bj][m][n] = __builtin_amdgcn_mfma_f32_16x16x32_bf16(Bt[n][k], At[m][k], acc[ai][bj][m][n], 0, 0, 0); __builtin_amdgcn_s_setprio(0); } while (0)
; #define PG8_WAIT_V(n) asm volatile("s_waitcnt vmcnt(" #n ")" ::: "memory")
; #define PG8_WAIT_L(n) asm volatile("s_waitcnt lgkmcnt(" #n ")" ::: "memory")
; #define PG8_BAR __builtin_amdgcn_s_barrier()
; #define PG8_SCHED __builtin_amdgcn_sched_barrier(0)
; template <class Epi, class Sched>
; __device__ __forceinline__ void gemm_phase(LAS unsigned char* lds, const Gemm g, const Sched& S, const Epi& E, int wid) {
;     ...
;             PG8_LDB(B0, 1, 0); PG8_LDB(B1, 1, 1); PG8_SCHED; PG8_LDA(At, 1, 0); PG8_STAGE(PG8_SA(0, 1), a2 + hstep);
;             PG8_WAIT_V(8); PG8_WAIT_L(0); PG8_BAR; PG8_MMA(0, 0, At, B0); PG8_MMA(0, 1, At, B1); PG8_BAR; PG8_SCHED;
	s_add_i32 s30, 0, 0x18000
	v_add_u32_e32 v3, s30, v145
	s_add_i32 s52, 0, 0x1c000
	ds_read_b128 v[116:119], v3
	ds_read_b128 v[120:123], v3 offset:1024
	ds_read_b128 v[154:157], v3 offset:2048
	ds_read_b128 v[158:161], v3 offset:3072
	v_add_u32_e32 v3, s52, v145
	ds_read_b128 v[162:165], v3
	ds_read_b128 v[180:183], v3 offset:1024
	ds_read_b128 v[184:187], v3 offset:2048
	ds_read_b128 v[188:191], v3 offset:3072
	s_add_u32 s50, s50, 0x40000
	s_addc_u32 s51, s51, 0
	s_mov_b32 m0, s8
	v_lshl_add_u64 v[168:169], s[50:51], 0, v[140:141]
	ds_read_b128 v[192:195], v236 offset:32768
	ds_read_b128 v[196:199], v236 offset:33792
	ds_read_b128 v[200:203], v236 offset:34816
	ds_read_b128 v[204:207], v236 offset:35840
	ds_read_b128 v[208:211], v236 offset:36864
	ds_read_b128 v[212:215], v236 offset:37888
	ds_read_b128 v[238:241], v236 offset:38912
	ds_read_b128 v[242:245], v236 offset:39936
	global_load_lds_dwordx4 v[168:169], off
	v_lshl_add_u64 v[168:169], s[50:51], 0, v[0:1]
	s_mov_b32 m0, s9
	s_nop 0
	global_load_lds_dwordx4 v[168:169], off
	s_waitcnt vmcnt(8)
	s_waitcnt lgkmcnt(0)
	s_barrier
	s_waitcnt lgkmcnt(0)
	v_mfma_f32_16x16x32_bf16 v[136:139], v[116:119], v[192:195], v[136:139]
	v_mfma_f32_16x16x32_bf16 v[96:99], v[154:157], v[192:195], v[96:99]
	v_mfma_f32_16x16x32_bf16 v[132:135], v[116:119], v[200:203], v[132:135]
	v_mfma_f32_16x16x32_bf16 v[92:95], v[154:157], v[200:203], v[92:95]
	v_mfma_f32_16x16x32_bf16 v[128:131], v[116:119], v[208:211], v[128:131]
	v_mfma_f32_16x16x32_bf16 v[88:91], v[154:157], v[208:211], v[88:91]
	v_mfma_f32_16x16x32_bf16 v[124:127], v[116:119], v[238:241], v[124:127]
	v_mfma_f32_16x16x32_bf16 v[84:87], v[154:157], v[238:241], v[84:87]
	v_mfma_f32_16x16x32_bf16 v[136:139], v[120:123], v[196:199], v[136:139]
	v_mfma_f32_16x16x32_bf16 v[96:99], v[158:161], v[196:199], v[96:99]
	v_mfma_f32_16x16x32_bf16 v[132:135], v[120:123], v[204:207], v[132:135]
	v_mfma_f32_16x16x32_bf16 v[92:95], v[158:161], v[204:207], v[92:95]
	v_mfma_f32_16x16x32_bf16 v[128:131], v[120:123], v[212:215], v[128:131]
	v_mfma_f32_16x16x32_bf16 v[88:91], v[158:161], v[212:215], v[88:91]
	v_mfma_f32_16x16x32_bf16 v[124:127], v[120:123], v[242:245], v[124:127]
	v_mfma_f32_16x16x32_bf16 v[84:87], v[158:161], v[242:245], v[84:87]
	v_mfma_f32_16x16x32_bf16 v[64:67], v[162:165], v[192:195], v[64:67]
	v_mfma_f32_16x16x32_bf16 v[32:35], v[184:187], v[192:195], v[32:35]
	v_mfma_f32_16x16x32_bf16 v[60:63], v[162:165], v[200:203], v[60:63]
	v_mfma_f32_16x16x32_bf16 v[28:31], v[184:187], v[200:203], v[28:31]
	v_mfma_f32_16x16x32_bf16 v[56:59], v[162:165], v[208:211], v[56:59]
	v_mfma_f32_16x16x32_bf16 v[24:27], v[184:187], v[208:211], v[24:27]
	v_mfma_f32_16x16x32_bf16 v[52:55], v[162:165], v[238:241], v[52:55]
	v_mfma_f32_16x16x32_bf16 v[20:23], v[184:187], v[238:241], v[20:23]
	v_mfma_f32_16x16x32_bf16 v[64:67], v[180:183], v[196:199], v[64:67]
	v_mfma_f32_16x16x32_bf16 v[32:35], v[188:191], v[196:199], v[32:35]
	v_mfma_f32_16x16x32_bf16 v[60:63], v[180:183], v[204:207], v[60:63]
	v_mfma_f32_16x16x32_bf16 v[28:31], v[188:191], v[204:207], v[28:31]
	v_mfma_f32_16x16x32_bf16 v[56:59], v[180:183], v[212:215], v[56:59]
	v_mfma_f32_16x16x32_bf16 v[24:27], v[188:191], v[212:215], v[24:27]
	v_mfma_f32_16x16x32_bf16 v[52:55], v[180:183], v[242:245], v[52:55]
	v_mfma_f32_16x16x32_bf16 v[20:23], v[188:191], v[242:245], v[20:23]
	s_barrier
; #define PG8_STAGE(bufoff, gbase) do { _Pragma("unroll") for (int _i = 0; _i < 2; ++_i) \
;         __builtin_amdgcn_global_load_lds((const unsigned*)((const char*)(gbase) + voffA[_i]), (LAS unsigned*)(lds + (bufoff) + ldsw + _i * 8192), 16, 0, 0); } while (0)
; #define PG8_LDA(dst, b, h) do { _Pragma("unroll") for (int m = 0; m < 4; ++m) _Pragma("unroll") for (int k = 0; k < 2; ++k) dst[m][k] = *(const LAS bf16x8*)(lds + PG8_SA(b, h) + aoff + m * 2048 + k * 1024); } while (0)
; #define PG8_MMA(ai, bj, At, Bt) do { __builtin_amdgcn_s_setprio(1); _Pragma("unroll") for (int m = 0; m < 4; ++m) _Pragma("unroll") for (int n = 0; n < 2; ++n) _Pragma("unroll") for (int k = 0; k < 2; ++k) \
;         acc[ai][bj][m][n] = __builtin_amdgcn_mfma_f32_16x16x32_bf16(Bt[n][k], At[m][k], acc[ai][bj][m][n], 0, 0, 0); __builtin_amdgcn_s_setprio(0); } while (0)
; #define PG8_WAIT_V(n) asm volatile("s_waitcnt vmcnt(" #n ")" ::: "memory")
; #define PG8_WAIT_L(n) asm volatile("s_waitcnt lgkmcnt(" #n ")" ::: "memory")
; #define PG8_BAR __builtin_amdgcn_s_barrier()
; #define PG8_SCHED __builtin_amdgcn_sched_barrier(0)
; template <class Epi, class Sched>
; __device__ __forceinline__ void gemm_phase(LAS unsigned char* lds, const Gemm g, const Sched& S, const Epi& E, int wid) {
;     ...
;             PG8_LDA(At, 1, 1); PG8_STAGE(PG8_SB(1, 0), b3); PG8_STAGE(PG8_SB(1, 1), b3 + hstep); PG8_STAGE(PG8_SA(1, 0), a3);
;             PG8_WAIT_V(8); PG8_WAIT_L(0); PG8_BAR; PG8_MMA(1, 0, At, B0); PG8_MMA(1, 1, At, B1); PG8_BAR; PG8_SCHED;
;         }
;         if (wr == 0) PG8_BAR;
	s_add_i32 s30, s30, s87
	v_lshl_add_u64 v[166:167], v[166:167], 0, s[92:93]
	s_mov_b32 m0, s30
	ds_read_b128 v[192:195], v236 offset:49152
	ds_read_b128 v[196:199], v236 offset:50176
	ds_read_b128 v[200:203], v236 offset:51200
	ds_read_b128 v[204:207], v236 offset:52224
	ds_read_b128 v[208:211], v236 offset:53248
	ds_read_b128 v[212:215], v236 offset:54272
	ds_read_b128 v[238:241], v236 offset:55296
	ds_read_b128 v[242:245], v236 offset:56320
	global_load_lds_dwordx4 v[166:167], off
	s_add_i32 m0, s30, 0x2000
	s_add_u32 s48, s48, 0x40080
	v_lshl_add_u64 v[166:167], v[216:217], 0, s[92:93]
	s_addc_u32 s49, s49, 0
	s_add_i32 s30, s52, s87
	global_load_lds_dwordx4 v[166:167], off
	v_lshl_add_u64 v[166:167], s[48:49], 0, v[140:141]
	s_mov_b32 m0, s30
	s_nop 0
	global_load_lds_dwordx4 v[166:167], off
	v_lshl_add_u64 v[166:167], s[48:49], 0, v[0:1]
	s_add_i32 m0, s30, 0x2000
	s_nop 0
	global_load_lds_dwordx4 v[166:167], off
	v_lshl_add_u64 v[166:167], v[246:247], 0, s[92:93]
	s_mov_b32 m0, s22
	s_nop 0
	global_load_lds_dwordx4 v[166:167], off
	v_lshl_add_u64 v[166:167], v[248:249], 0, s[92:93]
	s_mov_b32 m0, s23
	s_nop 0
	global_load_lds_dwordx4 v[166:167], off
	s_waitcnt vmcnt(8)
	s_waitcnt lgkmcnt(0)
	s_barrier
	s_waitcnt lgkmcnt(0)
	v_mfma_f32_16x16x32_bf16 v[112:115], v[116:119], v[192:195], v[112:115]
	v_mfma_f32_16x16x32_bf16 v[80:83], v[154:157], v[192:195], v[80:83]
	v_mfma_f32_16x16x32_bf16 v[108:111], v[116:119], v[200:203], v[108:111]
	v_mfma_f32_16x16x32_bf16 v[76:79], v[154:157], v[200:203], v[76:79]
	v_mfma_f32_16x16x32_bf16 v[104:107], v[116:119], v[208:211], v[104:107]
	v_mfma_f32_16x16x32_bf16 v[72:75], v[154:157], v[208:211], v[72:75]
	v_mfma_f32_16x16x32_bf16 v[100:103], v[116:119], v[238:241], v[100:103]
	v_mfma_f32_16x16x32_bf16 v[68:71], v[154:157], v[238:241], v[68:71]
	v_mfma_f32_16x16x32_bf16 v[112:115], v[120:123], v[196:199], v[112:115]
	v_mfma_f32_16x16x32_bf16 v[80:83], v[158:161], v[196:199], v[80:83]
	v_mfma_f32_16x16x32_bf16 v[108:111], v[120:123], v[204:207], v[108:111]
	v_mfma_f32_16x16x32_bf16 v[76:79], v[158:161], v[204:207], v[76:79]
	v_mfma_f32_16x16x32_bf16 v[104:107], v[120:123], v[212:215], v[104:107]
	v_mfma_f32_16x16x32_bf16 v[72:75], v[158:161], v[212:215], v[72:75]
	v_mfma_f32_16x16x32_bf16 v[100:103], v[120:123], v[242:245], v[100:103]
	v_mfma_f32_16x16x32_bf16 v[68:71], v[158:161], v[242:245], v[68:71]
	v_mfma_f32_16x16x32_bf16 v[48:51], v[162:165], v[192:195], v[48:51]
	v_mfma_f32_16x16x32_bf16 v[16:19], v[184:187], v[192:195], v[16:19]
	v_mfma_f32_16x16x32_bf16 v[44:47], v[162:165], v[200:203], v[44:47]
	v_mfma_f32_16x16x32_bf16 v[12:15], v[184:187], v[200:203], v[12:15]
	v_mfma_f32_16x16x32_bf16 v[40:43], v[162:165], v[208:211], v[40:43]
	v_mfma_f32_16x16x32_bf16 v[8:11], v[184:187], v[208:211], v[8:11]
	v_mfma_f32_16x16x32_bf16 v[36:39], v[162:165], v[238:241], v[36:39]
	v_mfma_f32_16x16x32_bf16 v[4:7], v[184:187], v[238:241], v[4:7]
	v_mfma_f32_16x16x32_bf16 v[48:51], v[180:183], v[196:199], v[48:51]
	v_mfma_f32_16x16x32_bf16 v[16:19], v[188:191], v[196:199], v[16:19]
	v_mfma_f32_16x16x32_bf16 v[44:47], v[180:183], v[204:207], v[44:47]
	v_mfma_f32_16x16x32_bf16 v[12:15], v[188:191], v[204:207], v[12:15]
	v_mfma_f32_16x16x32_bf16 v[40:43], v[180:183], v[212:215], v[40:43]
	v_mfma_f32_16x16x32_bf16 v[8:11], v[188:191], v[212:215], v[8:11]
	v_mfma_f32_16x16x32_bf16 v[36:39], v[180:183], v[242:245], v[36:39]
	v_mfma_f32_16x16x32_bf16 v[4:7], v[188:191], v[242:245], v[4:7]
	s_barrier
	s_add_i32 s29, s29, 2
	s_add_u32 s46, s46, 0x100
	s_addc_u32 s47, s47, 0
	s_add_u32 s10, s10, 0x100
	s_addc_u32 s11, s11, 0
	s_cmp_gt_u32 s29, 13
	s_cbranch_scc0 .LBB0_216
	s_setprio 0
	v_readlane_b32 s0, v252, 28
	v_readlane_b32 s1, v252, 29
	s_and_b64 vcc, exec, s[0:1]
	s_cbranch_vccz .LBB0_219
	s_barrier

; #define PG8_STAGE(bufoff, gbase) do { _Pragma("unroll") for (int _i = 0; _i < 2; ++_i) \
;         __builtin_amdgcn_global_load_lds((const unsigned*)((const char*)(gbase) + voffA[_i]), (LAS unsigned*)(lds + (bufoff) + ldsw + _i * 8192), 16, 0, 0); } while (0)
; #define PG8_LDA(dst, b, h) do { _Pragma("unroll") for (int m = 0; m < 4; ++m) _Pragma("unroll") for (int k = 0; k < 2; ++k) dst[m][k] = *(const LAS bf16x8*)(lds + PG8_SA(b, h) + aoff + m * 2048 + k * 1024); } while (0)
; #define PG8_LDB(dst, b, h) do { _Pragma("unroll") for (int n = 0; n < 2; ++n) _Pragma("unroll") for (int k = 0; k < 2; ++k) dst[n][k] = *(const LAS bf16x8*)(lds + PG8_SB(b, h) + boff + n * 2048 + k * 1024); } while (0)
; #define PG8_MMA(ai, bj, At, Bt) do { __builtin_amdgcn_s_setprio(1); _Pragma("unroll") for (int m = 0; m < 4; ++m) _Pragma("unroll") for (int n = 0; n < 2; ++n) _Pragma("unroll") for (int k = 0; k < 2; ++k) \
;         acc[ai][bj][m][n] = __builtin_amdgcn_mfma_f32_16x16x32_bf16(Bt[n][k], At[m][k], acc[ai][bj][m][n], 0, 0, 0); __builtin_amdgcn_s_setprio(0); } while (0)
; #define PG8_WAIT_V(n) asm volatile("s_waitcnt vmcnt(" #n ")" ::: "memory")
; template <class Epi, class Sched>
; __device__ __forceinline__ void gemm_phase(LAS unsigned char* lds, const Gemm g, const Sched& S, const Epi& E, int wid) {
;     ...
; #pragma unroll
;     for (int a = 0; a < 2; ++a)
; #pragma unroll
;         for (int b = 0; b < 2; ++b)
; #pragma unroll
;             for (int m = 0; m < 4; ++m)
; #pragma unroll
;                 for (int n = 0; n < 2; ++n) acc[a][b][m][n] = (f32x4){0.f, 0.f, 0.f, 0.f};
;     ...
;         const bool has_next = S.next(ui + 1, nxt);
;         const char* nA = has_next ? (const char*)g.A + (size_t)nxt.pm * tstep : cA; const char* nB = has_next ? (const char*)g.Bt + (size_t)nxt.pn * tstep : cB;
;         for (int t = 0; t < nt; t += 2) {
;             const bool last = (t == nt - 2);
;             const char* a1 = cA + (size_t)(t + 1) * kstep;
;             const char* a2 = last ? nA : cA + (size_t)(t + 2) * kstep; const char* b2 = last ? nB : cB + (size_t)(t + 2) * kstep;
;             const char* a3 = a2 + kstep; const char* b3 = b2 + kstep;
;             PG8_LDB(B0, 0, 0); PG8_LDB(B1, 0, 1); PG8_SCHED; PG8_LDA(At, 0, 0); PG8_STAGE(PG8_SA(1, 1), a1 + hstep);
;             PG8_WAIT_V(8); PG8_WAIT_L(0); PG8_BAR; PG8_MMA(0, 0, At, B0); PG8_MMA(0, 1, At, B1); PG8_BAR; PG8_SCHED;
.LBB0_1519:
	s_ashr_i32 s43, s42, 31
	s_lshl_b64 s[0:1], s[42:43], 19
	v_readlane_b32 s29, v251, 56
	s_add_u32 s46, s29, s0
	v_readlane_b32 s0, v251, 57
	s_addc_u32 s47, s0, s1
	s_and_b64 s[0:1], s[40:41], exec
	s_cselect_b32 s0, s47, s51
	s_cselect_b32 s1, s46, s50
	s_ashr_i32 s45, s44, 31
	s_lshl_b64 s[48:49], s[44:45], 19
	s_add_u32 s48, s2, s48
	s_addc_u32 s49, s8, s49
	s_and_b64 s[54:55], s[40:41], exec
	s_cselect_b32 s29, s49, s53
	s_cselect_b32 s30, s48, s52
	s_add_u32 s50, s50, 0x40080
	s_addc_u32 s51, s51, 0
	s_add_u32 s43, s52, 0x100
	v_mov_b32_e32 v4, 0
	s_addc_u32 s45, s53, 0
	s_mov_b32 s56, -2
	v_mov_b32_e32 v5, v4
	v_mov_b32_e32 v6, v4
	v_mov_b32_e32 v7, v4
	v_mov_b32_e32 v20, v4
	v_mov_b32_e32 v21, v4
	v_mov_b32_e32 v22, v4
	v_mov_b32_e32 v23, v4
	v_mov_b32_e32 v8, v4
	v_mov_b32_e32 v9, v4
	v_mov_b32_e32 v10, v4
	v_mov_b32_e32 v11, v4
	v_mov_b32_e32 v24, v4
	v_mov_b32_e32 v25, v4
	v_mov_b32_e32 v26, v4
	v_mov_b32_e32 v27, v4
	v_mov_b32_e32 v12, v4
	v_mov_b32_e32 v13, v4
	v_mov_b32_e32 v14, v4
	v_mov_b32_e32 v15, v4
	v_mov_b32_e32 v28, v4
	v_mov_b32_e32 v29, v4
	v_mov_b32_e32 v30, v4
	v_mov_b32_e32 v31, v4
	v_mov_b32_e32 v16, v4
	v_mov_b32_e32 v17, v4
	v_mov_b32_e32 v18, v4
	v_mov_b32_e32 v19, v4
	v_mov_b32_e32 v36, v4
	v_mov_b32_e32 v37, v4
	v_mov_b32_e32 v38, v4
	v_mov_b32_e32 v39, v4
	v_mov_b32_e32 v48, v4
	v_mov_b32_e32 v49, v4
	v_mov_b32_e32 v50, v4
	v_mov_b32_e32 v51, v4
	v_mov_b32_e32 v84, v4
	v_mov_b32_e32 v85, v4
	v_mov_b32_e32 v86, v4
	v_mov_b32_e32 v87, v4
	v_mov_b32_e32 v60, v4
	v_mov_b32_e32 v61, v4
	v_mov_b32_e32 v62, v4
	v_mov_b32_e32 v63, v4
	v_mov_b32_e32 v88, v4
	v_mov_b32_e32 v89, v4
	v_mov_b32_e32 v90, v4
	v_mov_b32_e32 v91, v4
	v_mov_b32_e32 v68, v4
	v_mov_b32_e32 v69, v4
	v_mov_b32_e32 v70, v4
	v_mov_b32_e32 v71, v4
	v_mov_b32_e32 v100, v4
	v_mov_b32_e32 v101, v4
	v_mov_b32_e32 v102, v4
	v_mov_b32_e32 v103, v4
	v_mov_b32_e32 v76, v4
	v_mov_b32_e32 v77, v4
	v_mov_b32_e32 v78, v4
	v_mov_b32_e32 v79, v4
	v_mov_b32_e32 v108, v4
	v_mov_b32_e32 v109, v4
	v_mov_b32_e32 v110, v4
	v_mov_b32_e32 v111, v4
	v_mov_b32_e32 v32, v4
	v_mov_b32_e32 v33, v4
	v_mov_b32_e32 v34, v4
	v_mov_b32_e32 v35, v4
	v_mov_b32_e32 v56, v4
	v_mov_b32_e32 v57, v4
	v_mov_b32_e32 v58, v4
	v_mov_b32_e32 v59, v4
	v_mov_b32_e32 v40, v4
	v_mov_b32_e32 v41, v4
	v_mov_b32_e32 v42, v4
	v_mov_b32_e32 v43, v4
	v_mov_b32_e32 v64, v4
	v_mov_b32_e32 v65, v4
	v_mov_b32_e32 v66, v4
	v_mov_b32_e32 v67, v4
	v_mov_b32_e32 v44, v4
	v_mov_b32_e32 v45, v4
	v_mov_b32_e32 v46, v4
	v_mov_b32_e32 v47, v4
	v_mov_b32_e32 v72, v4
	v_mov_b32_e32 v73, v4
	v_mov_b32_e32 v74, v4
	v_mov_b32_e32 v75, v4
	v_mov_b32_e32 v52, v4
	v_mov_b32_e32 v53, v4
	v_mov_b32_e32 v54, v4
	v_mov_b32_e32 v55, v4
	v_mov_b32_e32 v80, v4
	v_mov_b32_e32 v81, v4
	v_mov_b32_e32 v82, v4
	v_mov_b32_e32 v83, v4
	v_mov_b32_e32 v92, v4
	v_mov_b32_e32 v93, v4
	v_mov_b32_e32 v94, v4
	v_mov_b32_e32 v95, v4
	v_mov_b32_e32 v116, v4
	v_mov_b32_e32 v117, v4
	v_mov_b32_e32 v118, v4
	v_mov_b32_e32 v119, v4
	v_mov_b32_e32 v96, v4
	v_mov_b32_e32 v97, v4
	v_mov_b32_e32 v98, v4
	v_mov_b32_e32 v99, v4
	v_mov_b32_e32 v120, v4
	v_mov_b32_e32 v121, v4
	v_mov_b32_e32 v122, v4
	v_mov_b32_e32 v123, v4
	v_mov_b32_e32 v104, v4
	v_mov_b32_e32 v105, v4
	v_mov_b32_e32 v106, v4
	v_mov_b32_e32 v107, v4
	v_mov_b32_e32 v124, v4
	v_mov_b32_e32 v125, v4
	v_mov_b32_e32 v126, v4
	v_mov_b32_e32 v127, v4
	v_mov_b32_e32 v112, v4
	v_mov_b32_e32 v113, v4
	v_mov_b32_e32 v114, v4
	v_mov_b32_e32 v115, v4
	v_mov_b32_e32 v128, v4
	v_mov_b32_e32 v129, v4
	v_mov_b32_e32 v130, v4
	v_mov_b32_e32 v131, v4
	v_readlane_b32 s100, v251, 60
	s_cmp_lt_u32 s100, 4
	s_cbranch_scc1 .Lmy_prio_1
	s_setprio 1
.Lmy_prio_1:
.LBB0_1520:
	s_add_u32 s52, s50, 0xfffc0080
	s_addc_u32 s53, s51, -1
	s_add_i32 s57, 0, 0x10000
	s_cmp_eq_u32 s56, 12
	s_cselect_b32 s55, s0, s53
	s_cselect_b32 s54, s1, s52
	v_add_u32_e32 v141, s57, v138
	s_cselect_b32 s53, s29, s45
	s_cselect_b32 s52, s30, s43
	s_add_i32 s60, 0, 0x14000
	ds_read_b128 v[142:145], v141
	ds_read_b128 v[146:149], v141 offset:1024
	ds_read_b128 v[150:153], v141 offset:2048
	ds_read_b128 v[154:157], v141 offset:3072
	v_add_u32_e32 v141, s60, v138
	ds_read_b128 v[158:161], v141
	ds_read_b128 v[162:165], v141 offset:1024
	ds_read_b128 v[180:183], v141 offset:2048
	ds_read_b128 v[184:187], v141 offset:3072
	v_lshl_add_u64 v[166:167], s[50:51], 0, v[134:135]
	s_add_i32 m0, s85, 0xc000
	ds_read_b128 v[188:191], v140
	ds_read_b128 v[192:195], v140 offset:1024
	ds_read_b128 v[196:199], v140 offset:2048
	ds_read_b128 v[200:203], v140 offset:3072
	ds_read_b128 v[204:207], v140 offset:4096
	ds_read_b128 v[208:211], v140 offset:5120
	ds_read_b128 v[212:215], v140 offset:6144
	ds_read_b128 v[234:237], v140 offset:7168
	global_load_lds_dwordx4 v[166:167], off
	v_lshl_add_u64 v[166:167], s[50:51], 0, v[136:137]
	s_add_i32 m0, s85, 0xe000
	s_nop 0
	global_load_lds_dwordx4 v[166:167], off
	s_waitcnt vmcnt(8)
	s_waitcnt lgkmcnt(0)
	s_barrier
; #define PG8_STAGE(bufoff, gbase) do { _Pragma("unroll") for (int _i = 0; _i < 2; ++_i) \
;         __builtin_amdgcn_global_load_lds((const unsigned*)((const char*)(gbase) + voffA[_i]), (LAS unsigned*)(lds + (bufoff) + ldsw + _i * 8192), 16, 0, 0); } while (0)
; #define PG8_LDA(dst, b, h) do { _Pragma("unroll") for (int m = 0; m < 4; ++m) _Pragma("unroll") for (int k = 0; k < 2; ++k) dst[m][k] = *(const LAS bf16x8*)(lds + PG8_SA(b, h) + aoff + m * 2048 + k * 1024); } while (0)
; #define PG8_MMA(ai, bj, At, Bt) do { __builtin_amdgcn_s_setprio(1); _Pragma("unroll") for (int m = 0; m < 4; ++m) _Pragma("unroll") for (int n = 0; n < 2; ++n) _Pragma("unroll") for (int k = 0; k < 2; ++k) \
;         acc[ai][bj][m][n] = __builtin_amdgcn_mfma_f32_16x16x32_bf16(Bt[n][k], At[m][k], acc[ai][bj][m][n], 0, 0, 0); __builtin_amdgcn_s_setprio(0); } while (0)
; #define PG8_WAIT_V(n) asm volatile("s_waitcnt vmcnt(" #n ")" ::: "memory")
; #define PG8_WAIT_L(n) asm volatile("s_waitcnt lgkmcnt(" #n ")" ::: "memory")
; #define PG8_BAR __builtin_amdgcn_s_barrier()
; #define PG8_SCHED __builtin_amdgcn_sched_barrier(0)
; template <class Epi, class Sched>
; __device__ __forceinline__ void gemm_phase(LAS unsigned char* lds, const Gemm g, const Sched& S, const Epi& E, int wid) {
;     ...
;             PG8_WAIT_V(8); PG8_WAIT_L(0); PG8_BAR; PG8_MMA(0, 0, At, B0); PG8_MMA(0, 1, At, B1); PG8_BAR; PG8_SCHED;
;             PG8_LDA(At, 0, 1); PG8_STAGE(PG8_SB(0, 0), b2); PG8_STAGE(PG8_SB(0, 1), b2 + hstep); PG8_STAGE(PG8_SA(0, 0), a2);
;             PG8_WAIT_V(8); PG8_WAIT_L(0); PG8_BAR; PG8_MMA(1, 0, At, B0); PG8_MMA(1, 1, At, B1); PG8_BAR; PG8_SCHED;
	s_waitcnt lgkmcnt(0)
	v_mfma_f32_16x16x32_bf16 v[128:131], v[142:145], v[188:191], v[128:131]
	v_mfma_f32_16x16x32_bf16 v[112:115], v[150:153], v[188:191], v[112:115]
	v_mfma_f32_16x16x32_bf16 v[124:127], v[142:145], v[196:199], v[124:127]
	v_mfma_f32_16x16x32_bf16 v[104:107], v[150:153], v[196:199], v[104:107]
	v_mfma_f32_16x16x32_bf16 v[120:123], v[142:145], v[204:207], v[120:123]
	v_mfma_f32_16x16x32_bf16 v[96:99], v[150:153], v[204:207], v[96:99]
	v_mfma_f32_16x16x32_bf16 v[116:119], v[142:145], v[212:215], v[116:119]
	v_mfma_f32_16x16x32_bf16 v[92:95], v[150:153], v[212:215], v[92:95]
	v_mfma_f32_16x16x32_bf16 v[128:131], v[146:149], v[192:195], v[128:131]
	v_mfma_f32_16x16x32_bf16 v[112:115], v[154:157], v[192:195], v[112:115]
	v_mfma_f32_16x16x32_bf16 v[124:127], v[146:149], v[200:203], v[124:127]
	v_mfma_f32_16x16x32_bf16 v[104:107], v[154:157], v[200:203], v[104:107]
	v_mfma_f32_16x16x32_bf16 v[120:123], v[146:149], v[208:211], v[120:123]
	v_mfma_f32_16x16x32_bf16 v[96:99], v[154:157], v[208:211], v[96:99]
	v_mfma_f32_16x16x32_bf16 v[116:119], v[146:149], v[234:237], v[116:119]
	v_mfma_f32_16x16x32_bf16 v[92:95], v[154:157], v[234:237], v[92:95]
	v_mfma_f32_16x16x32_bf16 v[80:83], v[158:161], v[188:191], v[80:83]
	v_mfma_f32_16x16x32_bf16 v[52:55], v[180:183], v[188:191], v[52:55]
	v_mfma_f32_16x16x32_bf16 v[72:75], v[158:161], v[196:199], v[72:75]
	v_mfma_f32_16x16x32_bf16 v[44:47], v[180:183], v[196:199], v[44:47]
	v_mfma_f32_16x16x32_bf16 v[64:67], v[158:161], v[204:207], v[64:67]
	v_mfma_f32_16x16x32_bf16 v[40:43], v[180:183], v[204:207], v[40:43]
	v_mfma_f32_16x16x32_bf16 v[56:59], v[158:161], v[212:215], v[56:59]
	v_mfma_f32_16x16x32_bf16 v[32:35], v[180:183], v[212:215], v[32:35]
	v_mfma_f32_16x16x32_bf16 v[80:83], v[162:165], v[192:195], v[80:83]
	v_mfma_f32_16x16x32_bf16 v[52:55], v[184:187], v[192:195], v[52:55]
	v_mfma_f32_16x16x32_bf16 v[72:75], v[162:165], v[200:203], v[72:75]
	v_mfma_f32_16x16x32_bf16 v[44:47], v[184:187], v[200:203], v[44:47]
	v_mfma_f32_16x16x32_bf16 v[64:67], v[162:165], v[208:211], v[64:67]
	v_mfma_f32_16x16x32_bf16 v[40:43], v[184:187], v[208:211], v[40:43]
	v_mfma_f32_16x16x32_bf16 v[56:59], v[162:165], v[234:237], v[56:59]
	v_mfma_f32_16x16x32_bf16 v[32:35], v[184:187], v[234:237], v[32:35]
	s_barrier
	s_add_i32 s57, s57, s87
	v_lshl_add_u64 v[166:167], s[52:53], 0, v[132:133]
	s_mov_b32 m0, s57
	ds_read_b128 v[188:191], v140 offset:16384
	ds_read_b128 v[192:195], v140 offset:17408
	ds_read_b128 v[196:199], v140 offset:18432
	ds_read_b128 v[200:203], v140 offset:19456
	ds_read_b128 v[204:207], v140 offset:20480
	ds_read_b128 v[208:211], v140 offset:21504
	ds_read_b128 v[212:215], v140 offset:22528
	ds_read_b128 v[234:237], v140 offset:23552
	global_load_lds_dwordx4 v[166:167], off
	s_add_i32 m0, s57, 0x2000
	s_add_u32 s58, s52, 0x40000
	v_lshl_add_u64 v[168:169], s[52:53], 0, v[0:1]
	s_addc_u32 s59, s53, 0
	s_add_i32 s57, s60, s87
	global_load_lds_dwordx4 v[168:169], off
	v_lshl_add_u64 v[216:217], s[58:59], 0, v[132:133]
	s_mov_b32 m0, s57
	v_lshl_add_u64 v[238:239], s[54:55], 0, v[0:1]
	global_load_lds_dwordx4 v[216:217], off
	v_lshl_add_u64 v[216:217], s[58:59], 0, v[0:1]
	s_add_i32 m0, s57, 0x2000
	s_nop 0
	global_load_lds_dwordx4 v[216:217], off
	v_lshl_add_u64 v[216:217], s[54:55], 0, v[132:133]
	s_mov_b32 m0, s85
	s_nop 0
	global_load_lds_dwordx4 v[216:217], off
	s_mov_b32 m0, s9
	s_nop 0
	global_load_lds_dwordx4 v[238:239], off
	s_waitcnt vmcnt(8)
	s_waitcnt lgkmcnt(0)
	s_barrier
	s_waitcnt lgkmcnt(0)
	v_mfma_f32_16x16x32_bf16 v[108:111], v[142:145], v[188:191], v[108:111]
	v_mfma_f32_16x16x32_bf16 v[76:79], v[150:153], v[188:191], v[76:79]
	v_mfma_f32_16x16x32_bf16 v[100:103], v[142:145], v[196:199], v[100:103]
	v_mfma_f32_16x16x32_bf16 v[68:71], v[150:153], v[196:199], v[68:71]
	v_mfma_f32_16x16x32_bf16 v[88:91], v[142:145], v[204:207], v[88:91]
	v_mfma_f32_16x16x32_bf16 v[60:63], v[150:153], v[204:207], v[60:63]
	v_mfma_f32_16x16x32_bf16 v[84:87], v[142:145], v[212:215], v[84:87]
	v_mfma_f32_16x16x32_bf16 v[48:51], v[150:153], v[212:215], v[48:51]
	v_mfma_f32_16x16x32_bf16 v[108:111], v[146:149], v[192:195], v[108:111]
	v_mfma_f32_16x16x32_bf16 v[76:79], v[154:157], v[192:195], v[76:79]
	v_mfma_f32_16x16x32_bf16 v[100:103], v[146:149], v[200:203], v[100:103]
	v_mfma_f32_16x16x32_bf16 v[68:71], v[154:157], v[200:203], v[68:71]
	v_mfma_f32_16x16x32_bf16 v[88:91], v[146:149], v[208:211], v[88:91]
	v_mfma_f32_16x16x32_bf16 v[60:63], v[154:157], v[208:211], v[60:63]
	v_mfma_f32_16x16x32_bf16 v[84:87], v[146:149], v[234:237], v[84:87]
	v_mfma_f32_16x16x32_bf16 v[48:51], v[154:157], v[234:237], v[48:51]
	v_mfma_f32_16x16x32_bf16 v[36:39], v[158:161], v[188:191], v[36:39]
	v_mfma_f32_16x16x32_bf16 v[16:19], v[180:183], v[188:191], v[16:19]
	v_mfma_f32_16x16x32_bf16 v[28:31], v[158:161], v[196:199], v[28:31]
	v_mfma_f32_16x16x32_bf16 v[12:15], v[180:183], v[196:199], v[12:15]
	v_mfma_f32_16x16x32_bf16 v[24:27], v[158:161], v[204:207], v[24:27]
	v_mfma_f32_16x16x32_bf16 v[8:11], v[180:183], v[204:207], v[8:11]
	v_mfma_f32_16x16x32_bf16 v[20:23], v[158:161], v[212:215], v[20:23]
	v_mfma_f32_16x16x32_bf16 v[4:7], v[180:183], v[212:215], v[4:7]
	v_mfma_f32_16x16x32_bf16 v[36:39], v[162:165], v[192:195], v[36:39]
	v_mfma_f32_16x16x32_bf16 v[16:19], v[184:187], v[192:195], v[16:19]
	v_mfma_f32_16x16x32_bf16 v[28:31], v[162:165], v[200:203], v[28:31]
	v_mfma_f32_16x16x32_bf16 v[12:15], v[184:187], v[200:203], v[12:15]
	v_mfma_f32_16x16x32_bf16 v[24:27], v[162:165], v[208:211], v[24:27]
	v_mfma_f32_16x16x32_bf16 v[8:11], v[184:187], v[208:211], v[8:11]
	v_mfma_f32_16x16x32_bf16 v[20:23], v[162:165], v[234:237], v[20:23]
	v_mfma_f32_16x16x32_bf16 v[4:7], v[184:187], v[234:237], v[4:7]
	s_barrier
; #define PG8_STAGE(bufoff, gbase) do { _Pragma("unroll") for (int _i = 0; _i < 2; ++_i) \
;         __builtin_amdgcn_global_load_lds((const unsigned*)((const char*)(gbase) + voffA[_i]), (LAS unsigned*)(lds + (bufoff) + ldsw + _i * 8192), 16, 0, 0); } while (0)
; #define PG8_LDA(dst, b, h) do { _Pragma("unroll") for (int m = 0; m < 4; ++m) _Pragma("unroll") for (int k = 0; k < 2; ++k) dst[m][k] = *(const LAS bf16x8*)(lds + PG8_SA(b, h) + aoff + m * 2048 + k * 1024); } while (0)
; #define PG8_LDB(dst, b, h) do { _Pragma("unroll") for (int n = 0; n < 2; ++n) _Pragma("unroll") for (int k = 0; k < 2; ++k) dst[n][k] = *(const LAS bf16x8*)(lds + PG8_SB(b, h) + boff + n * 2048 + k * 1024); } while (0)
; #define PG8_MMA(ai, bj, At, Bt) do { __builtin_amdgcn_s_setprio(1); _Pragma("unroll") for (int m = 0; m < 4; ++m) _Pragma("unroll") for (int n = 0; n < 2; ++n) _Pragma("unroll") for (int k = 0; k < 2; ++k) \
;         acc[ai][bj][m][n] = __builtin_amdgcn_mfma_f32_16x16x32_bf16(Bt[n][k], At[m][k], acc[ai][bj][m][n], 0, 0, 0); __builtin_amdgcn_s_setprio(0); } while (0)
; #define PG8_WAIT_V(n) asm volatile("s_waitcnt vmcnt(" #n ")" ::: "memory")
; #define PG8_WAIT_L(n) asm volatile("s_waitcnt lgkmcnt(" #n ")" ::: "memory")
; #define PG8_BAR __builtin_amdgcn_s_barrier()
; #define PG8_SCHED __builtin_amdgcn_sched_barrier(0)
; template <class Epi, class Sched>
; __device__ __forceinline__ void gemm_phase(LAS unsigned char* lds, const Gemm g, const Sched& S, const Epi& E, int wid) {
;     ...
;             PG8_LDB(B0, 1, 0); PG8_LDB(B1, 1, 1); PG8_SCHED; PG8_LDA(At, 1, 0); PG8_STAGE(PG8_SA(0, 1), a2 + hstep);
;             PG8_WAIT_V(8); PG8_WAIT_L(0); PG8_BAR; PG8_MMA(0, 0, At, B0); PG8_MMA(0, 1, At, B1); PG8_BAR; PG8_SCHED;
	s_add_i32 s57, 0, 0x18000
	v_add_u32_e32 v141, s57, v138
	s_add_i32 s58, 0, 0x1c000
	ds_read_b128 v[142:145], v141
	ds_read_b128 v[146:149], v141 offset:1024
	ds_read_b128 v[150:153], v141 offset:2048
	ds_read_b128 v[154:157], v141 offset:3072
	v_add_u32_e32 v141, s58, v138
	ds_read_b128 v[158:161], v141
	ds_read_b128 v[162:165], v141 offset:1024
	ds_read_b128 v[180:183], v141 offset:2048
	ds_read_b128 v[184:187], v141 offset:3072
	s_add_u32 s54, s54, 0x40000
	s_addc_u32 s55, s55, 0
	s_mov_b32 m0, s10
	v_lshl_add_u64 v[240:241], s[54:55], 0, v[132:133]
	ds_read_b128 v[188:191], v140 offset:32768
	ds_read_b128 v[192:195], v140 offset:33792
	ds_read_b128 v[196:199], v140 offset:34816
	ds_read_b128 v[200:203], v140 offset:35840
	ds_read_b128 v[204:207], v140 offset:36864
	ds_read_b128 v[208:211], v140 offset:37888
	ds_read_b128 v[212:215], v140 offset:38912
	ds_read_b128 v[234:237], v140 offset:39936
	global_load_lds_dwordx4 v[240:241], off
	v_lshl_add_u64 v[240:241], s[54:55], 0, v[0:1]
	s_mov_b32 m0, s11
	s_nop 0
	global_load_lds_dwordx4 v[240:241], off
	s_waitcnt vmcnt(8)
	s_waitcnt lgkmcnt(0)
	s_barrier
	s_waitcnt lgkmcnt(0)
	v_mfma_f32_16x16x32_bf16 v[128:131], v[142:145], v[188:191], v[128:131]
	v_mfma_f32_16x16x32_bf16 v[112:115], v[150:153], v[188:191], v[112:115]
	v_mfma_f32_16x16x32_bf16 v[124:127], v[142:145], v[196:199], v[124:127]
	v_mfma_f32_16x16x32_bf16 v[104:107], v[150:153], v[196:199], v[104:107]
	v_mfma_f32_16x16x32_bf16 v[120:123], v[142:145], v[204:207], v[120:123]
	v_mfma_f32_16x16x32_bf16 v[96:99], v[150:153], v[204:207], v[96:99]
	v_mfma_f32_16x16x32_bf16 v[116:119], v[142:145], v[212:215], v[116:119]
	v_mfma_f32_16x16x32_bf16 v[92:95], v[150:153], v[212:215], v[92:95]
	v_mfma_f32_16x16x32_bf16 v[128:131], v[146:149], v[192:195], v[128:131]
	v_mfma_f32_16x16x32_bf16 v[112:115], v[154:157], v[192:195], v[112:115]
	v_mfma_f32_16x16x32_bf16 v[124:127], v[146:149], v[200:203], v[124:127]
	v_mfma_f32_16x16x32_bf16 v[104:107], v[154:157], v[200:203], v[104:107]
	v_mfma_f32_16x16x32_bf16 v[120:123], v[146:149], v[208:211], v[120:123]
	v_mfma_f32_16x16x32_bf16 v[96:99], v[154:157], v[208:211], v[96:99]
	v_mfma_f32_16x16x32_bf16 v[116:119], v[146:149], v[234:237], v[116:119]
	v_mfma_f32_16x16x32_bf16 v[92:95], v[154:157], v[234:237], v[92:95]
	v_mfma_f32_16x16x32_bf16 v[80:83], v[158:161], v[188:191], v[80:83]
	v_mfma_f32_16x16x32_bf16 v[52:55], v[180:183], v[188:191], v[52:55]
	v_mfma_f32_16x16x32_bf16 v[72:75], v[158:161], v[196:199], v[72:75]
	v_mfma_f32_16x16x32_bf16 v[44:47], v[180:183], v[196:199], v[44:47]
	v_mfma_f32_16x16x32_bf16 v[64:67], v[158:161], v[204:207], v[64:67]
	v_mfma_f32_16x16x32_bf16 v[40:43], v[180:183], v[204:207], v[40:43]
	v_mfma_f32_16x16x32_bf16 v[56:59], v[158:161], v[212:215], v[56:59]
	v_mfma_f32_16x16x32_bf16 v[32:35], v[180:183], v[212:215], v[32:35]
	v_mfma_f32_16x16x32_bf16 v[80:83], v[162:165], v[192:195], v[80:83]
	v_mfma_f32_16x16x32_bf16 v[52:55], v[184:187], v[192:195], v[52:55]
	v_mfma_f32_16x16x32_bf16 v[72:75], v[162:165], v[200:203], v[72:75]
	v_mfma_f32_16x16x32_bf16 v[44:47], v[184:187], v[200:203], v[44:47]
	v_mfma_f32_16x16x32_bf16 v[64:67], v[162:165], v[208:211], v[64:67]
	v_mfma_f32_16x16x32_bf16 v[40:43], v[184:187], v[208:211], v[40:43]
	v_mfma_f32_16x16x32_bf16 v[56:59], v[162:165], v[234:237], v[56:59]
	v_mfma_f32_16x16x32_bf16 v[32:35], v[184:187], v[234:237], v[32:35]
	s_barrier
; #define PG8_STAGE(bufoff, gbase) do { _Pragma("unroll") for (int _i = 0; _i < 2; ++_i) \
;         __builtin_amdgcn_global_load_lds((const unsigned*)((const char*)(gbase) + voffA[_i]), (LAS unsigned*)(lds + (bufoff) + ldsw + _i * 8192), 16, 0, 0); } while (0)
; #define PG8_LDA(dst, b, h) do { _Pragma("unroll") for (int m = 0; m < 4; ++m) _Pragma("unroll") for (int k = 0; k < 2; ++k) dst[m][k] = *(const LAS bf16x8*)(lds + PG8_SA(b, h) + aoff + m * 2048 + k * 1024); } while (0)
; #define PG8_MMA(ai, bj, At, Bt) do { __builtin_amdgcn_s_setprio(1); _Pragma("unroll") for (int m = 0; m < 4; ++m) _Pragma("unroll") for (int n = 0; n < 2; ++n) _Pragma("unroll") for (int k = 0; k < 2; ++k) \
;         acc[ai][bj][m][n] = __builtin_amdgcn_mfma_f32_16x16x32_bf16(Bt[n][k], At[m][k], acc[ai][bj][m][n], 0, 0, 0); __builtin_amdgcn_s_setprio(0); } while (0)
; #define PG8_WAIT_V(n) asm volatile("s_waitcnt vmcnt(" #n ")" ::: "memory")
; #define PG8_WAIT_L(n) asm volatile("s_waitcnt lgkmcnt(" #n ")" ::: "memory")
; #define PG8_BAR __builtin_amdgcn_s_barrier()
; #define PG8_SCHED __builtin_amdgcn_sched_barrier(0)
; template <class Epi, class Sched>
; __device__ __forceinline__ void gemm_phase(LAS unsigned char* lds, const Gemm g, const Sched& S, const Epi& E, int wid) {
;     ...
;             PG8_LDA(At, 1, 1); PG8_STAGE(PG8_SB(1, 0), b3); PG8_STAGE(PG8_SB(1, 1), b3 + hstep); PG8_STAGE(PG8_SA(1, 0), a3);
;             PG8_WAIT_V(8); PG8_WAIT_L(0); PG8_BAR; PG8_MMA(1, 0, At, B0); PG8_MMA(1, 1, At, B1); PG8_BAR; PG8_SCHED;
;         }
;         if (wr == 0) PG8_BAR;
	s_add_i32 s54, s57, s87
	v_lshl_add_u64 v[166:167], v[166:167], 0, s[92:93]
	s_mov_b32 m0, s54
	ds_read_b128 v[188:191], v140 offset:49152
	ds_read_b128 v[192:195], v140 offset:50176
	ds_read_b128 v[196:199], v140 offset:51200
	ds_read_b128 v[200:203], v140 offset:52224
	ds_read_b128 v[204:207], v140 offset:53248
	ds_read_b128 v[208:211], v140 offset:54272
	ds_read_b128 v[212:215], v140 offset:55296
	ds_read_b128 v[234:237], v140 offset:56320
	global_load_lds_dwordx4 v[166:167], off
	s_add_i32 m0, s54, 0x2000
	s_add_u32 s52, s52, 0x40080
	v_lshl_add_u64 v[166:167], v[168:169], 0, s[92:93]
	s_addc_u32 s53, s53, 0
	s_add_i32 s54, s58, s87
	global_load_lds_dwordx4 v[166:167], off
	v_lshl_add_u64 v[166:167], s[52:53], 0, v[132:133]
	s_mov_b32 m0, s54
	s_nop 0
	global_load_lds_dwordx4 v[166:167], off
	v_lshl_add_u64 v[166:167], s[52:53], 0, v[0:1]
	s_add_i32 m0, s54, 0x2000
	s_nop 0
	global_load_lds_dwordx4 v[166:167], off
	v_lshl_add_u64 v[166:167], v[216:217], 0, s[92:93]
	s_mov_b32 m0, s20
	s_nop 0
	global_load_lds_dwordx4 v[166:167], off
	v_lshl_add_u64 v[166:167], v[238:239], 0, s[92:93]
	s_mov_b32 m0, s21
	s_nop 0
	global_load_lds_dwordx4 v[166:167], off
	s_waitcnt vmcnt(8)
	s_waitcnt lgkmcnt(0)
	s_barrier
	s_waitcnt lgkmcnt(0)
	v_mfma_f32_16x16x32_bf16 v[108:111], v[142:145], v[188:191], v[108:111]
	v_mfma_f32_16x16x32_bf16 v[76:79], v[150:153], v[188:191], v[76:79]
	v_mfma_f32_16x16x32_bf16 v[100:103], v[142:145], v[196:199], v[100:103]
	v_mfma_f32_16x16x32_bf16 v[68:71], v[150:153], v[196:199], v[68:71]
	v_mfma_f32_16x16x32_bf16 v[88:91], v[142:145], v[204:207], v[88:91]
	v_mfma_f32_16x16x32_bf16 v[60:63], v[150:153], v[204:207], v[60:63]
	v_mfma_f32_16x16x32_bf16 v[84:87], v[142:145], v[212:215], v[84:87]
	v_mfma_f32_16x16x32_bf16 v[48:51], v[150:153], v[212:215], v[48:51]
	v_mfma_f32_16x16x32_bf16 v[108:111], v[146:149], v[192:195], v[108:111]
	v_mfma_f32_16x16x32_bf16 v[76:79], v[154:157], v[192:195], v[76:79]
	v_mfma_f32_16x16x32_bf16 v[100:103], v[146:149], v[200:203], v[100:103]
	v_mfma_f32_16x16x32_bf16 v[68:71], v[154:157], v[200:203], v[68:71]
	v_mfma_f32_16x16x32_bf16 v[88:91], v[146:149], v[208:211], v[88:91]
	v_mfma_f32_16x16x32_bf16 v[60:63], v[154:157], v[208:211], v[60:63]
	v_mfma_f32_16x16x32_bf16 v[84:87], v[146:149], v[234:237], v[84:87]
	v_mfma_f32_16x16x32_bf16 v[48:51], v[154:157], v[234:237], v[48:51]
	v_mfma_f32_16x16x32_bf16 v[36:39], v[158:161], v[188:191], v[36:39]
	v_mfma_f32_16x16x32_bf16 v[16:19], v[180:183], v[188:191], v[16:19]
	v_mfma_f32_16x16x32_bf16 v[28:31], v[158:161], v[196:199], v[28:31]
	v_mfma_f32_16x16x32_bf16 v[12:15], v[180:183], v[196:199], v[12:15]
	v_mfma_f32_16x16x32_bf16 v[24:27], v[158:161], v[204:207], v[24:27]
	v_mfma_f32_16x16x32_bf16 v[8:11], v[180:183], v[204:207], v[8:11]
	v_mfma_f32_16x16x32_bf16 v[20:23], v[158:161], v[212:215], v[20:23]
	v_mfma_f32_16x16x32_bf16 v[4:7], v[180:183], v[212:215], v[4:7]
	v_mfma_f32_16x16x32_bf16 v[36:39], v[162:165], v[192:195], v[36:39]
	v_mfma_f32_16x16x32_bf16 v[16:19], v[184:187], v[192:195], v[16:19]
	v_mfma_f32_16x16x32_bf16 v[28:31], v[162:165], v[200:203], v[28:31]
	v_mfma_f32_16x16x32_bf16 v[12:15], v[184:187], v[200:203], v[12:15]
	v_mfma_f32_16x16x32_bf16 v[24:27], v[162:165], v[208:211], v[24:27]
	v_mfma_f32_16x16x32_bf16 v[8:11], v[184:187], v[208:211], v[8:11]
	v_mfma_f32_16x16x32_bf16 v[20:23], v[162:165], v[234:237], v[20:23]
	v_mfma_f32_16x16x32_bf16 v[4:7], v[184:187], v[234:237], v[4:7]
	s_barrier
	s_add_i32 s56, s56, 2
	s_add_u32 s50, s50, 0x100
	s_addc_u32 s51, s51, 0
	s_add_u32 s43, s43, 0x100
	s_addc_u32 s45, s45, 0
	s_cmp_gt_u32 s56, 13
	s_cbranch_scc0 .LBB0_1520
	s_setprio 0
	v_readlane_b32 s0, v252, 28
	v_readlane_b32 s1, v252, 29
	s_and_b64 vcc, exec, s[0:1]
	s_cbranch_vccz .LBB0_1523
	s_barrier

; #define PG8_STAGE(bufoff, gbase) do { _Pragma("unroll") for (int _i = 0; _i < 2; ++_i) \
;         __builtin_amdgcn_global_load_lds((const unsigned*)((const char*)(gbase) + voffA[_i]), (LAS unsigned*)(lds + (bufoff) + ldsw + _i * 8192), 16, 0, 0); } while (0)
; #define PG8_LDA(dst, b, h) do { _Pragma("unroll") for (int m = 0; m < 4; ++m) _Pragma("unroll") for (int k = 0; k < 2; ++k) dst[m][k] = *(const LAS bf16x8*)(lds + PG8_SA(b, h) + aoff + m * 2048 + k * 1024); } while (0)
; #define PG8_LDB(dst, b, h) do { _Pragma("unroll") for (int n = 0; n < 2; ++n) _Pragma("unroll") for (int k = 0; k < 2; ++k) dst[n][k] = *(const LAS bf16x8*)(lds + PG8_SB(b, h) + boff + n * 2048 + k * 1024); } while (0)
; #define PG8_MMA(ai, bj, At, Bt) do { __builtin_amdgcn_s_setprio(1); _Pragma("unroll") for (int m = 0; m < 4; ++m) _Pragma("unroll") for (int n = 0; n < 2; ++n) _Pragma("unroll") for (int k = 0; k < 2; ++k) \
;         acc[ai][bj][m][n] = __builtin_amdgcn_mfma_f32_16x16x32_bf16(Bt[n][k], At[m][k], acc[ai][bj][m][n], 0, 0, 0); __builtin_amdgcn_s_setprio(0); } while (0)
; #define PG8_WAIT_V(n) asm volatile("s_waitcnt vmcnt(" #n ")" ::: "memory")
; template <class Epi, class Sched>
; __device__ __forceinline__ void gemm_phase(LAS unsigned char* lds, const Gemm g, const Sched& S, const Epi& E, int wid) {
;     ...
; #pragma unroll
;     for (int a = 0; a < 2; ++a)
; #pragma unroll
;         for (int b = 0; b < 2; ++b)
; #pragma unroll
;             for (int m = 0; m < 4; ++m)
; #pragma unroll
;                 for (int n = 0; n < 2; ++n) acc[a][b][m][n] = (f32x4){0.f, 0.f, 0.f, 0.f};
;     ...
;         const bool has_next = S.next(ui + 1, nxt);
;         const char* nA = has_next ? (const char*)g.A + (size_t)nxt.pm * tstep : cA; const char* nB = has_next ? (const char*)g.Bt + (size_t)nxt.pn * tstep : cB;
;         for (int t = 0; t < nt; t += 2) {
;             const bool last = (t == nt - 2);
;             const char* a1 = cA + (size_t)(t + 1) * kstep;
;             const char* a2 = last ? nA : cA + (size_t)(t + 2) * kstep; const char* b2 = last ? nB : cB + (size_t)(t + 2) * kstep;
;             const char* a3 = a2 + kstep; const char* b3 = b2 + kstep;
;             PG8_LDB(B0, 0, 0); PG8_LDB(B1, 0, 1); PG8_SCHED; PG8_LDA(At, 0, 0); PG8_STAGE(PG8_SA(1, 1), a1 + hstep);
;             PG8_WAIT_V(8); PG8_WAIT_L(0); PG8_BAR; PG8_MMA(0, 0, At, B0); PG8_MMA(0, 1, At, B1); PG8_BAR; PG8_SCHED;
.LBB0_1832:
	s_ashr_i32 s53, s52, 31
	s_lshl_b64 s[0:1], s[52:53], 19
	s_add_u32 s54, s74, s0
	s_addc_u32 s55, s75, s1
	s_and_b64 s[0:1], s[42:43], exec
	s_cselect_b32 s0, s55, s45
	s_cselect_b32 s1, s54, s44
	s_ashr_i32 s51, s50, 31
	s_lshl_b64 s[56:57], s[50:51], 19
	s_add_u32 s76, s2, s56
	s_addc_u32 s77, s8, s57
	s_and_b64 s[60:61], s[42:43], exec
	s_cselect_b32 s30, s77, s59
	s_cselect_b32 s51, s76, s58
	s_add_u32 s53, s58, 0x100
	v_mov_b32_e32 v4, 0
	s_addc_u32 s66, s59, 0
	s_mov_b32 s67, -2
	v_mov_b32_e32 v5, v4
	s_waitcnt lgkmcnt(0)
	v_mov_b32_e32 v6, v4
	v_mov_b32_e32 v7, v4
	v_mov_b32_e32 v8, v4
	v_mov_b32_e32 v9, v4
	v_mov_b32_e32 v10, v4
	v_mov_b32_e32 v11, v4
	v_mov_b32_e32 v20, v4
	v_mov_b32_e32 v21, v4
	v_mov_b32_e32 v22, v4
	v_mov_b32_e32 v23, v4
	v_mov_b32_e32 v24, v4
	v_mov_b32_e32 v25, v4
	v_mov_b32_e32 v26, v4
	v_mov_b32_e32 v27, v4
	v_mov_b32_e32 v36, v4
	v_mov_b32_e32 v37, v4
	v_mov_b32_e32 v38, v4
	v_mov_b32_e32 v39, v4
	v_mov_b32_e32 v40, v4
	v_mov_b32_e32 v41, v4
	v_mov_b32_e32 v42, v4
	v_mov_b32_e32 v43, v4
	v_mov_b32_e32 v52, v4
	v_mov_b32_e32 v53, v4
	v_mov_b32_e32 v54, v4
	v_mov_b32_e32 v55, v4
	v_mov_b32_e32 v56, v4
	v_mov_b32_e32 v57, v4
	v_mov_b32_e32 v58, v4
	v_mov_b32_e32 v59, v4
	v_mov_b32_e32 v12, v4
	v_mov_b32_e32 v13, v4
	v_mov_b32_e32 v14, v4
	v_mov_b32_e32 v15, v4
	v_mov_b32_e32 v16, v4
	v_mov_b32_e32 v17, v4
	v_mov_b32_e32 v18, v4
	v_mov_b32_e32 v19, v4
	v_mov_b32_e32 v28, v4
	v_mov_b32_e32 v29, v4
	v_mov_b32_e32 v30, v4
	v_mov_b32_e32 v31, v4
	v_mov_b32_e32 v32, v4
	v_mov_b32_e32 v33, v4
	v_mov_b32_e32 v34, v4
	v_mov_b32_e32 v35, v4
	v_mov_b32_e32 v44, v4
	v_mov_b32_e32 v45, v4
	v_mov_b32_e32 v46, v4
	v_mov_b32_e32 v47, v4
	v_mov_b32_e32 v48, v4
	v_mov_b32_e32 v49, v4
	v_mov_b32_e32 v50, v4
	v_mov_b32_e32 v51, v4
	v_mov_b32_e32 v60, v4
	v_mov_b32_e32 v61, v4
	v_mov_b32_e32 v62, v4
	v_mov_b32_e32 v63, v4
	v_mov_b32_e32 v64, v4
	v_mov_b32_e32 v65, v4
	v_mov_b32_e32 v66, v4
	v_mov_b32_e32 v67, v4
	v_mov_b32_e32 v68, v4
	v_mov_b32_e32 v69, v4
	v_mov_b32_e32 v70, v4
	v_mov_b32_e32 v71, v4
	v_mov_b32_e32 v72, v4
	v_mov_b32_e32 v73, v4
	v_mov_b32_e32 v74, v4
	v_mov_b32_e32 v75, v4
	v_mov_b32_e32 v84, v4
	v_mov_b32_e32 v85, v4
	v_mov_b32_e32 v86, v4
	v_mov_b32_e32 v87, v4
	v_mov_b32_e32 v88, v4
	v_mov_b32_e32 v89, v4
	v_mov_b32_e32 v90, v4
	v_mov_b32_e32 v91, v4
	v_mov_b32_e32 v100, v4
	v_mov_b32_e32 v101, v4
	v_mov_b32_e32 v102, v4
	v_mov_b32_e32 v103, v4
	v_mov_b32_e32 v104, v4
	v_mov_b32_e32 v105, v4
	v_mov_b32_e32 v106, v4
	v_mov_b32_e32 v107, v4
	v_mov_b32_e32 v116, v4
	v_mov_b32_e32 v117, v4
	v_mov_b32_e32 v118, v4
	v_mov_b32_e32 v119, v4
	v_mov_b32_e32 v120, v4
	v_mov_b32_e32 v121, v4
	v_mov_b32_e32 v122, v4
	v_mov_b32_e32 v123, v4
	v_mov_b32_e32 v76, v4
	v_mov_b32_e32 v77, v4
	v_mov_b32_e32 v78, v4
	v_mov_b32_e32 v79, v4
	v_mov_b32_e32 v80, v4
	v_mov_b32_e32 v81, v4
	v_mov_b32_e32 v82, v4
	v_mov_b32_e32 v83, v4
	v_mov_b32_e32 v92, v4
	v_mov_b32_e32 v93, v4
	v_mov_b32_e32 v94, v4
	v_mov_b32_e32 v95, v4
	v_mov_b32_e32 v96, v4
	v_mov_b32_e32 v97, v4
	v_mov_b32_e32 v98, v4
	v_mov_b32_e32 v99, v4
	v_mov_b32_e32 v108, v4
	v_mov_b32_e32 v109, v4
	v_mov_b32_e32 v110, v4
	v_mov_b32_e32 v111, v4
	v_mov_b32_e32 v112, v4
	v_mov_b32_e32 v113, v4
	v_mov_b32_e32 v114, v4
	v_mov_b32_e32 v115, v4
	v_mov_b32_e32 v124, v4
	v_mov_b32_e32 v125, v4
	v_mov_b32_e32 v126, v4
	v_mov_b32_e32 v127, v4
	v_mov_b32_e32 v128, v4
	v_mov_b32_e32 v129, v4
	v_mov_b32_e32 v130, v4
	v_mov_b32_e32 v131, v4
	v_readlane_b32 s100, v251, 60
	s_cmp_lt_u32 s100, 4
	s_cbranch_scc1 .Lmy_prio_2
	s_setprio 1
.Lmy_prio_2:
.LBB0_1833:
	s_add_u32 s58, s44, 0x100
	s_addc_u32 s59, s45, 0
	s_add_i32 s68, 0, 0x10000
	s_cmp_eq_u32 s67, 12
	s_cselect_b32 s63, s0, s59
	s_cselect_b32 s62, s1, s58
	v_add_u32_e32 v3, s68, v161
	s_cselect_b32 s61, s30, s66
	s_cselect_b32 s60, s51, s53
	s_add_i32 s69, 0, 0x14000
	ds_read_b128 v[140:143], v3
	ds_read_b128 v[144:147], v3 offset:1024
	ds_read_b128 v[148:151], v3 offset:2048
	ds_read_b128 v[152:155], v3 offset:3072
	v_add_u32_e32 v3, s69, v161
	ds_read_b128 v[156:159], v3
	ds_read_b128 v[164:167], v3 offset:1024
	ds_read_b128 v[180:183], v3 offset:2048
	ds_read_b128 v[184:187], v3 offset:3072
	v_lshl_add_u64 v[168:169], s[44:45], 0, v[136:137]
	s_add_i32 m0, s85, 0xc000
	ds_read_b128 v[188:191], v163
	ds_read_b128 v[192:195], v163 offset:1024
	ds_read_b128 v[196:199], v163 offset:2048
	ds_read_b128 v[200:203], v163 offset:3072
	ds_read_b128 v[204:207], v163 offset:4096
	ds_read_b128 v[208:211], v163 offset:5120
	ds_read_b128 v[212:215], v163 offset:6144
	ds_read_b128 v[234:237], v163 offset:7168
	global_load_lds_dwordx4 v[168:169], off
	v_lshl_add_u64 v[168:169], s[44:45], 0, v[138:139]
	s_add_i32 m0, s85, 0xe000
	s_nop 0
	global_load_lds_dwordx4 v[168:169], off
	s_waitcnt vmcnt(8)
	s_waitcnt lgkmcnt(0)
	s_barrier
; #define PG8_STAGE(bufoff, gbase) do { _Pragma("unroll") for (int _i = 0; _i < 2; ++_i) \
;         __builtin_amdgcn_global_load_lds((const unsigned*)((const char*)(gbase) + voffA[_i]), (LAS unsigned*)(lds + (bufoff) + ldsw + _i * 8192), 16, 0, 0); } while (0)
; #define PG8_LDA(dst, b, h) do { _Pragma("unroll") for (int m = 0; m < 4; ++m) _Pragma("unroll") for (int k = 0; k < 2; ++k) dst[m][k] = *(const LAS bf16x8*)(lds + PG8_SA(b, h) + aoff + m * 2048 + k * 1024); } while (0)
; #define PG8_MMA(ai, bj, At, Bt) do { __builtin_amdgcn_s_setprio(1); _Pragma("unroll") for (int m = 0; m < 4; ++m) _Pragma("unroll") for (int n = 0; n < 2; ++n) _Pragma("unroll") for (int k = 0; k < 2; ++k) \
;         acc[ai][bj][m][n] = __builtin_amdgcn_mfma_f32_16x16x32_bf16(Bt[n][k], At[m][k], acc[ai][bj][m][n], 0, 0, 0); __builtin_amdgcn_s_setprio(0); } while (0)
; #define PG8_WAIT_V(n) asm volatile("s_waitcnt vmcnt(" #n ")" ::: "memory")
; #define PG8_WAIT_L(n) asm volatile("s_waitcnt lgkmcnt(" #n ")" ::: "memory")
; #define PG8_BAR __builtin_amdgcn_s_barrier()
; #define PG8_SCHED __builtin_amdgcn_sched_barrier(0)
; template <class Epi, class Sched>
; __device__ __forceinline__ void gemm_phase(LAS unsigned char* lds, const Gemm g, const Sched& S, const Epi& E, int wid) {
;     ...
;             PG8_WAIT_V(8); PG8_WAIT_L(0); PG8_BAR; PG8_MMA(0, 0, At, B0); PG8_MMA(0, 1, At, B1); PG8_BAR; PG8_SCHED;
;             PG8_LDA(At, 0, 1); PG8_STAGE(PG8_SB(0, 0), b2); PG8_STAGE(PG8_SB(0, 1), b2 + hstep); PG8_STAGE(PG8_SA(0, 0), a2);
;             PG8_WAIT_V(8); PG8_WAIT_L(0); PG8_BAR; PG8_MMA(1, 0, At, B0); PG8_MMA(1, 1, At, B1); PG8_BAR; PG8_SCHED;
	s_waitcnt lgkmcnt(0)
	v_mfma_f32_16x16x32_bf16 v[128:131], v[140:143], v[188:191], v[128:131]
	v_mfma_f32_16x16x32_bf16 v[124:127], v[148:151], v[188:191], v[124:127]
	v_mfma_f32_16x16x32_bf16 v[112:115], v[140:143], v[196:199], v[112:115]
	v_mfma_f32_16x16x32_bf16 v[108:111], v[148:151], v[196:199], v[108:111]
	v_mfma_f32_16x16x32_bf16 v[96:99], v[140:143], v[204:207], v[96:99]
	v_mfma_f32_16x16x32_bf16 v[92:95], v[148:151], v[204:207], v[92:95]
	v_mfma_f32_16x16x32_bf16 v[80:83], v[140:143], v[212:215], v[80:83]
	v_mfma_f32_16x16x32_bf16 v[76:79], v[148:151], v[212:215], v[76:79]
	v_mfma_f32_16x16x32_bf16 v[128:131], v[144:147], v[192:195], v[128:131]
	v_mfma_f32_16x16x32_bf16 v[124:127], v[152:155], v[192:195], v[124:127]
	v_mfma_f32_16x16x32_bf16 v[112:115], v[144:147], v[200:203], v[112:115]
	v_mfma_f32_16x16x32_bf16 v[108:111], v[152:155], v[200:203], v[108:111]
	v_mfma_f32_16x16x32_bf16 v[96:99], v[144:147], v[208:211], v[96:99]
	v_mfma_f32_16x16x32_bf16 v[92:95], v[152:155], v[208:211], v[92:95]
	v_mfma_f32_16x16x32_bf16 v[80:83], v[144:147], v[234:237], v[80:83]
	v_mfma_f32_16x16x32_bf16 v[76:79], v[152:155], v[234:237], v[76:79]
	v_mfma_f32_16x16x32_bf16 v[120:123], v[156:159], v[188:191], v[120:123]
	v_mfma_f32_16x16x32_bf16 v[116:119], v[180:183], v[188:191], v[116:119]
	v_mfma_f32_16x16x32_bf16 v[104:107], v[156:159], v[196:199], v[104:107]
	v_mfma_f32_16x16x32_bf16 v[100:103], v[180:183], v[196:199], v[100:103]
	v_mfma_f32_16x16x32_bf16 v[88:91], v[156:159], v[204:207], v[88:91]
	v_mfma_f32_16x16x32_bf16 v[84:87], v[180:183], v[204:207], v[84:87]
	v_mfma_f32_16x16x32_bf16 v[72:75], v[156:159], v[212:215], v[72:75]
	v_mfma_f32_16x16x32_bf16 v[68:71], v[180:183], v[212:215], v[68:71]
	v_mfma_f32_16x16x32_bf16 v[120:123], v[164:167], v[192:195], v[120:123]
	v_mfma_f32_16x16x32_bf16 v[116:119], v[184:187], v[192:195], v[116:119]
	v_mfma_f32_16x16x32_bf16 v[104:107], v[164:167], v[200:203], v[104:107]
	v_mfma_f32_16x16x32_bf16 v[100:103], v[184:187], v[200:203], v[100:103]
	v_mfma_f32_16x16x32_bf16 v[88:91], v[164:167], v[208:211], v[88:91]
	v_mfma_f32_16x16x32_bf16 v[84:87], v[184:187], v[208:211], v[84:87]
	v_mfma_f32_16x16x32_bf16 v[72:75], v[164:167], v[234:237], v[72:75]
	v_mfma_f32_16x16x32_bf16 v[68:71], v[184:187], v[234:237], v[68:71]
	s_barrier
	s_add_i32 s44, s68, s87
	v_lshl_add_u64 v[168:169], s[60:61], 0, v[132:133]
	s_mov_b32 m0, s44
	ds_read_b128 v[188:191], v163 offset:16384
	ds_read_b128 v[192:195], v163 offset:17408
	ds_read_b128 v[196:199], v163 offset:18432
	ds_read_b128 v[200:203], v163 offset:19456
	ds_read_b128 v[204:207], v163 offset:20480
	ds_read_b128 v[208:211], v163 offset:21504
	ds_read_b128 v[212:215], v163 offset:22528
	ds_read_b128 v[234:237], v163 offset:23552
	global_load_lds_dwordx4 v[168:169], off
	s_add_i32 m0, s44, 0x2000
	s_add_u32 s44, s60, 0x40000
	v_lshl_add_u64 v[216:217], s[60:61], 0, v[0:1]
	s_addc_u32 s45, s61, 0
	s_add_i32 s68, s69, s87
	global_load_lds_dwordx4 v[216:217], off
	v_lshl_add_u64 v[238:239], s[44:45], 0, v[132:133]
	s_mov_b32 m0, s68
	v_lshl_add_u64 v[240:241], s[62:63], 0, v[0:1]
	global_load_lds_dwordx4 v[238:239], off
	v_lshl_add_u64 v[238:239], s[44:45], 0, v[0:1]
	s_add_i32 m0, s68, 0x2000
	s_nop 0
	global_load_lds_dwordx4 v[238:239], off
	v_lshl_add_u64 v[238:239], s[62:63], 0, v[132:133]
	s_mov_b32 m0, s85
	s_nop 0
	global_load_lds_dwordx4 v[238:239], off
	s_mov_b32 m0, s9
	s_nop 0
	global_load_lds_dwordx4 v[240:241], off
	s_waitcnt vmcnt(8)
	s_waitcnt lgkmcnt(0)
	s_barrier
	s_waitcnt lgkmcnt(0)
	v_mfma_f32_16x16x32_bf16 v[64:67], v[140:143], v[188:191], v[64:67]
	v_mfma_f32_16x16x32_bf16 v[60:63], v[148:151], v[188:191], v[60:63]
	v_mfma_f32_16x16x32_bf16 v[48:51], v[140:143], v[196:199], v[48:51]
	v_mfma_f32_16x16x32_bf16 v[44:47], v[148:151], v[196:199], v[44:47]
	v_mfma_f32_16x16x32_bf16 v[32:35], v[140:143], v[204:207], v[32:35]
	v_mfma_f32_16x16x32_bf16 v[28:31], v[148:151], v[204:207], v[28:31]
	v_mfma_f32_16x16x32_bf16 v[16:19], v[140:143], v[212:215], v[16:19]
	v_mfma_f32_16x16x32_bf16 v[12:15], v[148:151], v[212:215], v[12:15]
	v_mfma_f32_16x16x32_bf16 v[64:67], v[144:147], v[192:195], v[64:67]
	v_mfma_f32_16x16x32_bf16 v[60:63], v[152:155], v[192:195], v[60:63]
	v_mfma_f32_16x16x32_bf16 v[48:51], v[144:147], v[200:203], v[48:51]
	v_mfma_f32_16x16x32_bf16 v[44:47], v[152:155], v[200:203], v[44:47]
	v_mfma_f32_16x16x32_bf16 v[32:35], v[144:147], v[208:211], v[32:35]
	v_mfma_f32_16x16x32_bf16 v[28:31], v[152:155], v[208:211], v[28:31]
	v_mfma_f32_16x16x32_bf16 v[16:19], v[144:147], v[234:237], v[16:19]
	v_mfma_f32_16x16x32_bf16 v[12:15], v[152:155], v[234:237], v[12:15]
	v_mfma_f32_16x16x32_bf16 v[56:59], v[156:159], v[188:191], v[56:59]
	v_mfma_f32_16x16x32_bf16 v[52:55], v[180:183], v[188:191], v[52:55]
	v_mfma_f32_16x16x32_bf16 v[40:43], v[156:159], v[196:199], v[40:43]
	v_mfma_f32_16x16x32_bf16 v[36:39], v[180:183], v[196:199], v[36:39]
	v_mfma_f32_16x16x32_bf16 v[24:27], v[156:159], v[204:207], v[24:27]
	v_mfma_f32_16x16x32_bf16 v[20:23], v[180:183], v[204:207], v[20:23]
	v_mfma_f32_16x16x32_bf16 v[8:11], v[156:159], v[212:215], v[8:11]
	v_mfma_f32_16x16x32_bf16 v[4:7], v[180:183], v[212:215], v[4:7]
	v_mfma_f32_16x16x32_bf16 v[56:59], v[164:167], v[192:195], v[56:59]
	v_mfma_f32_16x16x32_bf16 v[52:55], v[184:187], v[192:195], v[52:55]
	v_mfma_f32_16x16x32_bf16 v[40:43], v[164:167], v[200:203], v[40:43]
	v_mfma_f32_16x16x32_bf16 v[36:39], v[184:187], v[200:203], v[36:39]
	v_mfma_f32_16x16x32_bf16 v[24:27], v[164:167], v[208:211], v[24:27]
	v_mfma_f32_16x16x32_bf16 v[20:23], v[184:187], v[208:211], v[20:23]
	v_mfma_f32_16x16x32_bf16 v[8:11], v[164:167], v[234:237], v[8:11]
	v_mfma_f32_16x16x32_bf16 v[4:7], v[184:187], v[234:237], v[4:7]
	s_barrier
; #define PG8_STAGE(bufoff, gbase) do { _Pragma("unroll") for (int _i = 0; _i < 2; ++_i) \
;         __builtin_amdgcn_global_load_lds((const unsigned*)((const char*)(gbase) + voffA[_i]), (LAS unsigned*)(lds + (bufoff) + ldsw + _i * 8192), 16, 0, 0); } while (0)
; #define PG8_LDA(dst, b, h) do { _Pragma("unroll") for (int m = 0; m < 4; ++m) _Pragma("unroll") for (int k = 0; k < 2; ++k) dst[m][k] = *(const LAS bf16x8*)(lds + PG8_SA(b, h) + aoff + m * 2048 + k * 1024); } while (0)
; #define PG8_LDB(dst, b, h) do { _Pragma("unroll") for (int n = 0; n < 2; ++n) _Pragma("unroll") for (int k = 0; k < 2; ++k) dst[n][k] = *(const LAS bf16x8*)(lds + PG8_SB(b, h) + boff + n * 2048 + k * 1024); } while (0)
; #define PG8_MMA(ai, bj, At, Bt) do { __builtin_amdgcn_s_setprio(1); _Pragma("unroll") for (int m = 0; m < 4; ++m) _Pragma("unroll") for (int n = 0; n < 2; ++n) _Pragma("unroll") for (int k = 0; k < 2; ++k) \
;         acc[ai][bj][m][n] = __builtin_amdgcn_mfma_f32_16x16x32_bf16(Bt[n][k], At[m][k], acc[ai][bj][m][n], 0, 0, 0); __builtin_amdgcn_s_setprio(0); } while (0)
; #define PG8_WAIT_V(n) asm volatile("s_waitcnt vmcnt(" #n ")" ::: "memory")
; #define PG8_WAIT_L(n) asm volatile("s_waitcnt lgkmcnt(" #n ")" ::: "memory")
; #define PG8_BAR __builtin_amdgcn_s_barrier()
; #define PG8_SCHED __builtin_amdgcn_sched_barrier(0)
; template <class Epi, class Sched>
; __device__ __forceinline__ void gemm_phase(LAS unsigned char* lds, const Gemm g, const Sched& S, const Epi& E, int wid) {
;     ...
;             PG8_LDB(B0, 1, 0); PG8_LDB(B1, 1, 1); PG8_SCHED; PG8_LDA(At, 1, 0); PG8_STAGE(PG8_SA(0, 1), a2 + hstep);
;             PG8_WAIT_V(8); PG8_WAIT_L(0); PG8_BAR; PG8_MMA(0, 0, At, B0); PG8_MMA(0, 1, At, B1); PG8_BAR; PG8_SCHED;
	s_add_i32 s68, 0, 0x18000
	v_add_u32_e32 v3, s68, v161
	s_add_i32 s69, 0, 0x1c000
	ds_read_b128 v[140:143], v3
	ds_read_b128 v[144:147], v3 offset:1024
	ds_read_b128 v[148:151], v3 offset:2048
	ds_read_b128 v[152:155], v3 offset:3072
	v_add_u32_e32 v3, s69, v161
	ds_read_b128 v[156:159], v3
	ds_read_b128 v[164:167], v3 offset:1024
	ds_read_b128 v[180:183], v3 offset:2048
	ds_read_b128 v[184:187], v3 offset:3072
	s_add_u32 s44, s62, 0x40000
	s_addc_u32 s45, s63, 0
	s_mov_b32 m0, s10
	v_lshl_add_u64 v[242:243], s[44:45], 0, v[132:133]
	ds_read_b128 v[188:191], v163 offset:32768
	ds_read_b128 v[192:195], v163 offset:33792
	ds_read_b128 v[196:199], v163 offset:34816
	ds_read_b128 v[200:203], v163 offset:35840
	ds_read_b128 v[204:207], v163 offset:36864
	ds_read_b128 v[208:211], v163 offset:37888
	ds_read_b128 v[212:215], v163 offset:38912
	ds_read_b128 v[234:237], v163 offset:39936
	global_load_lds_dwordx4 v[242:243], off
	v_lshl_add_u64 v[242:243], s[44:45], 0, v[0:1]
	s_mov_b32 m0, s11
	s_nop 0
	global_load_lds_dwordx4 v[242:243], off
	s_waitcnt vmcnt(8)
	s_waitcnt lgkmcnt(0)
	s_barrier
	s_waitcnt lgkmcnt(0)
	v_mfma_f32_16x16x32_bf16 v[128:131], v[140:143], v[188:191], v[128:131]
	v_mfma_f32_16x16x32_bf16 v[124:127], v[148:151], v[188:191], v[124:127]
	v_mfma_f32_16x16x32_bf16 v[112:115], v[140:143], v[196:199], v[112:115]
	v_mfma_f32_16x16x32_bf16 v[108:111], v[148:151], v[196:199], v[108:111]
	v_mfma_f32_16x16x32_bf16 v[96:99], v[140:143], v[204:207], v[96:99]
	v_mfma_f32_16x16x32_bf16 v[92:95], v[148:151], v[204:207], v[92:95]
	v_mfma_f32_16x16x32_bf16 v[80:83], v[140:143], v[212:215], v[80:83]
	v_mfma_f32_16x16x32_bf16 v[76:79], v[148:151], v[212:215], v[76:79]
	v_mfma_f32_16x16x32_bf16 v[128:131], v[144:147], v[192:195], v[128:131]
	v_mfma_f32_16x16x32_bf16 v[124:127], v[152:155], v[192:195], v[124:127]
	v_mfma_f32_16x16x32_bf16 v[112:115], v[144:147], v[200:203], v[112:115]
	v_mfma_f32_16x16x32_bf16 v[108:111], v[152:155], v[200:203], v[108:111]
	v_mfma_f32_16x16x32_bf16 v[96:99], v[144:147], v[208:211], v[96:99]
	v_mfma_f32_16x16x32_bf16 v[92:95], v[152:155], v[208:211], v[92:95]
	v_mfma_f32_16x16x32_bf16 v[80:83], v[144:147], v[234:237], v[80:83]
	v_mfma_f32_16x16x32_bf16 v[76:79], v[152:155], v[234:237], v[76:79]
	v_mfma_f32_16x16x32_bf16 v[120:123], v[156:159], v[188:191], v[120:123]
	v_mfma_f32_16x16x32_bf16 v[116:119], v[180:183], v[188:191], v[116:119]
	v_mfma_f32_16x16x32_bf16 v[104:107], v[156:159], v[196:199], v[104:107]
	v_mfma_f32_16x16x32_bf16 v[100:103], v[180:183], v[196:199], v[100:103]
	v_mfma_f32_16x16x32_bf16 v[88:91], v[156:159], v[204:207], v[88:91]
	v_mfma_f32_16x16x32_bf16 v[84:87], v[180:183], v[204:207], v[84:87]
	v_mfma_f32_16x16x32_bf16 v[72:75], v[156:159], v[212:215], v[72:75]
	v_mfma_f32_16x16x32_bf16 v[68:71], v[180:183], v[212:215], v[68:71]
	v_mfma_f32_16x16x32_bf16 v[120:123], v[164:167], v[192:195], v[120:123]
	v_mfma_f32_16x16x32_bf16 v[116:119], v[184:187], v[192:195], v[116:119]
	v_mfma_f32_16x16x32_bf16 v[104:107], v[164:167], v[200:203], v[104:107]
	v_mfma_f32_16x16x32_bf16 v[100:103], v[184:187], v[200:203], v[100:103]
	v_mfma_f32_16x16x32_bf16 v[88:91], v[164:167], v[208:211], v[88:91]
	v_mfma_f32_16x16x32_bf16 v[84:87], v[184:187], v[208:211], v[84:87]
	v_mfma_f32_16x16x32_bf16 v[72:75], v[164:167], v[234:237], v[72:75]
	v_mfma_f32_16x16x32_bf16 v[68:71], v[184:187], v[234:237], v[68:71]
	s_barrier
; #define PG8_STAGE(bufoff, gbase) do { _Pragma("unroll") for (int _i = 0; _i < 2; ++_i) \
;         __builtin_amdgcn_global_load_lds((const unsigned*)((const char*)(gbase) + voffA[_i]), (LAS unsigned*)(lds + (bufoff) + ldsw + _i * 8192), 16, 0, 0); } while (0)
; #define PG8_LDA(dst, b, h) do { _Pragma("unroll") for (int m = 0; m < 4; ++m) _Pragma("unroll") for (int k = 0; k < 2; ++k) dst[m][k] = *(const LAS bf16x8*)(lds + PG8_SA(b, h) + aoff + m * 2048 + k * 1024); } while (0)
; #define PG8_MMA(ai, bj, At, Bt) do { __builtin_amdgcn_s_setprio(1); _Pragma("unroll") for (int m = 0; m < 4; ++m) _Pragma("unroll") for (int n = 0; n < 2; ++n) _Pragma("unroll") for (int k = 0; k < 2; ++k) \
;         acc[ai][bj][m][n] = __builtin_amdgcn_mfma_f32_16x16x32_bf16(Bt[n][k], At[m][k], acc[ai][bj][m][n], 0, 0, 0); __builtin_amdgcn_s_setprio(0); } while (0)
; #define PG8_WAIT_V(n) asm volatile("s_waitcnt vmcnt(" #n ")" ::: "memory")
; #define PG8_WAIT_L(n) asm volatile("s_waitcnt lgkmcnt(" #n ")" ::: "memory")
; #define PG8_BAR __builtin_amdgcn_s_barrier()
; #define PG8_SCHED __builtin_amdgcn_sched_barrier(0)
; template <class Epi, class Sched>
; __device__ __forceinline__ void gemm_phase(LAS unsigned char* lds, const Gemm g, const Sched& S, const Epi& E, int wid) {
;     ...
;             PG8_LDA(At, 1, 1); PG8_STAGE(PG8_SB(1, 0), b3); PG8_STAGE(PG8_SB(1, 1), b3 + hstep); PG8_STAGE(PG8_SA(1, 0), a3);
;             PG8_WAIT_V(8); PG8_WAIT_L(0); PG8_BAR; PG8_MMA(1, 0, At, B0); PG8_MMA(1, 1, At, B1); PG8_BAR; PG8_SCHED;
;         }
;         if (wr == 0) PG8_BAR;
	s_add_i32 s44, s68, s87
	v_lshl_add_u64 v[168:169], v[168:169], 0, s[92:93]
	s_mov_b32 m0, s44
	ds_read_b128 v[188:191], v163 offset:49152
	ds_read_b128 v[192:195], v163 offset:50176
	ds_read_b128 v[196:199], v163 offset:51200
	ds_read_b128 v[200:203], v163 offset:52224
	ds_read_b128 v[204:207], v163 offset:53248
	ds_read_b128 v[208:211], v163 offset:54272
	ds_read_b128 v[212:215], v163 offset:55296
	ds_read_b128 v[234:237], v163 offset:56320
	global_load_lds_dwordx4 v[168:169], off
	s_add_i32 m0, s44, 0x2000
	s_add_u32 s44, s60, 0x40080
	v_lshl_add_u64 v[168:169], v[216:217], 0, s[92:93]
	s_addc_u32 s45, s61, 0
	s_add_i32 s60, s69, s87
	global_load_lds_dwordx4 v[168:169], off
	v_lshl_add_u64 v[168:169], s[44:45], 0, v[132:133]
	s_mov_b32 m0, s60
	s_nop 0
	global_load_lds_dwordx4 v[168:169], off
	v_lshl_add_u64 v[168:169], s[44:45], 0, v[0:1]
	s_add_i32 m0, s60, 0x2000
	s_nop 0
	global_load_lds_dwordx4 v[168:169], off
	v_lshl_add_u64 v[168:169], v[238:239], 0, s[92:93]
	s_mov_b32 m0, s20
	s_nop 0
	global_load_lds_dwordx4 v[168:169], off
	v_lshl_add_u64 v[168:169], v[240:241], 0, s[92:93]
	s_mov_b32 m0, s21
	s_nop 0
	global_load_lds_dwordx4 v[168:169], off
	s_waitcnt vmcnt(8)
	s_waitcnt lgkmcnt(0)
	s_barrier
	s_waitcnt lgkmcnt(0)
	v_mfma_f32_16x16x32_bf16 v[64:67], v[140:143], v[188:191], v[64:67]
	v_mfma_f32_16x16x32_bf16 v[60:63], v[148:151], v[188:191], v[60:63]
	v_mfma_f32_16x16x32_bf16 v[48:51], v[140:143], v[196:199], v[48:51]
	v_mfma_f32_16x16x32_bf16 v[44:47], v[148:151], v[196:199], v[44:47]
	v_mfma_f32_16x16x32_bf16 v[32:35], v[140:143], v[204:207], v[32:35]
	v_mfma_f32_16x16x32_bf16 v[28:31], v[148:151], v[204:207], v[28:31]
	v_mfma_f32_16x16x32_bf16 v[16:19], v[140:143], v[212:215], v[16:19]
	v_mfma_f32_16x16x32_bf16 v[12:15], v[148:151], v[212:215], v[12:15]
	v_mfma_f32_16x16x32_bf16 v[64:67], v[144:147], v[192:195], v[64:67]
	v_mfma_f32_16x16x32_bf16 v[60:63], v[152:155], v[192:195], v[60:63]
	v_mfma_f32_16x16x32_bf16 v[48:51], v[144:147], v[200:203], v[48:51]
	v_mfma_f32_16x16x32_bf16 v[44:47], v[152:155], v[200:203], v[44:47]
	v_mfma_f32_16x16x32_bf16 v[32:35], v[144:147], v[208:211], v[32:35]
	v_mfma_f32_16x16x32_bf16 v[28:31], v[152:155], v[208:211], v[28:31]
	v_mfma_f32_16x16x32_bf16 v[16:19], v[144:147], v[234:237], v[16:19]
	v_mfma_f32_16x16x32_bf16 v[12:15], v[152:155], v[234:237], v[12:15]
	v_mfma_f32_16x16x32_bf16 v[56:59], v[156:159], v[188:191], v[56:59]
	v_mfma_f32_16x16x32_bf16 v[52:55], v[180:183], v[188:191], v[52:55]
	v_mfma_f32_16x16x32_bf16 v[40:43], v[156:159], v[196:199], v[40:43]
	v_mfma_f32_16x16x32_bf16 v[36:39], v[180:183], v[196:199], v[36:39]
	v_mfma_f32_16x16x32_bf16 v[24:27], v[156:159], v[204:207], v[24:27]
	v_mfma_f32_16x16x32_bf16 v[20:23], v[180:183], v[204:207], v[20:23]
	v_mfma_f32_16x16x32_bf16 v[8:11], v[156:159], v[212:215], v[8:11]
	v_mfma_f32_16x16x32_bf16 v[4:7], v[180:183], v[212:215], v[4:7]
	v_mfma_f32_16x16x32_bf16 v[56:59], v[164:167], v[192:195], v[56:59]
	v_mfma_f32_16x16x32_bf16 v[52:55], v[184:187], v[192:195], v[52:55]
	v_mfma_f32_16x16x32_bf16 v[40:43], v[164:167], v[200:203], v[40:43]
	v_mfma_f32_16x16x32_bf16 v[36:39], v[184:187], v[200:203], v[36:39]
	v_mfma_f32_16x16x32_bf16 v[24:27], v[164:167], v[208:211], v[24:27]
	v_mfma_f32_16x16x32_bf16 v[20:23], v[184:187], v[208:211], v[20:23]
	v_mfma_f32_16x16x32_bf16 v[8:11], v[164:167], v[234:237], v[8:11]
	v_mfma_f32_16x16x32_bf16 v[4:7], v[184:187], v[234:237], v[4:7]
	s_barrier
	s_add_i32 s67, s67, 2
	s_add_u32 s53, s53, 0x100
	s_addc_u32 s66, s66, 0
	s_cmp_gt_u32 s67, 13
	s_mov_b64 s[44:45], s[58:59]
	s_cbranch_scc0 .LBB0_1833
	s_setprio 0
	v_readlane_b32 s0, v252, 28
	v_readlane_b32 s1, v252, 29
	s_and_b64 vcc, exec, s[0:1]
	s_cbranch_vccz .LBB0_1836
	s_barrier

; #define PG8_STAGE(bufoff, gbase) do { _Pragma("unroll") for (int _i = 0; _i < 2; ++_i) \
;         __builtin_amdgcn_global_load_lds((const unsigned*)((const char*)(gbase) + voffA[_i]), (LAS unsigned*)(lds + (bufoff) + ldsw + _i * 8192), 16, 0, 0); } while (0)
; #define PG8_LDA(dst, b, h) do { _Pragma("unroll") for (int m = 0; m < 4; ++m) _Pragma("unroll") for (int k = 0; k < 2; ++k) dst[m][k] = *(const LAS bf16x8*)(lds + PG8_SA(b, h) + aoff + m * 2048 + k * 1024); } while (0)
; #define PG8_LDB(dst, b, h) do { _Pragma("unroll") for (int n = 0; n < 2; ++n) _Pragma("unroll") for (int k = 0; k < 2; ++k) dst[n][k] = *(const LAS bf16x8*)(lds + PG8_SB(b, h) + boff + n * 2048 + k * 1024); } while (0)
; #define PG8_MMA(ai, bj, At, Bt) do { __builtin_amdgcn_s_setprio(1); _Pragma("unroll") for (int m = 0; m < 4; ++m) _Pragma("unroll") for (int n = 0; n < 2; ++n) _Pragma("unroll") for (int k = 0; k < 2; ++k) \
;         acc[ai][bj][m][n] = __builtin_amdgcn_mfma_f32_16x16x32_bf16(Bt[n][k], At[m][k], acc[ai][bj][m][n], 0, 0, 0); __builtin_amdgcn_s_setprio(0); } while (0)
; #define PG8_WAIT_V(n) asm volatile("s_waitcnt vmcnt(" #n ")" ::: "memory")
; template <class Epi, class Sched>
; __device__ __forceinline__ void gemm_phase(LAS unsigned char* lds, const Gemm g, const Sched& S, const Epi& E, int wid) {
;     ...
; #pragma unroll
;     for (int a = 0; a < 2; ++a)
; #pragma unroll
;         for (int b = 0; b < 2; ++b)
; #pragma unroll
;             for (int m = 0; m < 4; ++m)
; #pragma unroll
;                 for (int n = 0; n < 2; ++n) acc[a][b][m][n] = (f32x4){0.f, 0.f, 0.f, 0.f};
;     ...
;         const bool has_next = S.next(ui + 1, nxt);
;         const char* nA = has_next ? (const char*)g.A + (size_t)nxt.pm * tstep : cA; const char* nB = has_next ? (const char*)g.Bt + (size_t)nxt.pn * tstep : cB;
;         for (int t = 0; t < nt; t += 2) {
;             const bool last = (t == nt - 2);
;             const char* a1 = cA + (size_t)(t + 1) * kstep;
;             const char* a2 = last ? nA : cA + (size_t)(t + 2) * kstep; const char* b2 = last ? nB : cB + (size_t)(t + 2) * kstep;
;             const char* a3 = a2 + kstep; const char* b3 = b2 + kstep;
;             PG8_LDB(B0, 0, 0); PG8_LDB(B1, 0, 1); PG8_SCHED; PG8_LDA(At, 0, 0); PG8_STAGE(PG8_SA(1, 1), a1 + hstep);
;             PG8_WAIT_V(8); PG8_WAIT_L(0); PG8_BAR; PG8_MMA(0, 0, At, B0); PG8_MMA(0, 1, At, B1); PG8_BAR; PG8_SCHED;
.LBB0_2022:
	s_ashr_i32 s51, s50, 31
	s_lshl_b64 s[0:1], s[50:51], 19
	s_add_u32 s52, s70, s0
	s_addc_u32 s53, s71, s1
	s_and_b64 s[0:1], s[40:41], exec
	s_cselect_b32 s0, s53, s57
	s_cselect_b32 s1, s52, s56
	s_ashr_i32 s49, s48, 31
	s_lshl_b64 s[54:55], s[48:49], 19
	s_add_u32 s54, s2, s54
	s_addc_u32 s55, s4, s55
	s_and_b64 s[60:61], s[40:41], exec
	s_cselect_b32 s29, s55, s59
	s_cselect_b32 s30, s54, s58
	s_add_u32 s56, s56, 0x40080
	s_addc_u32 s57, s57, 0
	s_add_u32 s49, s58, 0x100
	v_mov_b32_e32 v4, 0
	s_addc_u32 s51, s59, 0
	s_mov_b32 s62, -2
	v_mov_b32_e32 v5, v4
	v_mov_b32_e32 v6, v4
	v_mov_b32_e32 v7, v4
	v_mov_b32_e32 v24, v4
	v_mov_b32_e32 v25, v4
	v_mov_b32_e32 v26, v4
	v_mov_b32_e32 v27, v4
	v_mov_b32_e32 v8, v4
	v_mov_b32_e32 v9, v4
	v_mov_b32_e32 v10, v4
	v_mov_b32_e32 v11, v4
	v_mov_b32_e32 v32, v4
	v_mov_b32_e32 v33, v4
	v_mov_b32_e32 v34, v4
	v_mov_b32_e32 v35, v4
	v_mov_b32_e32 v12, v4
	v_mov_b32_e32 v13, v4
	v_mov_b32_e32 v14, v4
	v_mov_b32_e32 v15, v4
	v_mov_b32_e32 v40, v4
	v_mov_b32_e32 v41, v4
	v_mov_b32_e32 v42, v4
	v_mov_b32_e32 v43, v4
	v_mov_b32_e32 v16, v4
	v_mov_b32_e32 v17, v4
	v_mov_b32_e32 v18, v4
	v_mov_b32_e32 v19, v4
	v_mov_b32_e32 v48, v4
	v_mov_b32_e32 v49, v4
	v_mov_b32_e32 v50, v4
	v_mov_b32_e32 v51, v4
	v_mov_b32_e32 v60, v4
	v_mov_b32_e32 v61, v4
	v_mov_b32_e32 v62, v4
	v_mov_b32_e32 v63, v4
	v_mov_b32_e32 v88, v4
	v_mov_b32_e32 v89, v4
	v_mov_b32_e32 v90, v4
	v_mov_b32_e32 v91, v4
	v_mov_b32_e32 v68, v4
	v_mov_b32_e32 v69, v4
	v_mov_b32_e32 v70, v4
	v_mov_b32_e32 v71, v4
	v_mov_b32_e32 v96, v4
	v_mov_b32_e32 v97, v4
	v_mov_b32_e32 v98, v4
	v_mov_b32_e32 v99, v4
	v_mov_b32_e32 v76, v4
	v_mov_b32_e32 v77, v4
	v_mov_b32_e32 v78, v4
	v_mov_b32_e32 v79, v4
	v_mov_b32_e32 v104, v4
	v_mov_b32_e32 v105, v4
	v_mov_b32_e32 v106, v4
	v_mov_b32_e32 v107, v4
	v_mov_b32_e32 v80, v4
	v_mov_b32_e32 v81, v4
	v_mov_b32_e32 v82, v4
	v_mov_b32_e32 v83, v4
	v_mov_b32_e32 v112, v4
	v_mov_b32_e32 v113, v4
	v_mov_b32_e32 v114, v4
	v_mov_b32_e32 v115, v4
	v_mov_b32_e32 v20, v4
	v_mov_b32_e32 v21, v4
	v_mov_b32_e32 v22, v4
	v_mov_b32_e32 v23, v4
	v_mov_b32_e32 v52, v4
	v_mov_b32_e32 v53, v4
	v_mov_b32_e32 v54, v4
	v_mov_b32_e32 v55, v4
	v_mov_b32_e32 v28, v4
	v_mov_b32_e32 v29, v4
	v_mov_b32_e32 v30, v4
	v_mov_b32_e32 v31, v4
	v_mov_b32_e32 v56, v4
	v_mov_b32_e32 v57, v4
	v_mov_b32_e32 v58, v4
	v_mov_b32_e32 v59, v4
	v_mov_b32_e32 v36, v4
	v_mov_b32_e32 v37, v4
	v_mov_b32_e32 v38, v4
	v_mov_b32_e32 v39, v4
	v_mov_b32_e32 v64, v4
	v_mov_b32_e32 v65, v4
	v_mov_b32_e32 v66, v4
	v_mov_b32_e32 v67, v4
	v_mov_b32_e32 v44, v4
	v_mov_b32_e32 v45, v4
	v_mov_b32_e32 v46, v4
	v_mov_b32_e32 v47, v4
	v_mov_b32_e32 v72, v4
	v_mov_b32_e32 v73, v4
	v_mov_b32_e32 v74, v4
	v_mov_b32_e32 v75, v4
	v_mov_b32_e32 v84, v4
	v_mov_b32_e32 v85, v4
	v_mov_b32_e32 v86, v4
	v_mov_b32_e32 v87, v4
	v_mov_b32_e32 v116, v4
	v_mov_b32_e32 v117, v4
	v_mov_b32_e32 v118, v4
	v_mov_b32_e32 v119, v4
	v_mov_b32_e32 v92, v4
	v_mov_b32_e32 v93, v4
	v_mov_b32_e32 v94, v4
	v_mov_b32_e32 v95, v4
	v_mov_b32_e32 v120, v4
	v_mov_b32_e32 v121, v4
	v_mov_b32_e32 v122, v4
	v_mov_b32_e32 v123, v4
	v_mov_b32_e32 v100, v4
	v_mov_b32_e32 v101, v4
	v_mov_b32_e32 v102, v4
	v_mov_b32_e32 v103, v4
	v_mov_b32_e32 v124, v4
	v_mov_b32_e32 v125, v4
	v_mov_b32_e32 v126, v4
	v_mov_b32_e32 v127, v4
	v_mov_b32_e32 v108, v4
	v_mov_b32_e32 v109, v4
	v_mov_b32_e32 v110, v4
	v_mov_b32_e32 v111, v4
	v_mov_b32_e32 v128, v4
	v_mov_b32_e32 v129, v4
	v_mov_b32_e32 v130, v4
	v_mov_b32_e32 v131, v4
	v_readlane_b32 s100, v251, 60
	s_cmp_lt_u32 s100, 4
	s_cbranch_scc1 .Lmy_prio_3
	s_setprio 1
.Lmy_prio_3:
.LBB0_2023:
	s_add_u32 s58, s56, 0xfffc0080
	s_addc_u32 s59, s57, -1
	s_add_i32 s63, 0, 0x10000
	s_cmp_eq_u32 s62, 12
	s_cselect_b32 s61, s0, s59
	s_cselect_b32 s60, s1, s58
	v_add_u32_e32 v148, s63, v151
	s_cselect_b32 s59, s29, s51
	s_cselect_b32 s58, s30, s49
	s_add_i32 s68, 0, 0x14000
	ds_read_b128 v[132:135], v148
	ds_read_b128 v[136:139], v148 offset:1024
	ds_read_b128 v[160:163], v148 offset:2048
	ds_read_b128 v[164:167], v148 offset:3072
	v_add_u32_e32 v148, s68, v151
	ds_read_b128 v[180:183], v148
	ds_read_b128 v[184:187], v148 offset:1024
	ds_read_b128 v[188:191], v148 offset:2048
	ds_read_b128 v[192:195], v148 offset:3072
	v_lshl_add_u64 v[148:149], s[56:57], 0, v[144:145]
	s_add_i32 m0, s85, 0xc000
	ds_read_b128 v[196:199], v159
	ds_read_b128 v[200:203], v159 offset:1024
	ds_read_b128 v[204:207], v159 offset:2048
	ds_read_b128 v[208:211], v159 offset:3072
	ds_read_b128 v[212:215], v159 offset:4096
	ds_read_b128 v[234:237], v159 offset:5120
	ds_read_b128 v[238:241], v159 offset:6144
	ds_read_b128 v[242:245], v159 offset:7168
	global_load_lds_dwordx4 v[148:149], off
	v_lshl_add_u64 v[148:149], s[56:57], 0, v[146:147]
	s_add_i32 m0, s85, 0xe000
	s_nop 0
	global_load_lds_dwordx4 v[148:149], off
	s_waitcnt vmcnt(8)
	s_waitcnt lgkmcnt(0)
	s_barrier
; #define PG8_STAGE(bufoff, gbase) do { _Pragma("unroll") for (int _i = 0; _i < 2; ++_i) \
;         __builtin_amdgcn_global_load_lds((const unsigned*)((const char*)(gbase) + voffA[_i]), (LAS unsigned*)(lds + (bufoff) + ldsw + _i * 8192), 16, 0, 0); } while (0)
; #define PG8_LDA(dst, b, h) do { _Pragma("unroll") for (int m = 0; m < 4; ++m) _Pragma("unroll") for (int k = 0; k < 2; ++k) dst[m][k] = *(const LAS bf16x8*)(lds + PG8_SA(b, h) + aoff + m * 2048 + k * 1024); } while (0)
; #define PG8_MMA(ai, bj, At, Bt) do { __builtin_amdgcn_s_setprio(1); _Pragma("unroll") for (int m = 0; m < 4; ++m) _Pragma("unroll") for (int n = 0; n < 2; ++n) _Pragma("unroll") for (int k = 0; k < 2; ++k) \
;         acc[ai][bj][m][n] = __builtin_amdgcn_mfma_f32_16x16x32_bf16(Bt[n][k], At[m][k], acc[ai][bj][m][n], 0, 0, 0); __builtin_amdgcn_s_setprio(0); } while (0)
; #define PG8_WAIT_V(n) asm volatile("s_waitcnt vmcnt(" #n ")" ::: "memory")
; #define PG8_WAIT_L(n) asm volatile("s_waitcnt lgkmcnt(" #n ")" ::: "memory")
; #define PG8_BAR __builtin_amdgcn_s_barrier()
; #define PG8_SCHED __builtin_amdgcn_sched_barrier(0)
; template <class Epi, class Sched>
; __device__ __forceinline__ void gemm_phase(LAS unsigned char* lds, const Gemm g, const Sched& S, const Epi& E, int wid) {
;     ...
;             PG8_WAIT_V(8); PG8_WAIT_L(0); PG8_BAR; PG8_MMA(0, 0, At, B0); PG8_MMA(0, 1, At, B1); PG8_BAR; PG8_SCHED;
;             PG8_LDA(At, 0, 1); PG8_STAGE(PG8_SB(0, 0), b2); PG8_STAGE(PG8_SB(0, 1), b2 + hstep); PG8_STAGE(PG8_SA(0, 0), a2);
;             PG8_WAIT_V(8); PG8_WAIT_L(0); PG8_BAR; PG8_MMA(1, 0, At, B0); PG8_MMA(1, 1, At, B1); PG8_BAR; PG8_SCHED;
	s_waitcnt lgkmcnt(0)
	v_mfma_f32_16x16x32_bf16 v[128:131], v[132:135], v[196:199], v[128:131]
	v_mfma_f32_16x16x32_bf16 v[108:111], v[160:163], v[196:199], v[108:111]
	v_mfma_f32_16x16x32_bf16 v[124:127], v[132:135], v[204:207], v[124:127]
	v_mfma_f32_16x16x32_bf16 v[100:103], v[160:163], v[204:207], v[100:103]
	v_mfma_f32_16x16x32_bf16 v[120:123], v[132:135], v[212:215], v[120:123]
	v_mfma_f32_16x16x32_bf16 v[92:95], v[160:163], v[212:215], v[92:95]
	v_mfma_f32_16x16x32_bf16 v[116:119], v[132:135], v[238:241], v[116:119]
	v_mfma_f32_16x16x32_bf16 v[84:87], v[160:163], v[238:241], v[84:87]
	v_mfma_f32_16x16x32_bf16 v[128:131], v[136:139], v[200:203], v[128:131]
	v_mfma_f32_16x16x32_bf16 v[108:111], v[164:167], v[200:203], v[108:111]
	v_mfma_f32_16x16x32_bf16 v[124:127], v[136:139], v[208:211], v[124:127]
	v_mfma_f32_16x16x32_bf16 v[100:103], v[164:167], v[208:211], v[100:103]
	v_mfma_f32_16x16x32_bf16 v[120:123], v[136:139], v[234:237], v[120:123]
	v_mfma_f32_16x16x32_bf16 v[92:95], v[164:167], v[234:237], v[92:95]
	v_mfma_f32_16x16x32_bf16 v[116:119], v[136:139], v[242:245], v[116:119]
	v_mfma_f32_16x16x32_bf16 v[84:87], v[164:167], v[242:245], v[84:87]
	v_mfma_f32_16x16x32_bf16 v[72:75], v[180:183], v[196:199], v[72:75]
	v_mfma_f32_16x16x32_bf16 v[44:47], v[188:191], v[196:199], v[44:47]
	v_mfma_f32_16x16x32_bf16 v[64:67], v[180:183], v[204:207], v[64:67]
	v_mfma_f32_16x16x32_bf16 v[36:39], v[188:191], v[204:207], v[36:39]
	v_mfma_f32_16x16x32_bf16 v[56:59], v[180:183], v[212:215], v[56:59]
	v_mfma_f32_16x16x32_bf16 v[28:31], v[188:191], v[212:215], v[28:31]
	v_mfma_f32_16x16x32_bf16 v[52:55], v[180:183], v[238:241], v[52:55]
	v_mfma_f32_16x16x32_bf16 v[20:23], v[188:191], v[238:241], v[20:23]
	v_mfma_f32_16x16x32_bf16 v[72:75], v[184:187], v[200:203], v[72:75]
	v_mfma_f32_16x16x32_bf16 v[44:47], v[192:195], v[200:203], v[44:47]
	v_mfma_f32_16x16x32_bf16 v[64:67], v[184:187], v[208:211], v[64:67]
	v_mfma_f32_16x16x32_bf16 v[36:39], v[192:195], v[208:211], v[36:39]
	v_mfma_f32_16x16x32_bf16 v[56:59], v[184:187], v[234:237], v[56:59]
	v_mfma_f32_16x16x32_bf16 v[28:31], v[192:195], v[234:237], v[28:31]
	v_mfma_f32_16x16x32_bf16 v[52:55], v[184:187], v[242:245], v[52:55]
	v_mfma_f32_16x16x32_bf16 v[20:23], v[192:195], v[242:245], v[20:23]
	s_barrier
	s_add_i32 s63, s63, s87
	v_lshl_add_u64 v[148:149], s[58:59], 0, v[140:141]
	s_mov_b32 m0, s63
	ds_read_b128 v[196:199], v159 offset:16384
	ds_read_b128 v[200:203], v159 offset:17408
	ds_read_b128 v[204:207], v159 offset:18432
	ds_read_b128 v[208:211], v159 offset:19456
	ds_read_b128 v[212:215], v159 offset:20480
	ds_read_b128 v[234:237], v159 offset:21504
	ds_read_b128 v[238:241], v159 offset:22528
	ds_read_b128 v[242:245], v159 offset:23552
	global_load_lds_dwordx4 v[148:149], off
	s_add_i32 m0, s63, 0x2000
	s_add_u32 s66, s58, 0x40000
	v_lshl_add_u64 v[152:153], s[58:59], 0, v[0:1]
	s_addc_u32 s67, s59, 0
	s_add_i32 s63, s68, s87
	global_load_lds_dwordx4 v[152:153], off
	v_lshl_add_u64 v[156:157], s[66:67], 0, v[140:141]
	s_mov_b32 m0, s63
	v_lshl_add_u64 v[168:169], s[60:61], 0, v[0:1]
	global_load_lds_dwordx4 v[156:157], off
	v_lshl_add_u64 v[156:157], s[66:67], 0, v[0:1]
	s_add_i32 m0, s63, 0x2000
	s_nop 0
	global_load_lds_dwordx4 v[156:157], off
	v_lshl_add_u64 v[156:157], s[60:61], 0, v[140:141]
	s_mov_b32 m0, s85
	s_nop 0
	global_load_lds_dwordx4 v[156:157], off
	s_mov_b32 m0, s8
	s_nop 0
	global_load_lds_dwordx4 v[168:169], off
	s_waitcnt vmcnt(8)
	s_waitcnt lgkmcnt(0)
	s_barrier
	s_waitcnt lgkmcnt(0)
	v_mfma_f32_16x16x32_bf16 v[112:115], v[132:135], v[196:199], v[112:115]
	v_mfma_f32_16x16x32_bf16 v[80:83], v[160:163], v[196:199], v[80:83]
	v_mfma_f32_16x16x32_bf16 v[104:107], v[132:135], v[204:207], v[104:107]
	v_mfma_f32_16x16x32_bf16 v[76:79], v[160:163], v[204:207], v[76:79]
	v_mfma_f32_16x16x32_bf16 v[96:99], v[132:135], v[212:215], v[96:99]
	v_mfma_f32_16x16x32_bf16 v[68:71], v[160:163], v[212:215], v[68:71]
	v_mfma_f32_16x16x32_bf16 v[88:91], v[132:135], v[238:241], v[88:91]
	v_mfma_f32_16x16x32_bf16 v[60:63], v[160:163], v[238:241], v[60:63]
	v_mfma_f32_16x16x32_bf16 v[112:115], v[136:139], v[200:203], v[112:115]
	v_mfma_f32_16x16x32_bf16 v[80:83], v[164:167], v[200:203], v[80:83]
	v_mfma_f32_16x16x32_bf16 v[104:107], v[136:139], v[208:211], v[104:107]
	v_mfma_f32_16x16x32_bf16 v[76:79], v[164:167], v[208:211], v[76:79]
	v_mfma_f32_16x16x32_bf16 v[96:99], v[136:139], v[234:237], v[96:99]
	v_mfma_f32_16x16x32_bf16 v[68:71], v[164:167], v[234:237], v[68:71]
	v_mfma_f32_16x16x32_bf16 v[88:91], v[136:139], v[242:245], v[88:91]
	v_mfma_f32_16x16x32_bf16 v[60:63], v[164:167], v[242:245], v[60:63]
	v_mfma_f32_16x16x32_bf16 v[48:51], v[180:183], v[196:199], v[48:51]
	v_mfma_f32_16x16x32_bf16 v[16:19], v[188:191], v[196:199], v[16:19]
	v_mfma_f32_16x16x32_bf16 v[40:43], v[180:183], v[204:207], v[40:43]
	v_mfma_f32_16x16x32_bf16 v[12:15], v[188:191], v[204:207], v[12:15]
	v_mfma_f32_16x16x32_bf16 v[32:35], v[180:183], v[212:215], v[32:35]
	v_mfma_f32_16x16x32_bf16 v[8:11], v[188:191], v[212:215], v[8:11]
	v_mfma_f32_16x16x32_bf16 v[24:27], v[180:183], v[238:241], v[24:27]
	v_mfma_f32_16x16x32_bf16 v[4:7], v[188:191], v[238:241], v[4:7]
	v_mfma_f32_16x16x32_bf16 v[48:51], v[184:187], v[200:203], v[48:51]
	v_mfma_f32_16x16x32_bf16 v[16:19], v[192:195], v[200:203], v[16:19]
	v_mfma_f32_16x16x32_bf16 v[40:43], v[184:187], v[208:211], v[40:43]
	v_mfma_f32_16x16x32_bf16 v[12:15], v[192:195], v[208:211], v[12:15]
	v_mfma_f32_16x16x32_bf16 v[32:35], v[184:187], v[234:237], v[32:35]
	v_mfma_f32_16x16x32_bf16 v[8:11], v[192:195], v[234:237], v[8:11]
	v_mfma_f32_16x16x32_bf16 v[24:27], v[184:187], v[242:245], v[24:27]
	v_mfma_f32_16x16x32_bf16 v[4:7], v[192:195], v[242:245], v[4:7]
	s_barrier
; #define PG8_STAGE(bufoff, gbase) do { _Pragma("unroll") for (int _i = 0; _i < 2; ++_i) \
;         __builtin_amdgcn_global_load_lds((const unsigned*)((const char*)(gbase) + voffA[_i]), (LAS unsigned*)(lds + (bufoff) + ldsw + _i * 8192), 16, 0, 0); } while (0)
; #define PG8_LDA(dst, b, h) do { _Pragma("unroll") for (int m = 0; m < 4; ++m) _Pragma("unroll") for (int k = 0; k < 2; ++k) dst[m][k] = *(const LAS bf16x8*)(lds + PG8_SA(b, h) + aoff + m * 2048 + k * 1024); } while (0)
; #define PG8_LDB(dst, b, h) do { _Pragma("unroll") for (int n = 0; n < 2; ++n) _Pragma("unroll") for (int k = 0; k < 2; ++k) dst[n][k] = *(const LAS bf16x8*)(lds + PG8_SB(b, h) + boff + n * 2048 + k * 1024); } while (0)
; #define PG8_MMA(ai, bj, At, Bt) do { __builtin_amdgcn_s_setprio(1); _Pragma("unroll") for (int m = 0; m < 4; ++m) _Pragma("unroll") for (int n = 0; n < 2; ++n) _Pragma("unroll") for (int k = 0; k < 2; ++k) \
;         acc[ai][bj][m][n] = __builtin_amdgcn_mfma_f32_16x16x32_bf16(Bt[n][k], At[m][k], acc[ai][bj][m][n], 0, 0, 0); __builtin_amdgcn_s_setprio(0); } while (0)
; #define PG8_WAIT_V(n) asm volatile("s_waitcnt vmcnt(" #n ")" ::: "memory")
; #define PG8_WAIT_L(n) asm volatile("s_waitcnt lgkmcnt(" #n ")" ::: "memory")
; #define PG8_BAR __builtin_amdgcn_s_barrier()
; #define PG8_SCHED __builtin_amdgcn_sched_barrier(0)
; template <class Epi, class Sched>
; __device__ __forceinline__ void gemm_phase(LAS unsigned char* lds, const Gemm g, const Sched& S, const Epi& E, int wid) {
;     ...
;             PG8_LDB(B0, 1, 0); PG8_LDB(B1, 1, 1); PG8_SCHED; PG8_LDA(At, 1, 0); PG8_STAGE(PG8_SA(0, 1), a2 + hstep);
;             PG8_WAIT_V(8); PG8_WAIT_L(0); PG8_BAR; PG8_MMA(0, 0, At, B0); PG8_MMA(0, 1, At, B1); PG8_BAR; PG8_SCHED;
	s_add_i32 s63, 0, 0x18000
	v_add_u32_e32 v150, s63, v151
	s_add_i32 s66, 0, 0x1c000
	ds_read_b128 v[132:135], v150
	ds_read_b128 v[136:139], v150 offset:1024
	ds_read_b128 v[160:163], v150 offset:2048
	ds_read_b128 v[164:167], v150 offset:3072
	v_add_u32_e32 v150, s66, v151
	ds_read_b128 v[180:183], v150
	ds_read_b128 v[184:187], v150 offset:1024
	ds_read_b128 v[188:191], v150 offset:2048
	ds_read_b128 v[192:195], v150 offset:3072
	s_add_u32 s60, s60, 0x40000
	s_addc_u32 s61, s61, 0
	s_mov_b32 m0, s9
	v_lshl_add_u64 v[216:217], s[60:61], 0, v[140:141]
	ds_read_b128 v[196:199], v159 offset:32768
	ds_read_b128 v[200:203], v159 offset:33792
	ds_read_b128 v[204:207], v159 offset:34816
	ds_read_b128 v[208:211], v159 offset:35840
	ds_read_b128 v[212:215], v159 offset:36864
	ds_read_b128 v[234:237], v159 offset:37888
	ds_read_b128 v[238:241], v159 offset:38912
	ds_read_b128 v[242:245], v159 offset:39936
	global_load_lds_dwordx4 v[216:217], off
	v_lshl_add_u64 v[216:217], s[60:61], 0, v[0:1]
	s_mov_b32 m0, s10
	s_nop 0
	global_load_lds_dwordx4 v[216:217], off
	s_waitcnt vmcnt(8)
	s_waitcnt lgkmcnt(0)
	s_barrier
	s_waitcnt lgkmcnt(0)
	v_mfma_f32_16x16x32_bf16 v[128:131], v[132:135], v[196:199], v[128:131]
	v_mfma_f32_16x16x32_bf16 v[108:111], v[160:163], v[196:199], v[108:111]
	v_mfma_f32_16x16x32_bf16 v[124:127], v[132:135], v[204:207], v[124:127]
	v_mfma_f32_16x16x32_bf16 v[100:103], v[160:163], v[204:207], v[100:103]
	v_mfma_f32_16x16x32_bf16 v[120:123], v[132:135], v[212:215], v[120:123]
	v_mfma_f32_16x16x32_bf16 v[92:95], v[160:163], v[212:215], v[92:95]
	v_mfma_f32_16x16x32_bf16 v[116:119], v[132:135], v[238:241], v[116:119]
	v_mfma_f32_16x16x32_bf16 v[84:87], v[160:163], v[238:241], v[84:87]
	v_mfma_f32_16x16x32_bf16 v[128:131], v[136:139], v[200:203], v[128:131]
	v_mfma_f32_16x16x32_bf16 v[108:111], v[164:167], v[200:203], v[108:111]
	v_mfma_f32_16x16x32_bf16 v[124:127], v[136:139], v[208:211], v[124:127]
	v_mfma_f32_16x16x32_bf16 v[100:103], v[164:167], v[208:211], v[100:103]
	v_mfma_f32_16x16x32_bf16 v[120:123], v[136:139], v[234:237], v[120:123]
	v_mfma_f32_16x16x32_bf16 v[92:95], v[164:167], v[234:237], v[92:95]
	v_mfma_f32_16x16x32_bf16 v[116:119], v[136:139], v[242:245], v[116:119]
	v_mfma_f32_16x16x32_bf16 v[84:87], v[164:167], v[242:245], v[84:87]
	v_mfma_f32_16x16x32_bf16 v[72:75], v[180:183], v[196:199], v[72:75]
	v_mfma_f32_16x16x32_bf16 v[44:47], v[188:191], v[196:199], v[44:47]
	v_mfma_f32_16x16x32_bf16 v[64:67], v[180:183], v[204:207], v[64:67]
	v_mfma_f32_16x16x32_bf16 v[36:39], v[188:191], v[204:207], v[36:39]
	v_mfma_f32_16x16x32_bf16 v[56:59], v[180:183], v[212:215], v[56:59]
	v_mfma_f32_16x16x32_bf16 v[28:31], v[188:191], v[212:215], v[28:31]
	v_mfma_f32_16x16x32_bf16 v[52:55], v[180:183], v[238:241], v[52:55]
	v_mfma_f32_16x16x32_bf16 v[20:23], v[188:191], v[238:241], v[20:23]
	v_mfma_f32_16x16x32_bf16 v[72:75], v[184:187], v[200:203], v[72:75]
	v_mfma_f32_16x16x32_bf16 v[44:47], v[192:195], v[200:203], v[44:47]
	v_mfma_f32_16x16x32_bf16 v[64:67], v[184:187], v[208:211], v[64:67]
	v_mfma_f32_16x16x32_bf16 v[36:39], v[192:195], v[208:211], v[36:39]
	v_mfma_f32_16x16x32_bf16 v[56:59], v[184:187], v[234:237], v[56:59]
	v_mfma_f32_16x16x32_bf16 v[28:31], v[192:195], v[234:237], v[28:31]
	v_mfma_f32_16x16x32_bf16 v[52:55], v[184:187], v[242:245], v[52:55]
	v_mfma_f32_16x16x32_bf16 v[20:23], v[192:195], v[242:245], v[20:23]
	s_barrier
; #define PG8_STAGE(bufoff, gbase) do { _Pragma("unroll") for (int _i = 0; _i < 2; ++_i) \
;         __builtin_amdgcn_global_load_lds((const unsigned*)((const char*)(gbase) + voffA[_i]), (LAS unsigned*)(lds + (bufoff) + ldsw + _i * 8192), 16, 0, 0); } while (0)
; #define PG8_LDA(dst, b, h) do { _Pragma("unroll") for (int m = 0; m < 4; ++m) _Pragma("unroll") for (int k = 0; k < 2; ++k) dst[m][k] = *(const LAS bf16x8*)(lds + PG8_SA(b, h) + aoff + m * 2048 + k * 1024); } while (0)
; #define PG8_MMA(ai, bj, At, Bt) do { __builtin_amdgcn_s_setprio(1); _Pragma("unroll") for (int m = 0; m < 4; ++m) _Pragma("unroll") for (int n = 0; n < 2; ++n) _Pragma("unroll") for (int k = 0; k < 2; ++k) \
;         acc[ai][bj][m][n] = __builtin_amdgcn_mfma_f32_16x16x32_bf16(Bt[n][k], At[m][k], acc[ai][bj][m][n], 0, 0, 0); __builtin_amdgcn_s_setprio(0); } while (0)
; #define PG8_WAIT_V(n) asm volatile("s_waitcnt vmcnt(" #n ")" ::: "memory")
; #define PG8_WAIT_L(n) asm volatile("s_waitcnt lgkmcnt(" #n ")" ::: "memory")
; #define PG8_BAR __builtin_amdgcn_s_barrier()
; #define PG8_SCHED __builtin_amdgcn_sched_barrier(0)
; template <class Epi, class Sched>
; __device__ __forceinline__ void gemm_phase(LAS unsigned char* lds, const Gemm g, const Sched& S, const Epi& E, int wid) {
;     ...
;             PG8_LDA(At, 1, 1); PG8_STAGE(PG8_SB(1, 0), b3); PG8_STAGE(PG8_SB(1, 1), b3 + hstep); PG8_STAGE(PG8_SA(1, 0), a3);
;             PG8_WAIT_V(8); PG8_WAIT_L(0); PG8_BAR; PG8_MMA(1, 0, At, B0); PG8_MMA(1, 1, At, B1); PG8_BAR; PG8_SCHED;
;         }
;         if (wr == 0) PG8_BAR;
	s_add_i32 s60, s63, s87
	v_lshl_add_u64 v[148:149], v[148:149], 0, s[92:93]
	s_mov_b32 m0, s60
	ds_read_b128 v[196:199], v159 offset:49152
	ds_read_b128 v[200:203], v159 offset:50176
	ds_read_b128 v[204:207], v159 offset:51200
	ds_read_b128 v[208:211], v159 offset:52224
	ds_read_b128 v[212:215], v159 offset:53248
	ds_read_b128 v[234:237], v159 offset:54272
	ds_read_b128 v[238:241], v159 offset:55296
	ds_read_b128 v[242:245], v159 offset:56320
	global_load_lds_dwordx4 v[148:149], off
	s_add_i32 m0, s60, 0x2000
	s_add_u32 s58, s58, 0x40080
	v_lshl_add_u64 v[148:149], v[152:153], 0, s[92:93]
	s_addc_u32 s59, s59, 0
	s_add_i32 s60, s66, s87
	global_load_lds_dwordx4 v[148:149], off
	v_lshl_add_u64 v[148:149], s[58:59], 0, v[140:141]
	s_mov_b32 m0, s60
	s_nop 0
	global_load_lds_dwordx4 v[148:149], off
	v_lshl_add_u64 v[148:149], s[58:59], 0, v[0:1]
	s_add_i32 m0, s60, 0x2000
	s_nop 0
	global_load_lds_dwordx4 v[148:149], off
	v_lshl_add_u64 v[148:149], v[156:157], 0, s[92:93]
	s_mov_b32 m0, s11
	s_nop 0
	global_load_lds_dwordx4 v[148:149], off
	v_lshl_add_u64 v[148:149], v[168:169], 0, s[92:93]
	s_mov_b32 m0, s20
	s_nop 0
	global_load_lds_dwordx4 v[148:149], off
	s_waitcnt vmcnt(8)
	s_waitcnt lgkmcnt(0)
	s_barrier
	s_waitcnt lgkmcnt(0)
	v_mfma_f32_16x16x32_bf16 v[112:115], v[132:135], v[196:199], v[112:115]
	v_mfma_f32_16x16x32_bf16 v[80:83], v[160:163], v[196:199], v[80:83]
	v_mfma_f32_16x16x32_bf16 v[104:107], v[132:135], v[204:207], v[104:107]
	v_mfma_f32_16x16x32_bf16 v[76:79], v[160:163], v[204:207], v[76:79]
	v_mfma_f32_16x16x32_bf16 v[96:99], v[132:135], v[212:215], v[96:99]
	v_mfma_f32_16x16x32_bf16 v[68:71], v[160:163], v[212:215], v[68:71]
	v_mfma_f32_16x16x32_bf16 v[88:91], v[132:135], v[238:241], v[88:91]
	v_mfma_f32_16x16x32_bf16 v[60:63], v[160:163], v[238:241], v[60:63]
	v_mfma_f32_16x16x32_bf16 v[112:115], v[136:139], v[200:203], v[112:115]
	v_mfma_f32_16x16x32_bf16 v[80:83], v[164:167], v[200:203], v[80:83]
	v_mfma_f32_16x16x32_bf16 v[104:107], v[136:139], v[208:211], v[104:107]
	v_mfma_f32_16x16x32_bf16 v[76:79], v[164:167], v[208:211], v[76:79]
	v_mfma_f32_16x16x32_bf16 v[96:99], v[136:139], v[234:237], v[96:99]
	v_mfma_f32_16x16x32_bf16 v[68:71], v[164:167], v[234:237], v[68:71]
	v_mfma_f32_16x16x32_bf16 v[88:91], v[136:139], v[242:245], v[88:91]
	v_mfma_f32_16x16x32_bf16 v[60:63], v[164:167], v[242:245], v[60:63]
	v_mfma_f32_16x16x32_bf16 v[48:51], v[180:183], v[196:199], v[48:51]
	v_mfma_f32_16x16x32_bf16 v[16:19], v[188:191], v[196:199], v[16:19]
	v_mfma_f32_16x16x32_bf16 v[40:43], v[180:183], v[204:207], v[40:43]
	v_mfma_f32_16x16x32_bf16 v[12:15], v[188:191], v[204:207], v[12:15]
	v_mfma_f32_16x16x32_bf16 v[32:35], v[180:183], v[212:215], v[32:35]
	v_mfma_f32_16x16x32_bf16 v[8:11], v[188:191], v[212:215], v[8:11]
	v_mfma_f32_16x16x32_bf16 v[24:27], v[180:183], v[238:241], v[24:27]
	v_mfma_f32_16x16x32_bf16 v[4:7], v[188:191], v[238:241], v[4:7]
	v_mfma_f32_16x16x32_bf16 v[48:51], v[184:187], v[200:203], v[48:51]
	v_mfma_f32_16x16x32_bf16 v[16:19], v[192:195], v[200:203], v[16:19]
	v_mfma_f32_16x16x32_bf16 v[40:43], v[184:187], v[208:211], v[40:43]
	v_mfma_f32_16x16x32_bf16 v[12:15], v[192:195], v[208:211], v[12:15]
	v_mfma_f32_16x16x32_bf16 v[32:35], v[184:187], v[234:237], v[32:35]
	v_mfma_f32_16x16x32_bf16 v[8:11], v[192:195], v[234:237], v[8:11]
	v_mfma_f32_16x16x32_bf16 v[24:27], v[184:187], v[242:245], v[24:27]
	v_mfma_f32_16x16x32_bf16 v[4:7], v[192:195], v[242:245], v[4:7]
	s_barrier
	s_add_i32 s62, s62, 2
	s_add_u32 s56, s56, 0x100
	s_addc_u32 s57, s57, 0
	s_add_u32 s49, s49, 0x100
	s_addc_u32 s51, s51, 0
	s_cmp_gt_u32 s62, 13
	s_cbranch_scc0 .LBB0_2023
	s_setprio 0
	v_readlane_b32 s0, v252, 28
	v_readlane_b32 s1, v252, 29
	s_and_b64 vcc, exec, s[0:1]
	s_cbranch_vccz .LBB0_2026
	s_barrier

; #define PG8_STAGE(bufoff, gbase) do { _Pragma("unroll") for (int _i = 0; _i < 2; ++_i) \
;         __builtin_amdgcn_global_load_lds((const unsigned*)((const char*)(gbase) + voffA[_i]), (LAS unsigned*)(lds + (bufoff) + ldsw + _i * 8192), 16, 0, 0); } while (0)
; #define PG8_LDA(dst, b, h) do { _Pragma("unroll") for (int m = 0; m < 4; ++m) _Pragma("unroll") for (int k = 0; k < 2; ++k) dst[m][k] = *(const LAS bf16x8*)(lds + PG8_SA(b, h) + aoff + m * 2048 + k * 1024); } while (0)
; #define PG8_LDB(dst, b, h) do { _Pragma("unroll") for (int n = 0; n < 2; ++n) _Pragma("unroll") for (int k = 0; k < 2; ++k) dst[n][k] = *(const LAS bf16x8*)(lds + PG8_SB(b, h) + boff + n * 2048 + k * 1024); } while (0)
; #define PG8_MMA(ai, bj, At, Bt) do { __builtin_amdgcn_s_setprio(1); _Pragma("unroll") for (int m = 0; m < 4; ++m) _Pragma("unroll") for (int n = 0; n < 2; ++n) _Pragma("unroll") for (int k = 0; k < 2; ++k) \
;         acc[ai][bj][m][n] = __builtin_amdgcn_mfma_f32_16x16x32_bf16(Bt[n][k], At[m][k], acc[ai][bj][m][n], 0, 0, 0); __builtin_amdgcn_s_setprio(0); } while (0)
; #define PG8_WAIT_V(n) asm volatile("s_waitcnt vmcnt(" #n ")" ::: "memory")
; template <class Epi, class Sched>
; __device__ __forceinline__ void gemm_phase(LAS unsigned char* lds, const Gemm g, const Sched& S, const Epi& E, int wid) {
;     ...
; #pragma unroll
;     for (int a = 0; a < 2; ++a)
; #pragma unroll
;         for (int b = 0; b < 2; ++b)
; #pragma unroll
;             for (int m = 0; m < 4; ++m)
; #pragma unroll
;                 for (int n = 0; n < 2; ++n) acc[a][b][m][n] = (f32x4){0.f, 0.f, 0.f, 0.f};
;     ...
;         const bool has_next = S.next(ui + 1, nxt);
;         const char* nA = has_next ? (const char*)g.A + (size_t)nxt.pm * tstep : cA; const char* nB = has_next ? (const char*)g.Bt + (size_t)nxt.pn * tstep : cB;
;         for (int t = 0; t < nt; t += 2) {
;             const bool last = (t == nt - 2);
;             const char* a1 = cA + (size_t)(t + 1) * kstep;
;             const char* a2 = last ? nA : cA + (size_t)(t + 2) * kstep; const char* b2 = last ? nB : cB + (size_t)(t + 2) * kstep;
;             const char* a3 = a2 + kstep; const char* b3 = b2 + kstep;
;             PG8_LDB(B0, 0, 0); PG8_LDB(B1, 0, 1); PG8_SCHED; PG8_LDA(At, 0, 0); PG8_STAGE(PG8_SA(1, 1), a1 + hstep);
;             PG8_WAIT_V(8); PG8_WAIT_L(0); PG8_BAR; PG8_MMA(0, 0, At, B0); PG8_MMA(0, 1, At, B1); PG8_BAR; PG8_SCHED;
.LBB0_2199:
	s_ashr_i32 s55, s54, 31
	s_lshl_b64 s[0:1], s[54:55], 19
	v_readlane_b32 s24, v254, 32
	v_readlane_b32 s25, v254, 33
	s_add_u32 s56, s24, s0
	s_addc_u32 s57, s25, s1
	s_and_b64 s[0:1], s[42:43], exec
	s_cselect_b32 s0, s57, s61
	s_cselect_b32 s1, s56, s60
	s_ashr_i32 s53, s52, 31
	s_lshl_b64 s[58:59], s[52:53], 19
	s_add_u32 s58, s2, s58
	s_addc_u32 s59, s8, s59
	s_and_b64 s[66:67], s[42:43], exec
	s_cselect_b32 s29, s59, s63
	s_cselect_b32 s30, s58, s62
	s_add_u32 s53, s62, 0x100
	v_mov_b32_e32 v4, 0
	s_addc_u32 s55, s63, 0
	s_mov_b32 s66, -2
	v_mov_b32_e32 v5, v4
	s_waitcnt lgkmcnt(0)
	v_mov_b32_e32 v6, v4
	v_mov_b32_e32 v7, v4
	v_mov_b32_e32 v8, v4
	v_mov_b32_e32 v9, v4
	v_mov_b32_e32 v10, v4
	v_mov_b32_e32 v11, v4
	v_mov_b32_e32 v20, v4
	v_mov_b32_e32 v21, v4
	v_mov_b32_e32 v22, v4
	v_mov_b32_e32 v23, v4
	v_mov_b32_e32 v24, v4
	v_mov_b32_e32 v25, v4
	v_mov_b32_e32 v26, v4
	v_mov_b32_e32 v27, v4
	v_mov_b32_e32 v36, v4
	v_mov_b32_e32 v37, v4
	v_mov_b32_e32 v38, v4
	v_mov_b32_e32 v39, v4
	v_mov_b32_e32 v40, v4
	v_mov_b32_e32 v41, v4
	v_mov_b32_e32 v42, v4
	v_mov_b32_e32 v43, v4
	v_mov_b32_e32 v52, v4
	v_mov_b32_e32 v53, v4
	v_mov_b32_e32 v54, v4
	v_mov_b32_e32 v55, v4
	v_mov_b32_e32 v56, v4
	v_mov_b32_e32 v57, v4
	v_mov_b32_e32 v58, v4
	v_mov_b32_e32 v59, v4
	v_mov_b32_e32 v12, v4
	v_mov_b32_e32 v13, v4
	v_mov_b32_e32 v14, v4
	v_mov_b32_e32 v15, v4
	v_mov_b32_e32 v16, v4
	v_mov_b32_e32 v17, v4
	v_mov_b32_e32 v18, v4
	v_mov_b32_e32 v19, v4
	v_mov_b32_e32 v28, v4
	v_mov_b32_e32 v29, v4
	v_mov_b32_e32 v30, v4
	v_mov_b32_e32 v31, v4
	v_mov_b32_e32 v32, v4
	v_mov_b32_e32 v33, v4
	v_mov_b32_e32 v34, v4
	v_mov_b32_e32 v35, v4
	v_mov_b32_e32 v44, v4
	v_mov_b32_e32 v45, v4
	v_mov_b32_e32 v46, v4
	v_mov_b32_e32 v47, v4
	v_mov_b32_e32 v48, v4
	v_mov_b32_e32 v49, v4
	v_mov_b32_e32 v50, v4
	v_mov_b32_e32 v51, v4
	v_mov_b32_e32 v60, v4
	v_mov_b32_e32 v61, v4
	v_mov_b32_e32 v62, v4
	v_mov_b32_e32 v63, v4
	v_mov_b32_e32 v64, v4
	v_mov_b32_e32 v65, v4
	v_mov_b32_e32 v66, v4
	v_mov_b32_e32 v67, v4
	v_mov_b32_e32 v68, v4
	v_mov_b32_e32 v69, v4
	v_mov_b32_e32 v70, v4
	v_mov_b32_e32 v71, v4
	v_mov_b32_e32 v72, v4
	v_mov_b32_e32 v73, v4
	v_mov_b32_e32 v74, v4
	v_mov_b32_e32 v75, v4
	v_mov_b32_e32 v84, v4
	v_mov_b32_e32 v85, v4
	v_mov_b32_e32 v86, v4
	v_mov_b32_e32 v87, v4
	v_mov_b32_e32 v88, v4
	v_mov_b32_e32 v89, v4
	v_mov_b32_e32 v90, v4
	v_mov_b32_e32 v91, v4
	v_mov_b32_e32 v100, v4
	v_mov_b32_e32 v101, v4
	v_mov_b32_e32 v102, v4
	v_mov_b32_e32 v103, v4
	v_mov_b32_e32 v104, v4
	v_mov_b32_e32 v105, v4
	v_mov_b32_e32 v106, v4
	v_mov_b32_e32 v107, v4
	v_mov_b32_e32 v116, v4
	v_mov_b32_e32 v117, v4
	v_mov_b32_e32 v118, v4
	v_mov_b32_e32 v119, v4
	v_mov_b32_e32 v120, v4
	v_mov_b32_e32 v121, v4
	v_mov_b32_e32 v122, v4
	v_mov_b32_e32 v123, v4
	v_mov_b32_e32 v76, v4
	v_mov_b32_e32 v77, v4
	v_mov_b32_e32 v78, v4
	v_mov_b32_e32 v79, v4
	v_mov_b32_e32 v80, v4
	v_mov_b32_e32 v81, v4
	v_mov_b32_e32 v82, v4
	v_mov_b32_e32 v83, v4
	v_mov_b32_e32 v92, v4
	v_mov_b32_e32 v93, v4
	v_mov_b32_e32 v94, v4
	v_mov_b32_e32 v95, v4
	v_mov_b32_e32 v96, v4
	v_mov_b32_e32 v97, v4
	v_mov_b32_e32 v98, v4
	v_mov_b32_e32 v99, v4
	v_mov_b32_e32 v108, v4
	v_mov_b32_e32 v109, v4
	v_mov_b32_e32 v110, v4
	v_mov_b32_e32 v111, v4
	v_mov_b32_e32 v112, v4
	v_mov_b32_e32 v113, v4
	v_mov_b32_e32 v114, v4
	v_mov_b32_e32 v115, v4
	v_mov_b32_e32 v124, v4
	v_mov_b32_e32 v125, v4
	v_mov_b32_e32 v126, v4
	v_mov_b32_e32 v127, v4
	v_mov_b32_e32 v128, v4
	v_mov_b32_e32 v129, v4
	v_mov_b32_e32 v130, v4
	v_mov_b32_e32 v131, v4
	v_readlane_b32 s100, v251, 60
	s_cmp_lt_u32 s100, 4
	s_cbranch_scc1 .Lmy_prio_4
	s_setprio 1
.Lmy_prio_4:
.LBB0_2200:
	s_add_u32 s68, s60, 0x100
	s_addc_u32 s69, s61, 0
	s_add_i32 s67, 0, 0x10000
	s_cmp_eq_u32 s66, 12
	s_cselect_b32 s71, s0, s69
	s_cselect_b32 s70, s1, s68
	v_add_u32_e32 v3, s67, v165
	s_cselect_b32 s63, s29, s55
	s_cselect_b32 s62, s30, s53
	s_add_i32 s76, 0, 0x14000
	ds_read_b128 v[140:143], v3
	ds_read_b128 v[144:147], v3 offset:1024
	ds_read_b128 v[148:151], v3 offset:2048
	ds_read_b128 v[152:155], v3 offset:3072
	v_add_u32_e32 v3, s76, v165
	ds_read_b128 v[156:159], v3
	ds_read_b128 v[160:163], v3 offset:1024
	ds_read_b128 v[180:183], v3 offset:2048
	ds_read_b128 v[184:187], v3 offset:3072
	v_lshl_add_u64 v[168:169], s[60:61], 0, v[136:137]
	s_add_i32 m0, s85, 0xc000
	ds_read_b128 v[188:191], v167
	ds_read_b128 v[192:195], v167 offset:1024
	ds_read_b128 v[196:199], v167 offset:2048
	ds_read_b128 v[200:203], v167 offset:3072
	ds_read_b128 v[204:207], v167 offset:4096
	ds_read_b128 v[208:211], v167 offset:5120
	ds_read_b128 v[212:215], v167 offset:6144
	ds_read_b128 v[234:237], v167 offset:7168
	global_load_lds_dwordx4 v[168:169], off
	v_lshl_add_u64 v[168:169], s[60:61], 0, v[138:139]
	s_add_i32 m0, s85, 0xe000
	s_nop 0
	global_load_lds_dwordx4 v[168:169], off
	s_waitcnt vmcnt(8)
	s_waitcnt lgkmcnt(0)
	s_barrier
; #define PG8_STAGE(bufoff, gbase) do { _Pragma("unroll") for (int _i = 0; _i < 2; ++_i) \
;         __builtin_amdgcn_global_load_lds((const unsigned*)((const char*)(gbase) + voffA[_i]), (LAS unsigned*)(lds + (bufoff) + ldsw + _i * 8192), 16, 0, 0); } while (0)
; #define PG8_LDA(dst, b, h) do { _Pragma("unroll") for (int m = 0; m < 4; ++m) _Pragma("unroll") for (int k = 0; k < 2; ++k) dst[m][k] = *(const LAS bf16x8*)(lds + PG8_SA(b, h) + aoff + m * 2048 + k * 1024); } while (0)
; #define PG8_MMA(ai, bj, At, Bt) do { __builtin_amdgcn_s_setprio(1); _Pragma("unroll") for (int m = 0; m < 4; ++m) _Pragma("unroll") for (int n = 0; n < 2; ++n) _Pragma("unroll") for (int k = 0; k < 2; ++k) \
;         acc[ai][bj][m][n] = __builtin_amdgcn_mfma_f32_16x16x32_bf16(Bt[n][k], At[m][k], acc[ai][bj][m][n], 0, 0, 0); __builtin_amdgcn_s_setprio(0); } while (0)
; #define PG8_WAIT_V(n) asm volatile("s_waitcnt vmcnt(" #n ")" ::: "memory")
; #define PG8_WAIT_L(n) asm volatile("s_waitcnt lgkmcnt(" #n ")" ::: "memory")
; #define PG8_BAR __builtin_amdgcn_s_barrier()
; #define PG8_SCHED __builtin_amdgcn_sched_barrier(0)
; template <class Epi, class Sched>
; __device__ __forceinline__ void gemm_phase(LAS unsigned char* lds, const Gemm g, const Sched& S, const Epi& E, int wid) {
;     ...
;             PG8_WAIT_V(8); PG8_WAIT_L(0); PG8_BAR; PG8_MMA(0, 0, At, B0); PG8_MMA(0, 1, At, B1); PG8_BAR; PG8_SCHED;
;             PG8_LDA(At, 0, 1); PG8_STAGE(PG8_SB(0, 0), b2); PG8_STAGE(PG8_SB(0, 1), b2 + hstep); PG8_STAGE(PG8_SA(0, 0), a2);
;             PG8_WAIT_V(8); PG8_WAIT_L(0); PG8_BAR; PG8_MMA(1, 0, At, B0); PG8_MMA(1, 1, At, B1); PG8_BAR; PG8_SCHED;
	s_waitcnt lgkmcnt(0)
	v_mfma_f32_16x16x32_bf16 v[128:131], v[140:143], v[188:191], v[128:131]
	v_mfma_f32_16x16x32_bf16 v[124:127], v[148:151], v[188:191], v[124:127]
	v_mfma_f32_16x16x32_bf16 v[112:115], v[140:143], v[196:199], v[112:115]
	v_mfma_f32_16x16x32_bf16 v[108:111], v[148:151], v[196:199], v[108:111]
	v_mfma_f32_16x16x32_bf16 v[96:99], v[140:143], v[204:207], v[96:99]
	v_mfma_f32_16x16x32_bf16 v[92:95], v[148:151], v[204:207], v[92:95]
	v_mfma_f32_16x16x32_bf16 v[80:83], v[140:143], v[212:215], v[80:83]
	v_mfma_f32_16x16x32_bf16 v[76:79], v[148:151], v[212:215], v[76:79]
	v_mfma_f32_16x16x32_bf16 v[128:131], v[144:147], v[192:195], v[128:131]
	v_mfma_f32_16x16x32_bf16 v[124:127], v[152:155], v[192:195], v[124:127]
	v_mfma_f32_16x16x32_bf16 v[112:115], v[144:147], v[200:203], v[112:115]
	v_mfma_f32_16x16x32_bf16 v[108:111], v[152:155], v[200:203], v[108:111]
	v_mfma_f32_16x16x32_bf16 v[96:99], v[144:147], v[208:211], v[96:99]
	v_mfma_f32_16x16x32_bf16 v[92:95], v[152:155], v[208:211], v[92:95]
	v_mfma_f32_16x16x32_bf16 v[80:83], v[144:147], v[234:237], v[80:83]
	v_mfma_f32_16x16x32_bf16 v[76:79], v[152:155], v[234:237], v[76:79]
	v_mfma_f32_16x16x32_bf16 v[120:123], v[156:159], v[188:191], v[120:123]
	v_mfma_f32_16x16x32_bf16 v[116:119], v[180:183], v[188:191], v[116:119]
	v_mfma_f32_16x16x32_bf16 v[104:107], v[156:159], v[196:199], v[104:107]
	v_mfma_f32_16x16x32_bf16 v[100:103], v[180:183], v[196:199], v[100:103]
	v_mfma_f32_16x16x32_bf16 v[88:91], v[156:159], v[204:207], v[88:91]
	v_mfma_f32_16x16x32_bf16 v[84:87], v[180:183], v[204:207], v[84:87]
	v_mfma_f32_16x16x32_bf16 v[72:75], v[156:159], v[212:215], v[72:75]
	v_mfma_f32_16x16x32_bf16 v[68:71], v[180:183], v[212:215], v[68:71]
	v_mfma_f32_16x16x32_bf16 v[120:123], v[160:163], v[192:195], v[120:123]
	v_mfma_f32_16x16x32_bf16 v[116:119], v[184:187], v[192:195], v[116:119]
	v_mfma_f32_16x16x32_bf16 v[104:107], v[160:163], v[200:203], v[104:107]
	v_mfma_f32_16x16x32_bf16 v[100:103], v[184:187], v[200:203], v[100:103]
	v_mfma_f32_16x16x32_bf16 v[88:91], v[160:163], v[208:211], v[88:91]
	v_mfma_f32_16x16x32_bf16 v[84:87], v[184:187], v[208:211], v[84:87]
	v_mfma_f32_16x16x32_bf16 v[72:75], v[160:163], v[234:237], v[72:75]
	v_mfma_f32_16x16x32_bf16 v[68:71], v[184:187], v[234:237], v[68:71]
	s_barrier
	s_add_i32 s60, s67, s87
	v_lshl_add_u64 v[168:169], s[62:63], 0, v[132:133]
	s_mov_b32 m0, s60
	ds_read_b128 v[188:191], v167 offset:16384
	ds_read_b128 v[192:195], v167 offset:17408
	ds_read_b128 v[196:199], v167 offset:18432
	ds_read_b128 v[200:203], v167 offset:19456
	ds_read_b128 v[204:207], v167 offset:20480
	ds_read_b128 v[208:211], v167 offset:21504
	ds_read_b128 v[212:215], v167 offset:22528
	ds_read_b128 v[234:237], v167 offset:23552
	global_load_lds_dwordx4 v[168:169], off
	s_add_i32 m0, s60, 0x2000
	s_add_u32 s60, s62, 0x40000
	v_lshl_add_u64 v[216:217], s[62:63], 0, v[0:1]
	s_addc_u32 s61, s63, 0
	s_add_i32 s67, s76, s87
	global_load_lds_dwordx4 v[216:217], off
	v_lshl_add_u64 v[238:239], s[60:61], 0, v[132:133]
	s_mov_b32 m0, s67
	v_lshl_add_u64 v[240:241], s[70:71], 0, v[0:1]
	global_load_lds_dwordx4 v[238:239], off
	v_lshl_add_u64 v[238:239], s[60:61], 0, v[0:1]
	s_add_i32 m0, s67, 0x2000
	s_nop 0
	global_load_lds_dwordx4 v[238:239], off
	v_lshl_add_u64 v[238:239], s[70:71], 0, v[132:133]
	s_mov_b32 m0, s85
	s_nop 0
	global_load_lds_dwordx4 v[238:239], off
	s_mov_b32 m0, s4
	s_nop 0
	global_load_lds_dwordx4 v[240:241], off
	s_waitcnt vmcnt(8)
	s_waitcnt lgkmcnt(0)
	s_barrier
	s_waitcnt lgkmcnt(0)
	v_mfma_f32_16x16x32_bf16 v[64:67], v[140:143], v[188:191], v[64:67]
	v_mfma_f32_16x16x32_bf16 v[60:63], v[148:151], v[188:191], v[60:63]
	v_mfma_f32_16x16x32_bf16 v[48:51], v[140:143], v[196:199], v[48:51]
	v_mfma_f32_16x16x32_bf16 v[44:47], v[148:151], v[196:199], v[44:47]
	v_mfma_f32_16x16x32_bf16 v[32:35], v[140:143], v[204:207], v[32:35]
	v_mfma_f32_16x16x32_bf16 v[28:31], v[148:151], v[204:207], v[28:31]
	v_mfma_f32_16x16x32_bf16 v[16:19], v[140:143], v[212:215], v[16:19]
	v_mfma_f32_16x16x32_bf16 v[12:15], v[148:151], v[212:215], v[12:15]
	v_mfma_f32_16x16x32_bf16 v[64:67], v[144:147], v[192:195], v[64:67]
	v_mfma_f32_16x16x32_bf16 v[60:63], v[152:155], v[192:195], v[60:63]
	v_mfma_f32_16x16x32_bf16 v[48:51], v[144:147], v[200:203], v[48:51]
	v_mfma_f32_16x16x32_bf16 v[44:47], v[152:155], v[200:203], v[44:47]
	v_mfma_f32_16x16x32_bf16 v[32:35], v[144:147], v[208:211], v[32:35]
	v_mfma_f32_16x16x32_bf16 v[28:31], v[152:155], v[208:211], v[28:31]
	v_mfma_f32_16x16x32_bf16 v[16:19], v[144:147], v[234:237], v[16:19]
	v_mfma_f32_16x16x32_bf16 v[12:15], v[152:155], v[234:237], v[12:15]
	v_mfma_f32_16x16x32_bf16 v[56:59], v[156:159], v[188:191], v[56:59]
	v_mfma_f32_16x16x32_bf16 v[52:55], v[180:183], v[188:191], v[52:55]
	v_mfma_f32_16x16x32_bf16 v[40:43], v[156:159], v[196:199], v[40:43]
	v_mfma_f32_16x16x32_bf16 v[36:39], v[180:183], v[196:199], v[36:39]
	v_mfma_f32_16x16x32_bf16 v[24:27], v[156:159], v[204:207], v[24:27]
	v_mfma_f32_16x16x32_bf16 v[20:23], v[180:183], v[204:207], v[20:23]
	v_mfma_f32_16x16x32_bf16 v[8:11], v[156:159], v[212:215], v[8:11]
	v_mfma_f32_16x16x32_bf16 v[4:7], v[180:183], v[212:215], v[4:7]
	v_mfma_f32_16x16x32_bf16 v[56:59], v[160:163], v[192:195], v[56:59]
	v_mfma_f32_16x16x32_bf16 v[52:55], v[184:187], v[192:195], v[52:55]
	v_mfma_f32_16x16x32_bf16 v[40:43], v[160:163], v[200:203], v[40:43]
	v_mfma_f32_16x16x32_bf16 v[36:39], v[184:187], v[200:203], v[36:39]
	v_mfma_f32_16x16x32_bf16 v[24:27], v[160:163], v[208:211], v[24:27]
	v_mfma_f32_16x16x32_bf16 v[20:23], v[184:187], v[208:211], v[20:23]
	v_mfma_f32_16x16x32_bf16 v[8:11], v[160:163], v[234:237], v[8:11]
	v_mfma_f32_16x16x32_bf16 v[4:7], v[184:187], v[234:237], v[4:7]
	s_barrier
; #define PG8_STAGE(bufoff, gbase) do { _Pragma("unroll") for (int _i = 0; _i < 2; ++_i) \
;         __builtin_amdgcn_global_load_lds((const unsigned*)((const char*)(gbase) + voffA[_i]), (LAS unsigned*)(lds + (bufoff) + ldsw + _i * 8192), 16, 0, 0); } while (0)
; #define PG8_LDA(dst, b, h) do { _Pragma("unroll") for (int m = 0; m < 4; ++m) _Pragma("unroll") for (int k = 0; k < 2; ++k) dst[m][k] = *(const LAS bf16x8*)(lds + PG8_SA(b, h) + aoff + m * 2048 + k * 1024); } while (0)
; #define PG8_LDB(dst, b, h) do { _Pragma("unroll") for (int n = 0; n < 2; ++n) _Pragma("unroll") for (int k = 0; k < 2; ++k) dst[n][k] = *(const LAS bf16x8*)(lds + PG8_SB(b, h) + boff + n * 2048 + k * 1024); } while (0)
; #define PG8_MMA(ai, bj, At, Bt) do { __builtin_amdgcn_s_setprio(1); _Pragma("unroll") for (int m = 0; m < 4; ++m) _Pragma("unroll") for (int n = 0; n < 2; ++n) _Pragma("unroll") for (int k = 0; k < 2; ++k) \
;         acc[ai][bj][m][n] = __builtin_amdgcn_mfma_f32_16x16x32_bf16(Bt[n][k], At[m][k], acc[ai][bj][m][n], 0, 0, 0); __builtin_amdgcn_s_setprio(0); } while (0)
; #define PG8_WAIT_V(n) asm volatile("s_waitcnt vmcnt(" #n ")" ::: "memory")
; #define PG8_WAIT_L(n) asm volatile("s_waitcnt lgkmcnt(" #n ")" ::: "memory")
; #define PG8_BAR __builtin_amdgcn_s_barrier()
; #define PG8_SCHED __builtin_amdgcn_sched_barrier(0)
; template <class Epi, class Sched>
; __device__ __forceinline__ void gemm_phase(LAS unsigned char* lds, const Gemm g, const Sched& S, const Epi& E, int wid) {
;     ...
;             PG8_LDB(B0, 1, 0); PG8_LDB(B1, 1, 1); PG8_SCHED; PG8_LDA(At, 1, 0); PG8_STAGE(PG8_SA(0, 1), a2 + hstep);
;             PG8_WAIT_V(8); PG8_WAIT_L(0); PG8_BAR; PG8_MMA(0, 0, At, B0); PG8_MMA(0, 1, At, B1); PG8_BAR; PG8_SCHED;
	s_add_i32 s67, 0, 0x18000
	v_add_u32_e32 v3, s67, v165
	s_add_i32 s76, 0, 0x1c000
	ds_read_b128 v[140:143], v3
	ds_read_b128 v[144:147], v3 offset:1024
	ds_read_b128 v[148:151], v3 offset:2048
	ds_read_b128 v[152:155], v3 offset:3072
	v_add_u32_e32 v3, s76, v165
	ds_read_b128 v[156:159], v3
	ds_read_b128 v[160:163], v3 offset:1024
	ds_read_b128 v[180:183], v3 offset:2048
	ds_read_b128 v[184:187], v3 offset:3072
	s_add_u32 s60, s70, 0x40000
	s_addc_u32 s61, s71, 0
	s_mov_b32 m0, s9
	v_lshl_add_u64 v[242:243], s[60:61], 0, v[132:133]
	ds_read_b128 v[188:191], v167 offset:32768
	ds_read_b128 v[192:195], v167 offset:33792
	ds_read_b128 v[196:199], v167 offset:34816
	ds_read_b128 v[200:203], v167 offset:35840
	ds_read_b128 v[204:207], v167 offset:36864
	ds_read_b128 v[208:211], v167 offset:37888
	ds_read_b128 v[212:215], v167 offset:38912
	ds_read_b128 v[234:237], v167 offset:39936
	global_load_lds_dwordx4 v[242:243], off
	v_lshl_add_u64 v[242:243], s[60:61], 0, v[0:1]
	s_mov_b32 m0, s10
	s_nop 0
	global_load_lds_dwordx4 v[242:243], off
	s_waitcnt vmcnt(8)
	s_waitcnt lgkmcnt(0)
	s_barrier
	s_waitcnt lgkmcnt(0)
	v_mfma_f32_16x16x32_bf16 v[128:131], v[140:143], v[188:191], v[128:131]
	v_mfma_f32_16x16x32_bf16 v[124:127], v[148:151], v[188:191], v[124:127]
	v_mfma_f32_16x16x32_bf16 v[112:115], v[140:143], v[196:199], v[112:115]
	v_mfma_f32_16x16x32_bf16 v[108:111], v[148:151], v[196:199], v[108:111]
	v_mfma_f32_16x16x32_bf16 v[96:99], v[140:143], v[204:207], v[96:99]
	v_mfma_f32_16x16x32_bf16 v[92:95], v[148:151], v[204:207], v[92:95]
	v_mfma_f32_16x16x32_bf16 v[80:83], v[140:143], v[212:215], v[80:83]
	v_mfma_f32_16x16x32_bf16 v[76:79], v[148:151], v[212:215], v[76:79]
	v_mfma_f32_16x16x32_bf16 v[128:131], v[144:147], v[192:195], v[128:131]
	v_mfma_f32_16x16x32_bf16 v[124:127], v[152:155], v[192:195], v[124:127]
	v_mfma_f32_16x16x32_bf16 v[112:115], v[144:147], v[200:203], v[112:115]
	v_mfma_f32_16x16x32_bf16 v[108:111], v[152:155], v[200:203], v[108:111]
	v_mfma_f32_16x16x32_bf16 v[96:99], v[144:147], v[208:211], v[96:99]
	v_mfma_f32_16x16x32_bf16 v[92:95], v[152:155], v[208:211], v[92:95]
	v_mfma_f32_16x16x32_bf16 v[80:83], v[144:147], v[234:237], v[80:83]
	v_mfma_f32_16x16x32_bf16 v[76:79], v[152:155], v[234:237], v[76:79]
	v_mfma_f32_16x16x32_bf16 v[120:123], v[156:159], v[188:191], v[120:123]
	v_mfma_f32_16x16x32_bf16 v[116:119], v[180:183], v[188:191], v[116:119]
	v_mfma_f32_16x16x32_bf16 v[104:107], v[156:159], v[196:199], v[104:107]
	v_mfma_f32_16x16x32_bf16 v[100:103], v[180:183], v[196:199], v[100:103]
	v_mfma_f32_16x16x32_bf16 v[88:91], v[156:159], v[204:207], v[88:91]
	v_mfma_f32_16x16x32_bf16 v[84:87], v[180:183], v[204:207], v[84:87]
	v_mfma_f32_16x16x32_bf16 v[72:75], v[156:159], v[212:215], v[72:75]
	v_mfma_f32_16x16x32_bf16 v[68:71], v[180:183], v[212:215], v[68:71]
	v_mfma_f32_16x16x32_bf16 v[120:123], v[160:163], v[192:195], v[120:123]
	v_mfma_f32_16x16x32_bf16 v[116:119], v[184:187], v[192:195], v[116:119]
	v_mfma_f32_16x16x32_bf16 v[104:107], v[160:163], v[200:203], v[104:107]
	v_mfma_f32_16x16x32_bf16 v[100:103], v[184:187], v[200:203], v[100:103]
	v_mfma_f32_16x16x32_bf16 v[88:91], v[160:163], v[208:211], v[88:91]
	v_mfma_f32_16x16x32_bf16 v[84:87], v[184:187], v[208:211], v[84:87]
	v_mfma_f32_16x16x32_bf16 v[72:75], v[160:163], v[234:237], v[72:75]
	v_mfma_f32_16x16x32_bf16 v[68:71], v[184:187], v[234:237], v[68:71]
	s_barrier
; #define PG8_STAGE(bufoff, gbase) do { _Pragma("unroll") for (int _i = 0; _i < 2; ++_i) \
;         __builtin_amdgcn_global_load_lds((const unsigned*)((const char*)(gbase) + voffA[_i]), (LAS unsigned*)(lds + (bufoff) + ldsw + _i * 8192), 16, 0, 0); } while (0)
; #define PG8_LDA(dst, b, h) do { _Pragma("unroll") for (int m = 0; m < 4; ++m) _Pragma("unroll") for (int k = 0; k < 2; ++k) dst[m][k] = *(const LAS bf16x8*)(lds + PG8_SA(b, h) + aoff + m * 2048 + k * 1024); } while (0)
; #define PG8_MMA(ai, bj, At, Bt) do { __builtin_amdgcn_s_setprio(1); _Pragma("unroll") for (int m = 0; m < 4; ++m) _Pragma("unroll") for (int n = 0; n < 2; ++n) _Pragma("unroll") for (int k = 0; k < 2; ++k) \
;         acc[ai][bj][m][n] = __builtin_amdgcn_mfma_f32_16x16x32_bf16(Bt[n][k], At[m][k], acc[ai][bj][m][n], 0, 0, 0); __builtin_amdgcn_s_setprio(0); } while (0)
; #define PG8_WAIT_V(n) asm volatile("s_waitcnt vmcnt(" #n ")" ::: "memory")
; #define PG8_WAIT_L(n) asm volatile("s_waitcnt lgkmcnt(" #n ")" ::: "memory")
; #define PG8_BAR __builtin_amdgcn_s_barrier()
; #define PG8_SCHED __builtin_amdgcn_sched_barrier(0)
; template <class Epi, class Sched>
; __device__ __forceinline__ void gemm_phase(LAS unsigned char* lds, const Gemm g, const Sched& S, const Epi& E, int wid) {
;     ...
;             PG8_LDA(At, 1, 1); PG8_STAGE(PG8_SB(1, 0), b3); PG8_STAGE(PG8_SB(1, 1), b3 + hstep); PG8_STAGE(PG8_SA(1, 0), a3);
;             PG8_WAIT_V(8); PG8_WAIT_L(0); PG8_BAR; PG8_MMA(1, 0, At, B0); PG8_MMA(1, 1, At, B1); PG8_BAR; PG8_SCHED;
;         }
;         if (wr == 0) PG8_BAR;
	s_add_i32 s60, s67, s87
	v_lshl_add_u64 v[168:169], v[168:169], 0, s[92:93]
	s_mov_b32 m0, s60
	ds_read_b128 v[188:191], v167 offset:49152
	ds_read_b128 v[192:195], v167 offset:50176
	ds_read_b128 v[196:199], v167 offset:51200
	ds_read_b128 v[200:203], v167 offset:52224
	ds_read_b128 v[204:207], v167 offset:53248
	ds_read_b128 v[208:211], v167 offset:54272
	ds_read_b128 v[212:215], v167 offset:55296
	ds_read_b128 v[234:237], v167 offset:56320
	global_load_lds_dwordx4 v[168:169], off
	s_add_i32 m0, s60, 0x2000
	s_add_u32 s60, s62, 0x40080
	v_lshl_add_u64 v[168:169], v[216:217], 0, s[92:93]
	s_addc_u32 s61, s63, 0
	s_add_i32 s62, s76, s87
	global_load_lds_dwordx4 v[168:169], off
	v_lshl_add_u64 v[168:169], s[60:61], 0, v[132:133]
	s_mov_b32 m0, s62
	s_nop 0
	global_load_lds_dwordx4 v[168:169], off
	v_lshl_add_u64 v[168:169], s[60:61], 0, v[0:1]
	s_add_i32 m0, s62, 0x2000
	s_nop 0
	global_load_lds_dwordx4 v[168:169], off
	v_lshl_add_u64 v[168:169], v[238:239], 0, s[92:93]
	s_mov_b32 m0, s11
	s_nop 0
	global_load_lds_dwordx4 v[168:169], off
	v_lshl_add_u64 v[168:169], v[240:241], 0, s[92:93]
	s_mov_b32 m0, s20
	s_nop 0
	global_load_lds_dwordx4 v[168:169], off
	s_waitcnt vmcnt(8)
	s_waitcnt lgkmcnt(0)
	s_barrier
	s_waitcnt lgkmcnt(0)
	v_mfma_f32_16x16x32_bf16 v[64:67], v[140:143], v[188:191], v[64:67]
	v_mfma_f32_16x16x32_bf16 v[60:63], v[148:151], v[188:191], v[60:63]
	v_mfma_f32_16x16x32_bf16 v[48:51], v[140:143], v[196:199], v[48:51]
	v_mfma_f32_16x16x32_bf16 v[44:47], v[148:151], v[196:199], v[44:47]
	v_mfma_f32_16x16x32_bf16 v[32:35], v[140:143], v[204:207], v[32:35]
	v_mfma_f32_16x16x32_bf16 v[28:31], v[148:151], v[204:207], v[28:31]
	v_mfma_f32_16x16x32_bf16 v[16:19], v[140:143], v[212:215], v[16:19]
	v_mfma_f32_16x16x32_bf16 v[12:15], v[148:151], v[212:215], v[12:15]
	v_mfma_f32_16x16x32_bf16 v[64:67], v[144:147], v[192:195], v[64:67]
	v_mfma_f32_16x16x32_bf16 v[60:63], v[152:155], v[192:195], v[60:63]
	v_mfma_f32_16x16x32_bf16 v[48:51], v[144:147], v[200:203], v[48:51]
	v_mfma_f32_16x16x32_bf16 v[44:47], v[152:155], v[200:203], v[44:47]
	v_mfma_f32_16x16x32_bf16 v[32:35], v[144:147], v[208:211], v[32:35]
	v_mfma_f32_16x16x32_bf16 v[28:31], v[152:155], v[208:211], v[28:31]
	v_mfma_f32_16x16x32_bf16 v[16:19], v[144:147], v[234:237], v[16:19]
	v_mfma_f32_16x16x32_bf16 v[12:15], v[152:155], v[234:237], v[12:15]
	v_mfma_f32_16x16x32_bf16 v[56:59], v[156:159], v[188:191], v[56:59]
	v_mfma_f32_16x16x32_bf16 v[52:55], v[180:183], v[188:191], v[52:55]
	v_mfma_f32_16x16x32_bf16 v[40:43], v[156:159], v[196:199], v[40:43]
	v_mfma_f32_16x16x32_bf16 v[36:39], v[180:183], v[196:199], v[36:39]
	v_mfma_f32_16x16x32_bf16 v[24:27], v[156:159], v[204:207], v[24:27]
	v_mfma_f32_16x16x32_bf16 v[20:23], v[180:183], v[204:207], v[20:23]
	v_mfma_f32_16x16x32_bf16 v[8:11], v[156:159], v[212:215], v[8:11]
	v_mfma_f32_16x16x32_bf16 v[4:7], v[180:183], v[212:215], v[4:7]
	v_mfma_f32_16x16x32_bf16 v[56:59], v[160:163], v[192:195], v[56:59]
	v_mfma_f32_16x16x32_bf16 v[52:55], v[184:187], v[192:195], v[52:55]
	v_mfma_f32_16x16x32_bf16 v[40:43], v[160:163], v[200:203], v[40:43]
	v_mfma_f32_16x16x32_bf16 v[36:39], v[184:187], v[200:203], v[36:39]
	v_mfma_f32_16x16x32_bf16 v[24:27], v[160:163], v[208:211], v[24:27]
	v_mfma_f32_16x16x32_bf16 v[20:23], v[184:187], v[208:211], v[20:23]
	v_mfma_f32_16x16x32_bf16 v[8:11], v[160:163], v[234:237], v[8:11]
	v_mfma_f32_16x16x32_bf16 v[4:7], v[184:187], v[234:237], v[4:7]
	s_barrier
	s_add_i32 s66, s66, 2
	s_add_u32 s53, s53, 0x100
	s_addc_u32 s55, s55, 0
	s_cmp_gt_u32 s66, 13
	s_mov_b64 s[60:61], s[68:69]
	s_cbranch_scc0 .LBB0_2200
	s_setprio 0
	v_readlane_b32 s0, v252, 28
	v_readlane_b32 s1, v252, 29
	s_and_b64 vcc, exec, s[0:1]
	s_cbranch_vccz .LBB0_2203
	s_barrier

; #define PG8_STAGE(bufoff, gbase) do { _Pragma("unroll") for (int _i = 0; _i < 2; ++_i) \
;         __builtin_amdgcn_global_load_lds((const unsigned*)((const char*)(gbase) + voffA[_i]), (LAS unsigned*)(lds + (bufoff) + ldsw + _i * 8192), 16, 0, 0); } while (0)
; #define PG8_LDA(dst, b, h) do { _Pragma("unroll") for (int m = 0; m < 4; ++m) _Pragma("unroll") for (int k = 0; k < 2; ++k) dst[m][k] = *(const LAS bf16x8*)(lds + PG8_SA(b, h) + aoff + m * 2048 + k * 1024); } while (0)
; #define PG8_LDB(dst, b, h) do { _Pragma("unroll") for (int n = 0; n < 2; ++n) _Pragma("unroll") for (int k = 0; k < 2; ++k) dst[n][k] = *(const LAS bf16x8*)(lds + PG8_SB(b, h) + boff + n * 2048 + k * 1024); } while (0)
; #define PG8_SCHED __builtin_amdgcn_sched_barrier(0)
; template <class Epi, class Sched>
; __device__ __forceinline__ void gemm_phase(LAS unsigned char* lds, const Gemm g, const Sched& S, const Epi& E, int wid) {
;     ...
;         const bool has_next = S.next(ui + 1, nxt);
;         const char* nA = has_next ? (const char*)g.A + (size_t)nxt.pm * tstep : cA; const char* nB = has_next ? (const char*)g.Bt + (size_t)nxt.pn * tstep : cB;
;         for (int t = 0; t < nt; t += 2) {
;             const bool last = (t == nt - 2);
;             const char* a1 = cA + (size_t)(t + 1) * kstep;
;             const char* a2 = last ? nA : cA + (size_t)(t + 2) * kstep; const char* b2 = last ? nB : cB + (size_t)(t + 2) * kstep;
;             const char* a3 = a2 + kstep; const char* b3 = b2 + kstep;
;             PG8_LDB(B0, 0, 0); PG8_LDB(B1, 0, 1); PG8_SCHED; PG8_LDA(At, 0, 0); PG8_STAGE(PG8_SA(1, 1), a1 + hstep);
;     ...
; #pragma unroll
;         for (int a = 0; a < 2; ++a)
; #pragma unroll
;             for (int b = 0; b < 2; ++b)
; #pragma unroll
;                 for (int m = 0; m < 4; ++m)
; #pragma unroll
;                     for (int n = 0; n < 2; ++n) acc[a][b][m][n] = (f32x4){0.f, 0.f, 0.f, 0.f};
;         cur = nxt; cA = nA; cB = nB; ++ui;
.LBB0_2295:
	s_ashr_i32 s53, s52, 31
	s_lshl_b64 s[0:1], s[52:53], 19
	s_add_u32 s54, s70, s0
	s_addc_u32 s55, s71, s1
	s_and_b64 s[0:1], s[40:41], exec
	s_cselect_b32 s0, s55, s59
	s_cselect_b32 s1, s54, s58
	s_ashr_i32 s51, s50, 31
	s_lshl_b64 s[56:57], s[50:51], 19
	s_add_u32 s56, s2, s56
	s_addc_u32 s57, s4, s57
	s_and_b64 s[62:63], s[40:41], exec
	s_cselect_b32 s29, s57, s61
	s_cselect_b32 s30, s56, s60
	s_add_u32 s58, s58, 0x40080
	s_addc_u32 s59, s59, 0
	s_add_u32 s45, s60, 0x100
	v_mov_b32_e32 v4, 0
	s_addc_u32 s51, s61, 0
	s_mov_b32 s53, -2
	v_mov_b32_e32 v5, v4
	v_mov_b32_e32 v6, v4
	v_mov_b32_e32 v7, v4
	v_mov_b32_e32 v28, v4
	v_mov_b32_e32 v29, v4
	v_mov_b32_e32 v30, v4
	v_mov_b32_e32 v31, v4
	v_mov_b32_e32 v8, v4
	v_mov_b32_e32 v9, v4
	v_mov_b32_e32 v10, v4
	v_mov_b32_e32 v11, v4
	v_mov_b32_e32 v36, v4
	v_mov_b32_e32 v37, v4
	v_mov_b32_e32 v38, v4
	v_mov_b32_e32 v39, v4
	v_mov_b32_e32 v12, v4
	v_mov_b32_e32 v13, v4
	v_mov_b32_e32 v14, v4
	v_mov_b32_e32 v15, v4
	v_mov_b32_e32 v44, v4
	v_mov_b32_e32 v45, v4
	v_mov_b32_e32 v46, v4
	v_mov_b32_e32 v47, v4
	v_mov_b32_e32 v16, v4
	v_mov_b32_e32 v17, v4
	v_mov_b32_e32 v18, v4
	v_mov_b32_e32 v19, v4
	v_mov_b32_e32 v48, v4
	v_mov_b32_e32 v49, v4
	v_mov_b32_e32 v50, v4
	v_mov_b32_e32 v51, v4
	v_mov_b32_e32 v64, v4
	v_mov_b32_e32 v65, v4
	v_mov_b32_e32 v66, v4
	v_mov_b32_e32 v67, v4
	v_mov_b32_e32 v92, v4
	v_mov_b32_e32 v93, v4
	v_mov_b32_e32 v94, v4
	v_mov_b32_e32 v95, v4
	v_mov_b32_e32 v72, v4
	v_mov_b32_e32 v73, v4
	v_mov_b32_e32 v74, v4
	v_mov_b32_e32 v75, v4
	v_mov_b32_e32 v100, v4
	v_mov_b32_e32 v101, v4
	v_mov_b32_e32 v102, v4
	v_mov_b32_e32 v103, v4
	v_mov_b32_e32 v76, v4
	v_mov_b32_e32 v77, v4
	v_mov_b32_e32 v78, v4
	v_mov_b32_e32 v79, v4
	v_mov_b32_e32 v108, v4
	v_mov_b32_e32 v109, v4
	v_mov_b32_e32 v110, v4
	v_mov_b32_e32 v111, v4
	v_mov_b32_e32 v80, v4
	v_mov_b32_e32 v81, v4
	v_mov_b32_e32 v82, v4
	v_mov_b32_e32 v83, v4
	v_mov_b32_e32 v112, v4
	v_mov_b32_e32 v113, v4
	v_mov_b32_e32 v114, v4
	v_mov_b32_e32 v115, v4
	v_mov_b32_e32 v20, v4
	v_mov_b32_e32 v21, v4
	v_mov_b32_e32 v22, v4
	v_mov_b32_e32 v23, v4
	v_mov_b32_e32 v52, v4
	v_mov_b32_e32 v53, v4
	v_mov_b32_e32 v54, v4
	v_mov_b32_e32 v55, v4
	v_mov_b32_e32 v24, v4
	v_mov_b32_e32 v25, v4
	v_mov_b32_e32 v26, v4
	v_mov_b32_e32 v27, v4
	v_mov_b32_e32 v56, v4
	v_mov_b32_e32 v57, v4
	v_mov_b32_e32 v58, v4
	v_mov_b32_e32 v59, v4
	v_mov_b32_e32 v32, v4
	v_mov_b32_e32 v33, v4
	v_mov_b32_e32 v34, v4
	v_mov_b32_e32 v35, v4
	v_mov_b32_e32 v60, v4
	v_mov_b32_e32 v61, v4
	v_mov_b32_e32 v62, v4
	v_mov_b32_e32 v63, v4
	v_mov_b32_e32 v40, v4
	v_mov_b32_e32 v41, v4
	v_mov_b32_e32 v42, v4
	v_mov_b32_e32 v43, v4
	v_mov_b32_e32 v68, v4
	v_mov_b32_e32 v69, v4
	v_mov_b32_e32 v70, v4
	v_mov_b32_e32 v71, v4
	v_mov_b32_e32 v84, v4
	v_mov_b32_e32 v85, v4
	v_mov_b32_e32 v86, v4
	v_mov_b32_e32 v87, v4
	v_mov_b32_e32 v116, v4
	v_mov_b32_e32 v117, v4
	v_mov_b32_e32 v118, v4
	v_mov_b32_e32 v119, v4
	v_mov_b32_e32 v88, v4
	v_mov_b32_e32 v89, v4
	v_mov_b32_e32 v90, v4
	v_mov_b32_e32 v91, v4
	v_mov_b32_e32 v120, v4
	v_mov_b32_e32 v121, v4
	v_mov_b32_e32 v122, v4
	v_mov_b32_e32 v123, v4
	v_mov_b32_e32 v96, v4
	v_mov_b32_e32 v97, v4
	v_mov_b32_e32 v98, v4
	v_mov_b32_e32 v99, v4
	v_mov_b32_e32 v124, v4
	v_mov_b32_e32 v125, v4
	v_mov_b32_e32 v126, v4
	v_mov_b32_e32 v127, v4
	v_mov_b32_e32 v104, v4
	v_mov_b32_e32 v105, v4
	v_mov_b32_e32 v106, v4
	v_mov_b32_e32 v107, v4
	v_mov_b32_e32 v128, v4
	v_mov_b32_e32 v129, v4
	v_mov_b32_e32 v130, v4
	v_mov_b32_e32 v131, v4
	v_readlane_b32 s100, v251, 60
	s_cmp_lt_u32 s100, 4
	s_cbranch_scc1 .Lmy_prio_5
	s_setprio 1
.Lmy_prio_5:
.LBB0_2296:
	s_add_u32 s60, s58, 0xfffc0080
	s_addc_u32 s61, s59, -1
	s_add_i32 s66, 0, 0x10000
	s_cmp_eq_u32 s53, 12
	s_cselect_b32 s63, s0, s61
	s_cselect_b32 s62, s1, s60
	v_add_u32_e32 v148, s66, v151
	s_cselect_b32 s61, s29, s51
	s_cselect_b32 s60, s30, s45
	s_add_i32 s68, 0, 0x14000
	ds_read_b128 v[132:135], v148
	ds_read_b128 v[136:139], v148 offset:1024
	ds_read_b128 v[160:163], v148 offset:2048
	ds_read_b128 v[164:167], v148 offset:3072
	v_add_u32_e32 v148, s68, v151
	ds_read_b128 v[180:183], v148
	ds_read_b128 v[184:187], v148 offset:1024
	ds_read_b128 v[188:191], v148 offset:2048
	ds_read_b128 v[192:195], v148 offset:3072
	v_lshl_add_u64 v[148:149], s[58:59], 0, v[144:145]
	s_add_i32 m0, s85, 0xc000
	ds_read_b128 v[196:199], v159
	ds_read_b128 v[200:203], v159 offset:1024
	ds_read_b128 v[204:207], v159 offset:2048
	ds_read_b128 v[208:211], v159 offset:3072
	ds_read_b128 v[212:215], v159 offset:4096
	ds_read_b128 v[234:237], v159 offset:5120
	ds_read_b128 v[238:241], v159 offset:6144
	ds_read_b128 v[242:245], v159 offset:7168
	global_load_lds_dwordx4 v[148:149], off
	v_lshl_add_u64 v[148:149], s[58:59], 0, v[146:147]
	s_add_i32 m0, s85, 0xe000
	s_nop 0
	global_load_lds_dwordx4 v[148:149], off
	s_waitcnt vmcnt(8)
	s_waitcnt lgkmcnt(0)
	s_barrier
; #define PG8_STAGE(bufoff, gbase) do { _Pragma("unroll") for (int _i = 0; _i < 2; ++_i) \
;         __builtin_amdgcn_global_load_lds((const unsigned*)((const char*)(gbase) + voffA[_i]), (LAS unsigned*)(lds + (bufoff) + ldsw + _i * 8192), 16, 0, 0); } while (0)
; #define PG8_LDA(dst, b, h) do { _Pragma("unroll") for (int m = 0; m < 4; ++m) _Pragma("unroll") for (int k = 0; k < 2; ++k) dst[m][k] = *(const LAS bf16x8*)(lds + PG8_SA(b, h) + aoff + m * 2048 + k * 1024); } while (0)
; #define PG8_MMA(ai, bj, At, Bt) do { __builtin_amdgcn_s_setprio(1); _Pragma("unroll") for (int m = 0; m < 4; ++m) _Pragma("unroll") for (int n = 0; n < 2; ++n) _Pragma("unroll") for (int k = 0; k < 2; ++k) \
;         acc[ai][bj][m][n] = __builtin_amdgcn_mfma_f32_16x16x32_bf16(Bt[n][k], At[m][k], acc[ai][bj][m][n], 0, 0, 0); __builtin_amdgcn_s_setprio(0); } while (0)
; #define PG8_WAIT_V(n) asm volatile("s_waitcnt vmcnt(" #n ")" ::: "memory")
; #define PG8_WAIT_L(n) asm volatile("s_waitcnt lgkmcnt(" #n ")" ::: "memory")
; #define PG8_BAR __builtin_amdgcn_s_barrier()
; #define PG8_SCHED __builtin_amdgcn_sched_barrier(0)
; template <class Epi, class Sched>
; __device__ __forceinline__ void gemm_phase(LAS unsigned char* lds, const Gemm g, const Sched& S, const Epi& E, int wid) {
;     ...
;             PG8_WAIT_V(8); PG8_WAIT_L(0); PG8_BAR; PG8_MMA(0, 0, At, B0); PG8_MMA(0, 1, At, B1); PG8_BAR; PG8_SCHED;
;             PG8_LDA(At, 0, 1); PG8_STAGE(PG8_SB(0, 0), b2); PG8_STAGE(PG8_SB(0, 1), b2 + hstep); PG8_STAGE(PG8_SA(0, 0), a2);
;             PG8_WAIT_V(8); PG8_WAIT_L(0); PG8_BAR; PG8_MMA(1, 0, At, B0); PG8_MMA(1, 1, At, B1); PG8_BAR; PG8_SCHED;
	s_waitcnt lgkmcnt(0)
	v_mfma_f32_16x16x32_bf16 v[128:131], v[132:135], v[196:199], v[128:131]
	v_mfma_f32_16x16x32_bf16 v[104:107], v[160:163], v[196:199], v[104:107]
	v_mfma_f32_16x16x32_bf16 v[124:127], v[132:135], v[204:207], v[124:127]
	v_mfma_f32_16x16x32_bf16 v[96:99], v[160:163], v[204:207], v[96:99]
	v_mfma_f32_16x16x32_bf16 v[120:123], v[132:135], v[212:215], v[120:123]
	v_mfma_f32_16x16x32_bf16 v[88:91], v[160:163], v[212:215], v[88:91]
	v_mfma_f32_16x16x32_bf16 v[116:119], v[132:135], v[238:241], v[116:119]
	v_mfma_f32_16x16x32_bf16 v[84:87], v[160:163], v[238:241], v[84:87]
	v_mfma_f32_16x16x32_bf16 v[128:131], v[136:139], v[200:203], v[128:131]
	v_mfma_f32_16x16x32_bf16 v[104:107], v[164:167], v[200:203], v[104:107]
	v_mfma_f32_16x16x32_bf16 v[124:127], v[136:139], v[208:211], v[124:127]
	v_mfma_f32_16x16x32_bf16 v[96:99], v[164:167], v[208:211], v[96:99]
	v_mfma_f32_16x16x32_bf16 v[120:123], v[136:139], v[234:237], v[120:123]
	v_mfma_f32_16x16x32_bf16 v[88:91], v[164:167], v[234:237], v[88:91]
	v_mfma_f32_16x16x32_bf16 v[116:119], v[136:139], v[242:245], v[116:119]
	v_mfma_f32_16x16x32_bf16 v[84:87], v[164:167], v[242:245], v[84:87]
	v_mfma_f32_16x16x32_bf16 v[68:71], v[180:183], v[196:199], v[68:71]
	v_mfma_f32_16x16x32_bf16 v[40:43], v[188:191], v[196:199], v[40:43]
	v_mfma_f32_16x16x32_bf16 v[60:63], v[180:183], v[204:207], v[60:63]
	v_mfma_f32_16x16x32_bf16 v[32:35], v[188:191], v[204:207], v[32:35]
	v_mfma_f32_16x16x32_bf16 v[56:59], v[180:183], v[212:215], v[56:59]
	v_mfma_f32_16x16x32_bf16 v[24:27], v[188:191], v[212:215], v[24:27]
	v_mfma_f32_16x16x32_bf16 v[52:55], v[180:183], v[238:241], v[52:55]
	v_mfma_f32_16x16x32_bf16 v[20:23], v[188:191], v[238:241], v[20:23]
	v_mfma_f32_16x16x32_bf16 v[68:71], v[184:187], v[200:203], v[68:71]
	v_mfma_f32_16x16x32_bf16 v[40:43], v[192:195], v[200:203], v[40:43]
	v_mfma_f32_16x16x32_bf16 v[60:63], v[184:187], v[208:211], v[60:63]
	v_mfma_f32_16x16x32_bf16 v[32:35], v[192:195], v[208:211], v[32:35]
	v_mfma_f32_16x16x32_bf16 v[56:59], v[184:187], v[234:237], v[56:59]
	v_mfma_f32_16x16x32_bf16 v[24:27], v[192:195], v[234:237], v[24:27]
	v_mfma_f32_16x16x32_bf16 v[52:55], v[184:187], v[242:245], v[52:55]
	v_mfma_f32_16x16x32_bf16 v[20:23], v[192:195], v[242:245], v[20:23]
	s_barrier
	s_add_i32 s66, s66, s87
	v_lshl_add_u64 v[148:149], s[60:61], 0, v[140:141]
	s_mov_b32 m0, s66
	ds_read_b128 v[196:199], v159 offset:16384
	ds_read_b128 v[200:203], v159 offset:17408
	ds_read_b128 v[204:207], v159 offset:18432
	ds_read_b128 v[208:211], v159 offset:19456
	ds_read_b128 v[212:215], v159 offset:20480
	ds_read_b128 v[234:237], v159 offset:21504
	ds_read_b128 v[238:241], v159 offset:22528
	ds_read_b128 v[242:245], v159 offset:23552
	global_load_lds_dwordx4 v[148:149], off
	s_add_i32 m0, s66, 0x2000
	s_add_u32 s66, s60, 0x40000
	v_lshl_add_u64 v[152:153], s[60:61], 0, v[0:1]
	s_addc_u32 s67, s61, 0
	s_add_i32 s68, s68, s87
	global_load_lds_dwordx4 v[152:153], off
	v_lshl_add_u64 v[156:157], s[66:67], 0, v[140:141]
	s_mov_b32 m0, s68
	v_lshl_add_u64 v[168:169], s[62:63], 0, v[0:1]
	global_load_lds_dwordx4 v[156:157], off
	v_lshl_add_u64 v[156:157], s[66:67], 0, v[0:1]
	s_add_i32 m0, s68, 0x2000
	s_nop 0
	global_load_lds_dwordx4 v[156:157], off
	v_lshl_add_u64 v[156:157], s[62:63], 0, v[140:141]
	s_mov_b32 m0, s85
	s_nop 0
	global_load_lds_dwordx4 v[156:157], off
	s_mov_b32 m0, s8
	s_nop 0
	global_load_lds_dwordx4 v[168:169], off
	s_waitcnt vmcnt(8)
	s_waitcnt lgkmcnt(0)
	s_barrier
	s_waitcnt lgkmcnt(0)
	v_mfma_f32_16x16x32_bf16 v[112:115], v[132:135], v[196:199], v[112:115]
	v_mfma_f32_16x16x32_bf16 v[80:83], v[160:163], v[196:199], v[80:83]
	v_mfma_f32_16x16x32_bf16 v[108:111], v[132:135], v[204:207], v[108:111]
	v_mfma_f32_16x16x32_bf16 v[76:79], v[160:163], v[204:207], v[76:79]
	v_mfma_f32_16x16x32_bf16 v[100:103], v[132:135], v[212:215], v[100:103]
	v_mfma_f32_16x16x32_bf16 v[72:75], v[160:163], v[212:215], v[72:75]
	v_mfma_f32_16x16x32_bf16 v[92:95], v[132:135], v[238:241], v[92:95]
	v_mfma_f32_16x16x32_bf16 v[64:67], v[160:163], v[238:241], v[64:67]
	v_mfma_f32_16x16x32_bf16 v[112:115], v[136:139], v[200:203], v[112:115]
	v_mfma_f32_16x16x32_bf16 v[80:83], v[164:167], v[200:203], v[80:83]
	v_mfma_f32_16x16x32_bf16 v[108:111], v[136:139], v[208:211], v[108:111]
	v_mfma_f32_16x16x32_bf16 v[76:79], v[164:167], v[208:211], v[76:79]
	v_mfma_f32_16x16x32_bf16 v[100:103], v[136:139], v[234:237], v[100:103]
	v_mfma_f32_16x16x32_bf16 v[72:75], v[164:167], v[234:237], v[72:75]
	v_mfma_f32_16x16x32_bf16 v[92:95], v[136:139], v[242:245], v[92:95]
	v_mfma_f32_16x16x32_bf16 v[64:67], v[164:167], v[242:245], v[64:67]
	v_mfma_f32_16x16x32_bf16 v[48:51], v[180:183], v[196:199], v[48:51]
	v_mfma_f32_16x16x32_bf16 v[16:19], v[188:191], v[196:199], v[16:19]
	v_mfma_f32_16x16x32_bf16 v[44:47], v[180:183], v[204:207], v[44:47]
	v_mfma_f32_16x16x32_bf16 v[12:15], v[188:191], v[204:207], v[12:15]
	v_mfma_f32_16x16x32_bf16 v[36:39], v[180:183], v[212:215], v[36:39]
	v_mfma_f32_16x16x32_bf16 v[8:11], v[188:191], v[212:215], v[8:11]
	v_mfma_f32_16x16x32_bf16 v[28:31], v[180:183], v[238:241], v[28:31]
	v_mfma_f32_16x16x32_bf16 v[4:7], v[188:191], v[238:241], v[4:7]
	v_mfma_f32_16x16x32_bf16 v[48:51], v[184:187], v[200:203], v[48:51]
	v_mfma_f32_16x16x32_bf16 v[16:19], v[192:195], v[200:203], v[16:19]
	v_mfma_f32_16x16x32_bf16 v[44:47], v[184:187], v[208:211], v[44:47]
	v_mfma_f32_16x16x32_bf16 v[12:15], v[192:195], v[208:211], v[12:15]
	v_mfma_f32_16x16x32_bf16 v[36:39], v[184:187], v[234:237], v[36:39]
	v_mfma_f32_16x16x32_bf16 v[8:11], v[192:195], v[234:237], v[8:11]
	v_mfma_f32_16x16x32_bf16 v[28:31], v[184:187], v[242:245], v[28:31]
	v_mfma_f32_16x16x32_bf16 v[4:7], v[192:195], v[242:245], v[4:7]
	s_barrier
; #define PG8_STAGE(bufoff, gbase) do { _Pragma("unroll") for (int _i = 0; _i < 2; ++_i) \
;         __builtin_amdgcn_global_load_lds((const unsigned*)((const char*)(gbase) + voffA[_i]), (LAS unsigned*)(lds + (bufoff) + ldsw + _i * 8192), 16, 0, 0); } while (0)
; #define PG8_LDA(dst, b, h) do { _Pragma("unroll") for (int m = 0; m < 4; ++m) _Pragma("unroll") for (int k = 0; k < 2; ++k) dst[m][k] = *(const LAS bf16x8*)(lds + PG8_SA(b, h) + aoff + m * 2048 + k * 1024); } while (0)
; #define PG8_LDB(dst, b, h) do { _Pragma("unroll") for (int n = 0; n < 2; ++n) _Pragma("unroll") for (int k = 0; k < 2; ++k) dst[n][k] = *(const LAS bf16x8*)(lds + PG8_SB(b, h) + boff + n * 2048 + k * 1024); } while (0)
; #define PG8_MMA(ai, bj, At, Bt) do { __builtin_amdgcn_s_setprio(1); _Pragma("unroll") for (int m = 0; m < 4; ++m) _Pragma("unroll") for (int n = 0; n < 2; ++n) _Pragma("unroll") for (int k = 0; k < 2; ++k) \
;         acc[ai][bj][m][n] = __builtin_amdgcn_mfma_f32_16x16x32_bf16(Bt[n][k], At[m][k], acc[ai][bj][m][n], 0, 0, 0); __builtin_amdgcn_s_setprio(0); } while (0)
; #define PG8_WAIT_V(n) asm volatile("s_waitcnt vmcnt(" #n ")" ::: "memory")
; #define PG8_WAIT_L(n) asm volatile("s_waitcnt lgkmcnt(" #n ")" ::: "memory")
; #define PG8_BAR __builtin_amdgcn_s_barrier()
; #define PG8_SCHED __builtin_amdgcn_sched_barrier(0)
; template <class Epi, class Sched>
; __device__ __forceinline__ void gemm_phase(LAS unsigned char* lds, const Gemm g, const Sched& S, const Epi& E, int wid) {
;     ...
;             PG8_LDB(B0, 1, 0); PG8_LDB(B1, 1, 1); PG8_SCHED; PG8_LDA(At, 1, 0); PG8_STAGE(PG8_SA(0, 1), a2 + hstep);
;             PG8_WAIT_V(8); PG8_WAIT_L(0); PG8_BAR; PG8_MMA(0, 0, At, B0); PG8_MMA(0, 1, At, B1); PG8_BAR; PG8_SCHED;
	s_add_i32 s66, 0, 0x18000
	v_add_u32_e32 v150, s66, v151
	s_add_i32 s67, 0, 0x1c000
	ds_read_b128 v[132:135], v150
	ds_read_b128 v[136:139], v150 offset:1024
	ds_read_b128 v[160:163], v150 offset:2048
	ds_read_b128 v[164:167], v150 offset:3072
	v_add_u32_e32 v150, s67, v151
	ds_read_b128 v[180:183], v150
	ds_read_b128 v[184:187], v150 offset:1024
	ds_read_b128 v[188:191], v150 offset:2048
	ds_read_b128 v[192:195], v150 offset:3072
	s_add_u32 s62, s62, 0x40000
	s_addc_u32 s63, s63, 0
	s_mov_b32 m0, s9
	v_lshl_add_u64 v[216:217], s[62:63], 0, v[140:141]
	ds_read_b128 v[196:199], v159 offset:32768
	ds_read_b128 v[200:203], v159 offset:33792
	ds_read_b128 v[204:207], v159 offset:34816
	ds_read_b128 v[208:211], v159 offset:35840
	ds_read_b128 v[212:215], v159 offset:36864
	ds_read_b128 v[234:237], v159 offset:37888
	ds_read_b128 v[238:241], v159 offset:38912
	ds_read_b128 v[242:245], v159 offset:39936
	global_load_lds_dwordx4 v[216:217], off
	v_lshl_add_u64 v[216:217], s[62:63], 0, v[0:1]
	s_mov_b32 m0, s10
	s_nop 0
	global_load_lds_dwordx4 v[216:217], off
	s_waitcnt vmcnt(8)
	s_waitcnt lgkmcnt(0)
	s_barrier
	s_waitcnt lgkmcnt(0)
	v_mfma_f32_16x16x32_bf16 v[128:131], v[132:135], v[196:199], v[128:131]
	v_mfma_f32_16x16x32_bf16 v[104:107], v[160:163], v[196:199], v[104:107]
	v_mfma_f32_16x16x32_bf16 v[124:127], v[132:135], v[204:207], v[124:127]
	v_mfma_f32_16x16x32_bf16 v[96:99], v[160:163], v[204:207], v[96:99]
	v_mfma_f32_16x16x32_bf16 v[120:123], v[132:135], v[212:215], v[120:123]
	v_mfma_f32_16x16x32_bf16 v[88:91], v[160:163], v[212:215], v[88:91]
	v_mfma_f32_16x16x32_bf16 v[116:119], v[132:135], v[238:241], v[116:119]
	v_mfma_f32_16x16x32_bf16 v[84:87], v[160:163], v[238:241], v[84:87]
	v_mfma_f32_16x16x32_bf16 v[128:131], v[136:139], v[200:203], v[128:131]
	v_mfma_f32_16x16x32_bf16 v[104:107], v[164:167], v[200:203], v[104:107]
	v_mfma_f32_16x16x32_bf16 v[124:127], v[136:139], v[208:211], v[124:127]
	v_mfma_f32_16x16x32_bf16 v[96:99], v[164:167], v[208:211], v[96:99]
	v_mfma_f32_16x16x32_bf16 v[120:123], v[136:139], v[234:237], v[120:123]
	v_mfma_f32_16x16x32_bf16 v[88:91], v[164:167], v[234:237], v[88:91]
	v_mfma_f32_16x16x32_bf16 v[116:119], v[136:139], v[242:245], v[116:119]
	v_mfma_f32_16x16x32_bf16 v[84:87], v[164:167], v[242:245], v[84:87]
	v_mfma_f32_16x16x32_bf16 v[68:71], v[180:183], v[196:199], v[68:71]
	v_mfma_f32_16x16x32_bf16 v[40:43], v[188:191], v[196:199], v[40:43]
	v_mfma_f32_16x16x32_bf16 v[60:63], v[180:183], v[204:207], v[60:63]
	v_mfma_f32_16x16x32_bf16 v[32:35], v[188:191], v[204:207], v[32:35]
	v_mfma_f32_16x16x32_bf16 v[56:59], v[180:183], v[212:215], v[56:59]
	v_mfma_f32_16x16x32_bf16 v[24:27], v[188:191], v[212:215], v[24:27]
	v_mfma_f32_16x16x32_bf16 v[52:55], v[180:183], v[238:241], v[52:55]
	v_mfma_f32_16x16x32_bf16 v[20:23], v[188:191], v[238:241], v[20:23]
	v_mfma_f32_16x16x32_bf16 v[68:71], v[184:187], v[200:203], v[68:71]
	v_mfma_f32_16x16x32_bf16 v[40:43], v[192:195], v[200:203], v[40:43]
	v_mfma_f32_16x16x32_bf16 v[60:63], v[184:187], v[208:211], v[60:63]
	v_mfma_f32_16x16x32_bf16 v[32:35], v[192:195], v[208:211], v[32:35]
	v_mfma_f32_16x16x32_bf16 v[56:59], v[184:187], v[234:237], v[56:59]
	v_mfma_f32_16x16x32_bf16 v[24:27], v[192:195], v[234:237], v[24:27]
	v_mfma_f32_16x16x32_bf16 v[52:55], v[184:187], v[242:245], v[52:55]
	v_mfma_f32_16x16x32_bf16 v[20:23], v[192:195], v[242:245], v[20:23]
	s_barrier
; #define PG8_STAGE(bufoff, gbase) do { _Pragma("unroll") for (int _i = 0; _i < 2; ++_i) \
;         __builtin_amdgcn_global_load_lds((const unsigned*)((const char*)(gbase) + voffA[_i]), (LAS unsigned*)(lds + (bufoff) + ldsw + _i * 8192), 16, 0, 0); } while (0)
; #define PG8_LDA(dst, b, h) do { _Pragma("unroll") for (int m = 0; m < 4; ++m) _Pragma("unroll") for (int k = 0; k < 2; ++k) dst[m][k] = *(const LAS bf16x8*)(lds + PG8_SA(b, h) + aoff + m * 2048 + k * 1024); } while (0)
; #define PG8_MMA(ai, bj, At, Bt) do { __builtin_amdgcn_s_setprio(1); _Pragma("unroll") for (int m = 0; m < 4; ++m) _Pragma("unroll") for (int n = 0; n < 2; ++n) _Pragma("unroll") for (int k = 0; k < 2; ++k) \
;         acc[ai][bj][m][n] = __builtin_amdgcn_mfma_f32_16x16x32_bf16(Bt[n][k], At[m][k], acc[ai][bj][m][n], 0, 0, 0); __builtin_amdgcn_s_setprio(0); } while (0)
; #define PG8_WAIT_V(n) asm volatile("s_waitcnt vmcnt(" #n ")" ::: "memory")
; #define PG8_WAIT_L(n) asm volatile("s_waitcnt lgkmcnt(" #n ")" ::: "memory")
; #define PG8_BAR __builtin_amdgcn_s_barrier()
; #define PG8_SCHED __builtin_amdgcn_sched_barrier(0)
; template <class Epi, class Sched>
; __device__ __forceinline__ void gemm_phase(LAS unsigned char* lds, const Gemm g, const Sched& S, const Epi& E, int wid) {
;     ...
;             PG8_LDA(At, 1, 1); PG8_STAGE(PG8_SB(1, 0), b3); PG8_STAGE(PG8_SB(1, 1), b3 + hstep); PG8_STAGE(PG8_SA(1, 0), a3);
;             PG8_WAIT_V(8); PG8_WAIT_L(0); PG8_BAR; PG8_MMA(1, 0, At, B0); PG8_MMA(1, 1, At, B1); PG8_BAR; PG8_SCHED;
;         }
;         if (wr == 0) PG8_BAR;
	s_add_i32 s62, s66, s87
	v_lshl_add_u64 v[148:149], v[148:149], 0, s[92:93]
	s_mov_b32 m0, s62
	ds_read_b128 v[196:199], v159 offset:49152
	ds_read_b128 v[200:203], v159 offset:50176
	ds_read_b128 v[204:207], v159 offset:51200
	ds_read_b128 v[208:211], v159 offset:52224
	ds_read_b128 v[212:215], v159 offset:53248
	ds_read_b128 v[234:237], v159 offset:54272
	ds_read_b128 v[238:241], v159 offset:55296
	ds_read_b128 v[242:245], v159 offset:56320
	global_load_lds_dwordx4 v[148:149], off
	s_add_i32 m0, s62, 0x2000
	s_add_u32 s60, s60, 0x40080
	v_lshl_add_u64 v[148:149], v[152:153], 0, s[92:93]
	s_addc_u32 s61, s61, 0
	s_add_i32 s62, s67, s87
	global_load_lds_dwordx4 v[148:149], off
	v_lshl_add_u64 v[148:149], s[60:61], 0, v[140:141]
	s_mov_b32 m0, s62
	s_nop 0
	global_load_lds_dwordx4 v[148:149], off
	v_lshl_add_u64 v[148:149], s[60:61], 0, v[0:1]
	s_add_i32 m0, s62, 0x2000
	s_nop 0
	global_load_lds_dwordx4 v[148:149], off
	v_lshl_add_u64 v[148:149], v[156:157], 0, s[92:93]
	s_mov_b32 m0, s11
	s_nop 0
	global_load_lds_dwordx4 v[148:149], off
	v_lshl_add_u64 v[148:149], v[168:169], 0, s[92:93]
	s_mov_b32 m0, s20
	s_nop 0
	global_load_lds_dwordx4 v[148:149], off
	s_waitcnt vmcnt(8)
	s_waitcnt lgkmcnt(0)
	s_barrier
	s_waitcnt lgkmcnt(0)
	v_mfma_f32_16x16x32_bf16 v[112:115], v[132:135], v[196:199], v[112:115]
	v_mfma_f32_16x16x32_bf16 v[80:83], v[160:163], v[196:199], v[80:83]
	v_mfma_f32_16x16x32_bf16 v[108:111], v[132:135], v[204:207], v[108:111]
	v_mfma_f32_16x16x32_bf16 v[76:79], v[160:163], v[204:207], v[76:79]
	v_mfma_f32_16x16x32_bf16 v[100:103], v[132:135], v[212:215], v[100:103]
	v_mfma_f32_16x16x32_bf16 v[72:75], v[160:163], v[212:215], v[72:75]
	v_mfma_f32_16x16x32_bf16 v[92:95], v[132:135], v[238:241], v[92:95]
	v_mfma_f32_16x16x32_bf16 v[64:67], v[160:163], v[238:241], v[64:67]
	v_mfma_f32_16x16x32_bf16 v[112:115], v[136:139], v[200:203], v[112:115]
	v_mfma_f32_16x16x32_bf16 v[80:83], v[164:167], v[200:203], v[80:83]
	v_mfma_f32_16x16x32_bf16 v[108:111], v[136:139], v[208:211], v[108:111]
	v_mfma_f32_16x16x32_bf16 v[76:79], v[164:167], v[208:211], v[76:79]
	v_mfma_f32_16x16x32_bf16 v[100:103], v[136:139], v[234:237], v[100:103]
	v_mfma_f32_16x16x32_bf16 v[72:75], v[164:167], v[234:237], v[72:75]
	v_mfma_f32_16x16x32_bf16 v[92:95], v[136:139], v[242:245], v[92:95]
	v_mfma_f32_16x16x32_bf16 v[64:67], v[164:167], v[242:245], v[64:67]
	v_mfma_f32_16x16x32_bf16 v[48:51], v[180:183], v[196:199], v[48:51]
	v_mfma_f32_16x16x32_bf16 v[16:19], v[188:191], v[196:199], v[16:19]
	v_mfma_f32_16x16x32_bf16 v[44:47], v[180:183], v[204:207], v[44:47]
	v_mfma_f32_16x16x32_bf16 v[12:15], v[188:191], v[204:207], v[12:15]
	v_mfma_f32_16x16x32_bf16 v[36:39], v[180:183], v[212:215], v[36:39]
	v_mfma_f32_16x16x32_bf16 v[8:11], v[188:191], v[212:215], v[8:11]
	v_mfma_f32_16x16x32_bf16 v[28:31], v[180:183], v[238:241], v[28:31]
	v_mfma_f32_16x16x32_bf16 v[4:7], v[188:191], v[238:241], v[4:7]
	v_mfma_f32_16x16x32_bf16 v[48:51], v[184:187], v[200:203], v[48:51]
	v_mfma_f32_16x16x32_bf16 v[16:19], v[192:195], v[200:203], v[16:19]
	v_mfma_f32_16x16x32_bf16 v[44:47], v[184:187], v[208:211], v[44:47]
	v_mfma_f32_16x16x32_bf16 v[12:15], v[192:195], v[208:211], v[12:15]
	v_mfma_f32_16x16x32_bf16 v[36:39], v[184:187], v[234:237], v[36:39]
	v_mfma_f32_16x16x32_bf16 v[8:11], v[192:195], v[234:237], v[8:11]
	v_mfma_f32_16x16x32_bf16 v[28:31], v[184:187], v[242:245], v[28:31]
	v_mfma_f32_16x16x32_bf16 v[4:7], v[192:195], v[242:245], v[4:7]
	s_barrier
	s_add_i32 s53, s53, 2
	s_add_u32 s58, s58, 0x100
	s_addc_u32 s59, s59, 0
	s_add_u32 s45, s45, 0x100
	s_addc_u32 s51, s51, 0
	s_cmp_gt_u32 s53, 13
	s_cbranch_scc0 .LBB0_2296
	s_setprio 0
	v_readlane_b32 s0, v252, 28
	v_readlane_b32 s1, v252, 29
	s_and_b64 vcc, exec, s[0:1]
	s_cbranch_vccz .LBB0_2299
	s_barrier

; #define PG8_STAGE(bufoff, gbase) do { _Pragma("unroll") for (int _i = 0; _i < 2; ++_i) \
;         __builtin_amdgcn_global_load_lds((const unsigned*)((const char*)(gbase) + voffA[_i]), (LAS unsigned*)(lds + (bufoff) + ldsw + _i * 8192), 16, 0, 0); } while (0)
; #define PG8_LDA(dst, b, h) do { _Pragma("unroll") for (int m = 0; m < 4; ++m) _Pragma("unroll") for (int k = 0; k < 2; ++k) dst[m][k] = *(const LAS bf16x8*)(lds + PG8_SA(b, h) + aoff + m * 2048 + k * 1024); } while (0)
; #define PG8_LDB(dst, b, h) do { _Pragma("unroll") for (int n = 0; n < 2; ++n) _Pragma("unroll") for (int k = 0; k < 2; ++k) dst[n][k] = *(const LAS bf16x8*)(lds + PG8_SB(b, h) + boff + n * 2048 + k * 1024); } while (0)
; #define PG8_SCHED __builtin_amdgcn_sched_barrier(0)
; template <class Epi, class Sched>
; __device__ __forceinline__ void gemm_phase(LAS unsigned char* lds, const Gemm g, const Sched& S, const Epi& E, int wid) {
;     ...
;         const bool has_next = S.next(ui + 1, nxt);
;         const char* nA = has_next ? (const char*)g.A + (size_t)nxt.pm * tstep : cA; const char* nB = has_next ? (const char*)g.Bt + (size_t)nxt.pn * tstep : cB;
;         for (int t = 0; t < nt; t += 2) {
;             const bool last = (t == nt - 2);
;             const char* a1 = cA + (size_t)(t + 1) * kstep;
;             const char* a2 = last ? nA : cA + (size_t)(t + 2) * kstep; const char* b2 = last ? nB : cB + (size_t)(t + 2) * kstep;
;             const char* a3 = a2 + kstep; const char* b3 = b2 + kstep;
;             PG8_LDB(B0, 0, 0); PG8_LDB(B1, 0, 1); PG8_SCHED; PG8_LDA(At, 0, 0); PG8_STAGE(PG8_SA(1, 1), a1 + hstep);
;     ...
; #pragma unroll
;         for (int a = 0; a < 2; ++a)
; #pragma unroll
;             for (int b = 0; b < 2; ++b)
; #pragma unroll
;                 for (int m = 0; m < 4; ++m)
; #pragma unroll
;                     for (int n = 0; n < 2; ++n) acc[a][b][m][n] = (f32x4){0.f, 0.f, 0.f, 0.f};
;         cur = nxt; cA = nA; cB = nB; ++ui;
.LBB0_2373:
	s_ashr_i32 s57, s56, 31
	s_lshl_b64 s[0:1], s[56:57], 21
	v_readlane_b32 s24, v254, 42
	v_readlane_b32 s25, v254, 43
	s_add_u32 s58, s24, s0
	s_addc_u32 s59, s25, s1
	s_and_b64 s[0:1], s[42:43], exec
	s_cselect_b32 s0, s59, s69
	s_cselect_b32 s1, s58, s68
	s_ashr_i32 s55, s54, 31
	s_lshl_b64 s[60:61], s[54:55], 21
	s_add_u32 s60, s2, s60
	s_addc_u32 s61, s4, s61
	s_and_b64 s[66:67], s[42:43], exec
	s_cselect_b32 s29, s61, s63
	s_cselect_b32 s30, s60, s62
	s_add_u32 s55, s62, 0x100
	v_mov_b32_e32 v4, 0
	s_addc_u32 s57, s63, 0
	s_mov_b32 s66, -2
	v_mov_b32_e32 v5, v4
	s_waitcnt lgkmcnt(0)
	v_mov_b32_e32 v6, v4
	v_mov_b32_e32 v7, v4
	v_mov_b32_e32 v8, v4
	v_mov_b32_e32 v9, v4
	v_mov_b32_e32 v10, v4
	v_mov_b32_e32 v11, v4
	v_mov_b32_e32 v20, v4
	v_mov_b32_e32 v21, v4
	v_mov_b32_e32 v22, v4
	v_mov_b32_e32 v23, v4
	v_mov_b32_e32 v24, v4
	v_mov_b32_e32 v25, v4
	v_mov_b32_e32 v26, v4
	v_mov_b32_e32 v27, v4
	v_mov_b32_e32 v36, v4
	v_mov_b32_e32 v37, v4
	v_mov_b32_e32 v38, v4
	v_mov_b32_e32 v39, v4
	v_mov_b32_e32 v40, v4
	v_mov_b32_e32 v41, v4
	v_mov_b32_e32 v42, v4
	v_mov_b32_e32 v43, v4
	v_mov_b32_e32 v52, v4
	v_mov_b32_e32 v53, v4
	v_mov_b32_e32 v54, v4
	v_mov_b32_e32 v55, v4
	v_mov_b32_e32 v56, v4
	v_mov_b32_e32 v57, v4
	v_mov_b32_e32 v58, v4
	v_mov_b32_e32 v59, v4
	v_mov_b32_e32 v12, v4
	v_mov_b32_e32 v13, v4
	v_mov_b32_e32 v14, v4
	v_mov_b32_e32 v15, v4
	v_mov_b32_e32 v16, v4
	v_mov_b32_e32 v17, v4
	v_mov_b32_e32 v18, v4
	v_mov_b32_e32 v19, v4
	v_mov_b32_e32 v28, v4
	v_mov_b32_e32 v29, v4
	v_mov_b32_e32 v30, v4
	v_mov_b32_e32 v31, v4
	v_mov_b32_e32 v32, v4
	v_mov_b32_e32 v33, v4
	v_mov_b32_e32 v34, v4
	v_mov_b32_e32 v35, v4
	v_mov_b32_e32 v44, v4
	v_mov_b32_e32 v45, v4
	v_mov_b32_e32 v46, v4
	v_mov_b32_e32 v47, v4
	v_mov_b32_e32 v48, v4
	v_mov_b32_e32 v49, v4
	v_mov_b32_e32 v50, v4
	v_mov_b32_e32 v51, v4
	v_mov_b32_e32 v60, v4
	v_mov_b32_e32 v61, v4
	v_mov_b32_e32 v62, v4
	v_mov_b32_e32 v63, v4
	v_mov_b32_e32 v64, v4
	v_mov_b32_e32 v65, v4
	v_mov_b32_e32 v66, v4
	v_mov_b32_e32 v67, v4
	v_mov_b32_e32 v68, v4
	v_mov_b32_e32 v69, v4
	v_mov_b32_e32 v70, v4
	v_mov_b32_e32 v71, v4
	v_mov_b32_e32 v72, v4
	v_mov_b32_e32 v73, v4
	v_mov_b32_e32 v74, v4
	v_mov_b32_e32 v75, v4
	v_mov_b32_e32 v84, v4
	v_mov_b32_e32 v85, v4
	v_mov_b32_e32 v86, v4
	v_mov_b32_e32 v87, v4
	v_mov_b32_e32 v88, v4
	v_mov_b32_e32 v89, v4
	v_mov_b32_e32 v90, v4
	v_mov_b32_e32 v91, v4
	v_mov_b32_e32 v100, v4
	v_mov_b32_e32 v101, v4
	v_mov_b32_e32 v102, v4
	v_mov_b32_e32 v103, v4
	v_mov_b32_e32 v104, v4
	v_mov_b32_e32 v105, v4
	v_mov_b32_e32 v106, v4
	v_mov_b32_e32 v107, v4
	v_mov_b32_e32 v116, v4
	v_mov_b32_e32 v117, v4
	v_mov_b32_e32 v118, v4
	v_mov_b32_e32 v119, v4
	v_mov_b32_e32 v120, v4
	v_mov_b32_e32 v121, v4
	v_mov_b32_e32 v122, v4
	v_mov_b32_e32 v123, v4
	v_mov_b32_e32 v76, v4
	v_mov_b32_e32 v77, v4
	v_mov_b32_e32 v78, v4
	v_mov_b32_e32 v79, v4
	v_mov_b32_e32 v80, v4
	v_mov_b32_e32 v81, v4
	v_mov_b32_e32 v82, v4
	v_mov_b32_e32 v83, v4
	v_mov_b32_e32 v92, v4
	v_mov_b32_e32 v93, v4
	v_mov_b32_e32 v94, v4
	v_mov_b32_e32 v95, v4
	v_mov_b32_e32 v96, v4
	v_mov_b32_e32 v97, v4
	v_mov_b32_e32 v98, v4
	v_mov_b32_e32 v99, v4
	v_mov_b32_e32 v108, v4
	v_mov_b32_e32 v109, v4
	v_mov_b32_e32 v110, v4
	v_mov_b32_e32 v111, v4
	v_mov_b32_e32 v112, v4
	v_mov_b32_e32 v113, v4
	v_mov_b32_e32 v114, v4
	v_mov_b32_e32 v115, v4
	v_mov_b32_e32 v124, v4
	v_mov_b32_e32 v125, v4
	v_mov_b32_e32 v126, v4
	v_mov_b32_e32 v127, v4
	v_mov_b32_e32 v128, v4
	v_mov_b32_e32 v129, v4
	v_mov_b32_e32 v130, v4
	v_mov_b32_e32 v131, v4
	v_readlane_b32 s100, v251, 60
	s_cmp_lt_u32 s100, 4
	s_cbranch_scc1 .Lmy_prio_6
	s_setprio 1
.Lmy_prio_6:
.LBB0_2374:
	s_add_u32 s70, s68, 0x100
	s_addc_u32 s71, s69, 0
	s_add_i32 s67, 0, 0x10000
	s_cmp_eq_u32 s66, 60
	s_cselect_b32 s77, s0, s71
	s_cselect_b32 s76, s1, s70
	v_add_u32_e32 v3, s67, v165
	s_cselect_b32 s63, s29, s57
	s_cselect_b32 s62, s30, s55
	s_add_i32 s78, 0, 0x14000
	ds_read_b128 v[140:143], v3
	ds_read_b128 v[144:147], v3 offset:1024
	ds_read_b128 v[148:151], v3 offset:2048
	ds_read_b128 v[152:155], v3 offset:3072
	v_add_u32_e32 v3, s78, v165
	ds_read_b128 v[156:159], v3
	ds_read_b128 v[160:163], v3 offset:1024
	ds_read_b128 v[180:183], v3 offset:2048
	ds_read_b128 v[184:187], v3 offset:3072
	v_lshl_add_u64 v[168:169], s[68:69], 0, v[136:137]
	s_add_i32 m0, s85, 0xc000
	ds_read_b128 v[188:191], v167
	ds_read_b128 v[192:195], v167 offset:1024
	ds_read_b128 v[196:199], v167 offset:2048
	ds_read_b128 v[200:203], v167 offset:3072
	ds_read_b128 v[204:207], v167 offset:4096
	ds_read_b128 v[208:211], v167 offset:5120
	ds_read_b128 v[212:215], v167 offset:6144
	ds_read_b128 v[234:237], v167 offset:7168
	global_load_lds_dwordx4 v[168:169], off
	v_lshl_add_u64 v[168:169], s[68:69], 0, v[138:139]
	s_add_i32 m0, s85, 0xe000
	s_nop 0
	global_load_lds_dwordx4 v[168:169], off
	s_waitcnt vmcnt(8)
	s_waitcnt lgkmcnt(0)
	s_barrier
; #define PG8_STAGE(bufoff, gbase) do { _Pragma("unroll") for (int _i = 0; _i < 2; ++_i) \
;         __builtin_amdgcn_global_load_lds((const unsigned*)((const char*)(gbase) + voffA[_i]), (LAS unsigned*)(lds + (bufoff) + ldsw + _i * 8192), 16, 0, 0); } while (0)
; #define PG8_LDA(dst, b, h) do { _Pragma("unroll") for (int m = 0; m < 4; ++m) _Pragma("unroll") for (int k = 0; k < 2; ++k) dst[m][k] = *(const LAS bf16x8*)(lds + PG8_SA(b, h) + aoff + m * 2048 + k * 1024); } while (0)
; #define PG8_MMA(ai, bj, At, Bt) do { __builtin_amdgcn_s_setprio(1); _Pragma("unroll") for (int m = 0; m < 4; ++m) _Pragma("unroll") for (int n = 0; n < 2; ++n) _Pragma("unroll") for (int k = 0; k < 2; ++k) \
;         acc[ai][bj][m][n] = __builtin_amdgcn_mfma_f32_16x16x32_bf16(Bt[n][k], At[m][k], acc[ai][bj][m][n], 0, 0, 0); __builtin_amdgcn_s_setprio(0); } while (0)
; #define PG8_WAIT_V(n) asm volatile("s_waitcnt vmcnt(" #n ")" ::: "memory")
; #define PG8_WAIT_L(n) asm volatile("s_waitcnt lgkmcnt(" #n ")" ::: "memory")
; #define PG8_BAR __builtin_amdgcn_s_barrier()
; #define PG8_SCHED __builtin_amdgcn_sched_barrier(0)
; template <class Epi, class Sched>
; __device__ __forceinline__ void gemm_phase(LAS unsigned char* lds, const Gemm g, const Sched& S, const Epi& E, int wid) {
;     ...
;             PG8_WAIT_V(8); PG8_WAIT_L(0); PG8_BAR; PG8_MMA(0, 0, At, B0); PG8_MMA(0, 1, At, B1); PG8_BAR; PG8_SCHED;
;             PG8_LDA(At, 0, 1); PG8_STAGE(PG8_SB(0, 0), b2); PG8_STAGE(PG8_SB(0, 1), b2 + hstep); PG8_STAGE(PG8_SA(0, 0), a2);
;             PG8_WAIT_V(8); PG8_WAIT_L(0); PG8_BAR; PG8_MMA(1, 0, At, B0); PG8_MMA(1, 1, At, B1); PG8_BAR; PG8_SCHED;
	s_waitcnt lgkmcnt(0)
	v_mfma_f32_16x16x32_bf16 v[128:131], v[140:143], v[188:191], v[128:131]
	v_mfma_f32_16x16x32_bf16 v[124:127], v[148:151], v[188:191], v[124:127]
	v_mfma_f32_16x16x32_bf16 v[112:115], v[140:143], v[196:199], v[112:115]
	v_mfma_f32_16x16x32_bf16 v[108:111], v[148:151], v[196:199], v[108:111]
	v_mfma_f32_16x16x32_bf16 v[96:99], v[140:143], v[204:207], v[96:99]
	v_mfma_f32_16x16x32_bf16 v[92:95], v[148:151], v[204:207], v[92:95]
	v_mfma_f32_16x16x32_bf16 v[80:83], v[140:143], v[212:215], v[80:83]
	v_mfma_f32_16x16x32_bf16 v[76:79], v[148:151], v[212:215], v[76:79]
	v_mfma_f32_16x16x32_bf16 v[128:131], v[144:147], v[192:195], v[128:131]
	v_mfma_f32_16x16x32_bf16 v[124:127], v[152:155], v[192:195], v[124:127]
	v_mfma_f32_16x16x32_bf16 v[112:115], v[144:147], v[200:203], v[112:115]
	v_mfma_f32_16x16x32_bf16 v[108:111], v[152:155], v[200:203], v[108:111]
	v_mfma_f32_16x16x32_bf16 v[96:99], v[144:147], v[208:211], v[96:99]
	v_mfma_f32_16x16x32_bf16 v[92:95], v[152:155], v[208:211], v[92:95]
	v_mfma_f32_16x16x32_bf16 v[80:83], v[144:147], v[234:237], v[80:83]
	v_mfma_f32_16x16x32_bf16 v[76:79], v[152:155], v[234:237], v[76:79]
	v_mfma_f32_16x16x32_bf16 v[120:123], v[156:159], v[188:191], v[120:123]
	v_mfma_f32_16x16x32_bf16 v[116:119], v[180:183], v[188:191], v[116:119]
	v_mfma_f32_16x16x32_bf16 v[104:107], v[156:159], v[196:199], v[104:107]
	v_mfma_f32_16x16x32_bf16 v[100:103], v[180:183], v[196:199], v[100:103]
	v_mfma_f32_16x16x32_bf16 v[88:91], v[156:159], v[204:207], v[88:91]
	v_mfma_f32_16x16x32_bf16 v[84:87], v[180:183], v[204:207], v[84:87]
	v_mfma_f32_16x16x32_bf16 v[72:75], v[156:159], v[212:215], v[72:75]
	v_mfma_f32_16x16x32_bf16 v[68:71], v[180:183], v[212:215], v[68:71]
	v_mfma_f32_16x16x32_bf16 v[120:123], v[160:163], v[192:195], v[120:123]
	v_mfma_f32_16x16x32_bf16 v[116:119], v[184:187], v[192:195], v[116:119]
	v_mfma_f32_16x16x32_bf16 v[104:107], v[160:163], v[200:203], v[104:107]
	v_mfma_f32_16x16x32_bf16 v[100:103], v[184:187], v[200:203], v[100:103]
	v_mfma_f32_16x16x32_bf16 v[88:91], v[160:163], v[208:211], v[88:91]
	v_mfma_f32_16x16x32_bf16 v[84:87], v[184:187], v[208:211], v[84:87]
	v_mfma_f32_16x16x32_bf16 v[72:75], v[160:163], v[234:237], v[72:75]
	v_mfma_f32_16x16x32_bf16 v[68:71], v[184:187], v[234:237], v[68:71]
	s_barrier
	s_add_i32 s67, s67, s87
	v_lshl_add_u64 v[168:169], s[62:63], 0, v[132:133]
	s_mov_b32 m0, s67
	ds_read_b128 v[188:191], v167 offset:16384
	ds_read_b128 v[192:195], v167 offset:17408
	ds_read_b128 v[196:199], v167 offset:18432
	ds_read_b128 v[200:203], v167 offset:19456
	ds_read_b128 v[204:207], v167 offset:20480
	ds_read_b128 v[208:211], v167 offset:21504
	ds_read_b128 v[212:215], v167 offset:22528
	ds_read_b128 v[234:237], v167 offset:23552
	global_load_lds_dwordx4 v[168:169], off
	s_add_i32 m0, s67, 0x2000
	s_add_u32 s68, s62, 0x100000
	v_lshl_add_u64 v[216:217], s[62:63], 0, v[0:1]
	s_addc_u32 s69, s63, 0
	s_add_i32 s67, s78, s87
	global_load_lds_dwordx4 v[216:217], off
	v_lshl_add_u64 v[238:239], s[68:69], 0, v[132:133]
	s_mov_b32 m0, s67
	v_lshl_add_u64 v[240:241], s[76:77], 0, v[0:1]
	global_load_lds_dwordx4 v[238:239], off
	v_lshl_add_u64 v[238:239], s[68:69], 0, v[0:1]
	s_add_i32 m0, s67, 0x2000
	s_nop 0
	global_load_lds_dwordx4 v[238:239], off
	v_lshl_add_u64 v[238:239], s[76:77], 0, v[132:133]
	s_mov_b32 m0, s85
	s_nop 0
	global_load_lds_dwordx4 v[238:239], off
	s_mov_b32 m0, s8
	s_nop 0
	global_load_lds_dwordx4 v[240:241], off
	s_waitcnt vmcnt(8)
	s_waitcnt lgkmcnt(0)
	s_barrier
	s_waitcnt lgkmcnt(0)
	v_mfma_f32_16x16x32_bf16 v[64:67], v[140:143], v[188:191], v[64:67]
	v_mfma_f32_16x16x32_bf16 v[60:63], v[148:151], v[188:191], v[60:63]
	v_mfma_f32_16x16x32_bf16 v[48:51], v[140:143], v[196:199], v[48:51]
	v_mfma_f32_16x16x32_bf16 v[44:47], v[148:151], v[196:199], v[44:47]
	v_mfma_f32_16x16x32_bf16 v[32:35], v[140:143], v[204:207], v[32:35]
	v_mfma_f32_16x16x32_bf16 v[28:31], v[148:151], v[204:207], v[28:31]
	v_mfma_f32_16x16x32_bf16 v[16:19], v[140:143], v[212:215], v[16:19]
	v_mfma_f32_16x16x32_bf16 v[12:15], v[148:151], v[212:215], v[12:15]
	v_mfma_f32_16x16x32_bf16 v[64:67], v[144:147], v[192:195], v[64:67]
	v_mfma_f32_16x16x32_bf16 v[60:63], v[152:155], v[192:195], v[60:63]
	v_mfma_f32_16x16x32_bf16 v[48:51], v[144:147], v[200:203], v[48:51]
	v_mfma_f32_16x16x32_bf16 v[44:47], v[152:155], v[200:203], v[44:47]
	v_mfma_f32_16x16x32_bf16 v[32:35], v[144:147], v[208:211], v[32:35]
	v_mfma_f32_16x16x32_bf16 v[28:31], v[152:155], v[208:211], v[28:31]
	v_mfma_f32_16x16x32_bf16 v[16:19], v[144:147], v[234:237], v[16:19]
	v_mfma_f32_16x16x32_bf16 v[12:15], v[152:155], v[234:237], v[12:15]
	v_mfma_f32_16x16x32_bf16 v[56:59], v[156:159], v[188:191], v[56:59]
	v_mfma_f32_16x16x32_bf16 v[52:55], v[180:183], v[188:191], v[52:55]
	v_mfma_f32_16x16x32_bf16 v[40:43], v[156:159], v[196:199], v[40:43]
	v_mfma_f32_16x16x32_bf16 v[36:39], v[180:183], v[196:199], v[36:39]
	v_mfma_f32_16x16x32_bf16 v[24:27], v[156:159], v[204:207], v[24:27]
	v_mfma_f32_16x16x32_bf16 v[20:23], v[180:183], v[204:207], v[20:23]
	v_mfma_f32_16x16x32_bf16 v[8:11], v[156:159], v[212:215], v[8:11]
	v_mfma_f32_16x16x32_bf16 v[4:7], v[180:183], v[212:215], v[4:7]
	v_mfma_f32_16x16x32_bf16 v[56:59], v[160:163], v[192:195], v[56:59]
	v_mfma_f32_16x16x32_bf16 v[52:55], v[184:187], v[192:195], v[52:55]
	v_mfma_f32_16x16x32_bf16 v[40:43], v[160:163], v[200:203], v[40:43]
	v_mfma_f32_16x16x32_bf16 v[36:39], v[184:187], v[200:203], v[36:39]
	v_mfma_f32_16x16x32_bf16 v[24:27], v[160:163], v[208:211], v[24:27]
	v_mfma_f32_16x16x32_bf16 v[20:23], v[184:187], v[208:211], v[20:23]
	v_mfma_f32_16x16x32_bf16 v[8:11], v[160:163], v[234:237], v[8:11]
	v_mfma_f32_16x16x32_bf16 v[4:7], v[184:187], v[234:237], v[4:7]
	s_barrier
; #define PG8_STAGE(bufoff, gbase) do { _Pragma("unroll") for (int _i = 0; _i < 2; ++_i) \
;         __builtin_amdgcn_global_load_lds((const unsigned*)((const char*)(gbase) + voffA[_i]), (LAS unsigned*)(lds + (bufoff) + ldsw + _i * 8192), 16, 0, 0); } while (0)
; #define PG8_LDA(dst, b, h) do { _Pragma("unroll") for (int m = 0; m < 4; ++m) _Pragma("unroll") for (int k = 0; k < 2; ++k) dst[m][k] = *(const LAS bf16x8*)(lds + PG8_SA(b, h) + aoff + m * 2048 + k * 1024); } while (0)
; #define PG8_LDB(dst, b, h) do { _Pragma("unroll") for (int n = 0; n < 2; ++n) _Pragma("unroll") for (int k = 0; k < 2; ++k) dst[n][k] = *(const LAS bf16x8*)(lds + PG8_SB(b, h) + boff + n * 2048 + k * 1024); } while (0)
; #define PG8_MMA(ai, bj, At, Bt) do { __builtin_amdgcn_s_setprio(1); _Pragma("unroll") for (int m = 0; m < 4; ++m) _Pragma("unroll") for (int n = 0; n < 2; ++n) _Pragma("unroll") for (int k = 0; k < 2; ++k) \
;         acc[ai][bj][m][n] = __builtin_amdgcn_mfma_f32_16x16x32_bf16(Bt[n][k], At[m][k], acc[ai][bj][m][n], 0, 0, 0); __builtin_amdgcn_s_setprio(0); } while (0)
; #define PG8_WAIT_V(n) asm volatile("s_waitcnt vmcnt(" #n ")" ::: "memory")
; #define PG8_WAIT_L(n) asm volatile("s_waitcnt lgkmcnt(" #n ")" ::: "memory")
; #define PG8_BAR __builtin_amdgcn_s_barrier()
; #define PG8_SCHED __builtin_amdgcn_sched_barrier(0)
; template <class Epi, class Sched>
; __device__ __forceinline__ void gemm_phase(LAS unsigned char* lds, const Gemm g, const Sched& S, const Epi& E, int wid) {
;     ...
;             PG8_LDB(B0, 1, 0); PG8_LDB(B1, 1, 1); PG8_SCHED; PG8_LDA(At, 1, 0); PG8_STAGE(PG8_SA(0, 1), a2 + hstep);
;             PG8_WAIT_V(8); PG8_WAIT_L(0); PG8_BAR; PG8_MMA(0, 0, At, B0); PG8_MMA(0, 1, At, B1); PG8_BAR; PG8_SCHED;
	s_add_i32 s67, 0, 0x18000
	v_add_u32_e32 v3, s67, v165
	s_add_i32 s78, 0, 0x1c000
	ds_read_b128 v[140:143], v3
	ds_read_b128 v[144:147], v3 offset:1024
	ds_read_b128 v[148:151], v3 offset:2048
	ds_read_b128 v[152:155], v3 offset:3072
	v_add_u32_e32 v3, s78, v165
	ds_read_b128 v[156:159], v3
	ds_read_b128 v[160:163], v3 offset:1024
	ds_read_b128 v[180:183], v3 offset:2048
	ds_read_b128 v[184:187], v3 offset:3072
	s_add_u32 s68, s76, 0x100000
	s_addc_u32 s69, s77, 0
	s_mov_b32 m0, s9
	v_lshl_add_u64 v[242:243], s[68:69], 0, v[132:133]
	ds_read_b128 v[188:191], v167 offset:32768
	ds_read_b128 v[192:195], v167 offset:33792
	ds_read_b128 v[196:199], v167 offset:34816
	ds_read_b128 v[200:203], v167 offset:35840
	ds_read_b128 v[204:207], v167 offset:36864
	ds_read_b128 v[208:211], v167 offset:37888
	ds_read_b128 v[212:215], v167 offset:38912
	ds_read_b128 v[234:237], v167 offset:39936
	global_load_lds_dwordx4 v[242:243], off
	v_lshl_add_u64 v[242:243], s[68:69], 0, v[0:1]
	s_mov_b32 m0, s10
	s_nop 0
	global_load_lds_dwordx4 v[242:243], off
	s_waitcnt vmcnt(8)
	s_waitcnt lgkmcnt(0)
	s_barrier
	s_waitcnt lgkmcnt(0)
	v_mfma_f32_16x16x32_bf16 v[128:131], v[140:143], v[188:191], v[128:131]
	v_mfma_f32_16x16x32_bf16 v[124:127], v[148:151], v[188:191], v[124:127]
	v_mfma_f32_16x16x32_bf16 v[112:115], v[140:143], v[196:199], v[112:115]
	v_mfma_f32_16x16x32_bf16 v[108:111], v[148:151], v[196:199], v[108:111]
	v_mfma_f32_16x16x32_bf16 v[96:99], v[140:143], v[204:207], v[96:99]
	v_mfma_f32_16x16x32_bf16 v[92:95], v[148:151], v[204:207], v[92:95]
	v_mfma_f32_16x16x32_bf16 v[80:83], v[140:143], v[212:215], v[80:83]
	v_mfma_f32_16x16x32_bf16 v[76:79], v[148:151], v[212:215], v[76:79]
	v_mfma_f32_16x16x32_bf16 v[128:131], v[144:147], v[192:195], v[128:131]
	v_mfma_f32_16x16x32_bf16 v[124:127], v[152:155], v[192:195], v[124:127]
	v_mfma_f32_16x16x32_bf16 v[112:115], v[144:147], v[200:203], v[112:115]
	v_mfma_f32_16x16x32_bf16 v[108:111], v[152:155], v[200:203], v[108:111]
	v_mfma_f32_16x16x32_bf16 v[96:99], v[144:147], v[208:211], v[96:99]
	v_mfma_f32_16x16x32_bf16 v[92:95], v[152:155], v[208:211], v[92:95]
	v_mfma_f32_16x16x32_bf16 v[80:83], v[144:147], v[234:237], v[80:83]
	v_mfma_f32_16x16x32_bf16 v[76:79], v[152:155], v[234:237], v[76:79]
	v_mfma_f32_16x16x32_bf16 v[120:123], v[156:159], v[188:191], v[120:123]
	v_mfma_f32_16x16x32_bf16 v[116:119], v[180:183], v[188:191], v[116:119]
	v_mfma_f32_16x16x32_bf16 v[104:107], v[156:159], v[196:199], v[104:107]
	v_mfma_f32_16x16x32_bf16 v[100:103], v[180:183], v[196:199], v[100:103]
	v_mfma_f32_16x16x32_bf16 v[88:91], v[156:159], v[204:207], v[88:91]
	v_mfma_f32_16x16x32_bf16 v[84:87], v[180:183], v[204:207], v[84:87]
	v_mfma_f32_16x16x32_bf16 v[72:75], v[156:159], v[212:215], v[72:75]
	v_mfma_f32_16x16x32_bf16 v[68:71], v[180:183], v[212:215], v[68:71]
	v_mfma_f32_16x16x32_bf16 v[120:123], v[160:163], v[192:195], v[120:123]
	v_mfma_f32_16x16x32_bf16 v[116:119], v[184:187], v[192:195], v[116:119]
	v_mfma_f32_16x16x32_bf16 v[104:107], v[160:163], v[200:203], v[104:107]
	v_mfma_f32_16x16x32_bf16 v[100:103], v[184:187], v[200:203], v[100:103]
	v_mfma_f32_16x16x32_bf16 v[88:91], v[160:163], v[208:211], v[88:91]
	v_mfma_f32_16x16x32_bf16 v[84:87], v[184:187], v[208:211], v[84:87]
	v_mfma_f32_16x16x32_bf16 v[72:75], v[160:163], v[234:237], v[72:75]
	v_mfma_f32_16x16x32_bf16 v[68:71], v[184:187], v[234:237], v[68:71]
	s_barrier
; #define PG8_STAGE(bufoff, gbase) do { _Pragma("unroll") for (int _i = 0; _i < 2; ++_i) \
;         __builtin_amdgcn_global_load_lds((const unsigned*)((const char*)(gbase) + voffA[_i]), (LAS unsigned*)(lds + (bufoff) + ldsw + _i * 8192), 16, 0, 0); } while (0)
; #define PG8_LDA(dst, b, h) do { _Pragma("unroll") for (int m = 0; m < 4; ++m) _Pragma("unroll") for (int k = 0; k < 2; ++k) dst[m][k] = *(const LAS bf16x8*)(lds + PG8_SA(b, h) + aoff + m * 2048 + k * 1024); } while (0)
; #define PG8_MMA(ai, bj, At, Bt) do { __builtin_amdgcn_s_setprio(1); _Pragma("unroll") for (int m = 0; m < 4; ++m) _Pragma("unroll") for (int n = 0; n < 2; ++n) _Pragma("unroll") for (int k = 0; k < 2; ++k) \
;         acc[ai][bj][m][n] = __builtin_amdgcn_mfma_f32_16x16x32_bf16(Bt[n][k], At[m][k], acc[ai][bj][m][n], 0, 0, 0); __builtin_amdgcn_s_setprio(0); } while (0)
; #define PG8_WAIT_V(n) asm volatile("s_waitcnt vmcnt(" #n ")" ::: "memory")
; #define PG8_WAIT_L(n) asm volatile("s_waitcnt lgkmcnt(" #n ")" ::: "memory")
; #define PG8_BAR __builtin_amdgcn_s_barrier()
; #define PG8_SCHED __builtin_amdgcn_sched_barrier(0)
; template <class Epi, class Sched>
; __device__ __forceinline__ void gemm_phase(LAS unsigned char* lds, const Gemm g, const Sched& S, const Epi& E, int wid) {
;     ...
;             PG8_LDA(At, 1, 1); PG8_STAGE(PG8_SB(1, 0), b3); PG8_STAGE(PG8_SB(1, 1), b3 + hstep); PG8_STAGE(PG8_SA(1, 0), a3);
;             PG8_WAIT_V(8); PG8_WAIT_L(0); PG8_BAR; PG8_MMA(1, 0, At, B0); PG8_MMA(1, 1, At, B1); PG8_BAR; PG8_SCHED;
;         }
;         if (wr == 0) PG8_BAR;
	s_add_i32 s67, s67, s87
	v_lshl_add_u64 v[168:169], v[168:169], 0, s[92:93]
	s_mov_b32 m0, s67
	ds_read_b128 v[188:191], v167 offset:49152
	ds_read_b128 v[192:195], v167 offset:50176
	ds_read_b128 v[196:199], v167 offset:51200
	ds_read_b128 v[200:203], v167 offset:52224
	ds_read_b128 v[204:207], v167 offset:53248
	ds_read_b128 v[208:211], v167 offset:54272
	ds_read_b128 v[212:215], v167 offset:55296
	ds_read_b128 v[234:237], v167 offset:56320
	global_load_lds_dwordx4 v[168:169], off
	s_add_i32 m0, s67, 0x2000
	s_add_u32 s62, s62, 0x100080
	v_lshl_add_u64 v[168:169], v[216:217], 0, s[92:93]
	s_addc_u32 s63, s63, 0
	s_add_i32 s67, s78, s87
	global_load_lds_dwordx4 v[168:169], off
	v_lshl_add_u64 v[168:169], s[62:63], 0, v[132:133]
	s_mov_b32 m0, s67
	s_nop 0
	global_load_lds_dwordx4 v[168:169], off
	v_lshl_add_u64 v[168:169], s[62:63], 0, v[0:1]
	s_add_i32 m0, s67, 0x2000
	s_nop 0
	global_load_lds_dwordx4 v[168:169], off
	v_lshl_add_u64 v[168:169], v[238:239], 0, s[92:93]
	s_mov_b32 m0, s11
	s_nop 0
	global_load_lds_dwordx4 v[168:169], off
	v_lshl_add_u64 v[168:169], v[240:241], 0, s[92:93]
	s_mov_b32 m0, s20
	s_nop 0
	global_load_lds_dwordx4 v[168:169], off
	s_waitcnt vmcnt(8)
	s_waitcnt lgkmcnt(0)
	s_barrier
	s_waitcnt lgkmcnt(0)
	v_mfma_f32_16x16x32_bf16 v[64:67], v[140:143], v[188:191], v[64:67]
	v_mfma_f32_16x16x32_bf16 v[60:63], v[148:151], v[188:191], v[60:63]
	v_mfma_f32_16x16x32_bf16 v[48:51], v[140:143], v[196:199], v[48:51]
	v_mfma_f32_16x16x32_bf16 v[44:47], v[148:151], v[196:199], v[44:47]
	v_mfma_f32_16x16x32_bf16 v[32:35], v[140:143], v[204:207], v[32:35]
	v_mfma_f32_16x16x32_bf16 v[28:31], v[148:151], v[204:207], v[28:31]
	v_mfma_f32_16x16x32_bf16 v[16:19], v[140:143], v[212:215], v[16:19]
	v_mfma_f32_16x16x32_bf16 v[12:15], v[148:151], v[212:215], v[12:15]
	v_mfma_f32_16x16x32_bf16 v[64:67], v[144:147], v[192:195], v[64:67]
	v_mfma_f32_16x16x32_bf16 v[60:63], v[152:155], v[192:195], v[60:63]
	v_mfma_f32_16x16x32_bf16 v[48:51], v[144:147], v[200:203], v[48:51]
	v_mfma_f32_16x16x32_bf16 v[44:47], v[152:155], v[200:203], v[44:47]
	v_mfma_f32_16x16x32_bf16 v[32:35], v[144:147], v[208:211], v[32:35]
	v_mfma_f32_16x16x32_bf16 v[28:31], v[152:155], v[208:211], v[28:31]
	v_mfma_f32_16x16x32_bf16 v[16:19], v[144:147], v[234:237], v[16:19]
	v_mfma_f32_16x16x32_bf16 v[12:15], v[152:155], v[234:237], v[12:15]
	v_mfma_f32_16x16x32_bf16 v[56:59], v[156:159], v[188:191], v[56:59]
	v_mfma_f32_16x16x32_bf16 v[52:55], v[180:183], v[188:191], v[52:55]
	v_mfma_f32_16x16x32_bf16 v[40:43], v[156:159], v[196:199], v[40:43]
	v_mfma_f32_16x16x32_bf16 v[36:39], v[180:183], v[196:199], v[36:39]
	v_mfma_f32_16x16x32_bf16 v[24:27], v[156:159], v[204:207], v[24:27]
	v_mfma_f32_16x16x32_bf16 v[20:23], v[180:183], v[204:207], v[20:23]
	v_mfma_f32_16x16x32_bf16 v[8:11], v[156:159], v[212:215], v[8:11]
	v_mfma_f32_16x16x32_bf16 v[4:7], v[180:183], v[212:215], v[4:7]
	v_mfma_f32_16x16x32_bf16 v[56:59], v[160:163], v[192:195], v[56:59]
	v_mfma_f32_16x16x32_bf16 v[52:55], v[184:187], v[192:195], v[52:55]
	v_mfma_f32_16x16x32_bf16 v[40:43], v[160:163], v[200:203], v[40:43]
	v_mfma_f32_16x16x32_bf16 v[36:39], v[184:187], v[200:203], v[36:39]
	v_mfma_f32_16x16x32_bf16 v[24:27], v[160:163], v[208:211], v[24:27]
	v_mfma_f32_16x16x32_bf16 v[20:23], v[184:187], v[208:211], v[20:23]
	v_mfma_f32_16x16x32_bf16 v[8:11], v[160:163], v[234:237], v[8:11]
	v_mfma_f32_16x16x32_bf16 v[4:7], v[184:187], v[234:237], v[4:7]
	s_barrier
	s_add_i32 s66, s66, 2
	s_add_u32 s55, s55, 0x100
	s_addc_u32 s57, s57, 0
	s_cmp_gt_u32 s66, 61
	s_mov_b64 s[68:69], s[70:71]
	s_cbranch_scc0 .LBB0_2374
	s_setprio 0
	v_readlane_b32 s0, v252, 28
	v_readlane_b32 s1, v252, 29
	s_and_b64 vcc, exec, s[0:1]
	s_cbranch_vccz .LBB0_2377
	s_barrier
